# GEMM K-loop: block-closing barrier moved early by 6 MFMAs before SP2-type load segments and 2 before SP1-type
# speedup vs baseline: 1.0086x; 1.0086x over previous
; #define PG8_STAGE(bufoff, gbase, voff) do { if constexpr (!pg8_noload<Epi>::value) { _Pragma("unroll") for (int _i = 0; _i < 2; ++_i) \
;         __builtin_amdgcn_global_load_lds((const unsigned*)((const char*)(gbase) + (size_t)_i * pstep + (voff)[0]), (PG8_LAS unsigned*)(lds + (bufoff) + ldsw + _i * 8192), 16, 0, 0); } } while (0)
; #define PG8_LDA(dst, b, h) do { _Pragma("unroll") for (int m = 0; m < 4; ++m) _Pragma("unroll") for (int k = 0; k < 2; ++k) dst[m][k] = *(const PG8_LAS bf16x8*)(lds + PG8_SA(b, h) + aoff + m * 2048 + k * 1024); } while (0)
; #define PG8_LDB(dst, b, h) do { _Pragma("unroll") for (int n = 0; n < 2; ++n) _Pragma("unroll") for (int k = 0; k < 2; ++k) dst[n][k] = *(const PG8_LAS bf16x8*)(lds + PG8_SB(b, h) + boff + n * 2048 + k * 1024); } while (0)
; #define PG8_MMA(ai, bj, At, Bt) do { __builtin_amdgcn_s_setprio(1); _Pragma("unroll") for (int m = 0; m < 4; ++m) _Pragma("unroll") for (int n = 0; n < 2; ++n) _Pragma("unroll") for (int k = 0; k < 2; ++k) \
;         acc[ai][bj][m][n] = __builtin_amdgcn_mfma_f32_16x16x32_bf16(Bt[n][k], At[m][k], acc[ai][bj][m][n], 0, 0, 0); __builtin_amdgcn_s_setprio(0); } while (0)
; #define PG8_WAIT_V(n) asm volatile("s_waitcnt vmcnt(" #n ")" ::: "memory")
; #define PG8_WAIT_L(n) asm volatile("s_waitcnt lgkmcnt(" #n ")" ::: "memory")
; #define PG8_BAR __builtin_amdgcn_s_barrier()
; #define PG8_SCHED __builtin_amdgcn_sched_barrier(0)
; template <class Epi, class Sched, bool ALIGN_EPI = false, bool SP2 = false, bool ABLK = false>
; __device__ __forceinline__ void gemm_phase(PG8_LAS unsigned char* lds, const Gemm g, const Sched& S, const Epi& E) {
;     ...
;             PG8_LDB(B0, 0, 0); PG8_LDB(B1, 0, 1); PG8_SCHED; PG8_LDA(At, 0, 0); PG8_STAGE(PG8_SA(1, 1), a1 + hstep, voffA);
;             PG8_WAIT_V(8); PG8_WAIT_L(0); PG8_BAR; PG8_MMA(0, 0, At, B0); PG8_MMA(0, 1, At, B1); PG8_BAR; PG8_SCHED;
;             PG8_LDA(At, 0, 1); PG8_STAGE(PG8_SB(0, 0), b2, voffB); PG8_STAGE(PG8_SB(0, 1), b2 + hstep, voffB); PG8_STAGE(PG8_SA(0, 0), a2, voffA);
;             PG8_WAIT_V(8); PG8_WAIT_L(0); PG8_BAR; PG8_MMA(1, 0, At, B0); PG8_MMA(1, 1, At, B1); PG8_BAR; PG8_SCHED;
.LBB0_114:
	ds_read_b128 v[144:147], v168
	ds_read_b128 v[184:187], v168 offset:1024
	ds_read_b128 v[188:191], v168 offset:2048
	ds_read_b128 v[192:195], v168 offset:3072
	ds_read_b128 v[196:199], v169
	ds_read_b128 v[200:203], v169 offset:1024
	ds_read_b128 v[204:207], v169 offset:2048
	ds_read_b128 v[208:211], v169 offset:3072
	s_add_u32 s71, vcc_lo, 0xfff80800
	s_addc_u32 s73, vcc_hi, -1
	s_cmp_eq_u32 s70, 28
	s_cselect_b32 s75, s3, s73
	s_cselect_b32 s74, s7, s71
	s_cselect_b32 s77, s21, s17
	s_cselect_b32 s76, s72, s16
	v_lshl_add_u64 v[244:245], vcc, 0, v[136:137]
	s_add_i32 m0, s53, 0xc000
	ds_read_b128 v[212:215], v170
	ds_read_b128 v[216:219], v170 offset:1024
	ds_read_b128 v[220:223], v170 offset:2048
	ds_read_b128 v[224:227], v170 offset:3072
	ds_read_b128 v[228:231], v170 offset:4096
	ds_read_b128 v[232:235], v170 offset:5120
	ds_read_b128 v[236:239], v170 offset:6144
	ds_read_b128 v[240:243], v170 offset:7168
	global_load_lds_dwordx4 v[244:245], off
	v_lshl_add_u64 v[244:245], v[244:245], 0, s[0:1]
	s_add_i32 m0, s53, 0xe000
	s_nop 0
	global_load_lds_dwordx4 v[244:245], off
	s_waitcnt vmcnt(8)
	s_waitcnt lgkmcnt(0)
	s_barrier
	s_setprio 1
	s_waitcnt lgkmcnt(0)
	v_mfma_f32_16x16x32_bf16 v[126:129], v[144:147], v[212:215], v[126:129]
	v_mfma_f32_16x16x32_bf16 v[122:125], v[188:191], v[212:215], v[122:125]
	v_mfma_f32_16x16x32_bf16 v[110:113], v[144:147], v[220:223], v[110:113]
	v_mfma_f32_16x16x32_bf16 v[106:109], v[188:191], v[220:223], v[106:109]
	v_mfma_f32_16x16x32_bf16 v[94:97], v[144:147], v[228:231], v[94:97]
	v_mfma_f32_16x16x32_bf16 v[90:93], v[188:191], v[228:231], v[90:93]
	v_mfma_f32_16x16x32_bf16 v[78:81], v[144:147], v[236:239], v[78:81]
	v_mfma_f32_16x16x32_bf16 v[74:77], v[188:191], v[236:239], v[74:77]
	v_mfma_f32_16x16x32_bf16 v[126:129], v[184:187], v[216:219], v[126:129]
	v_mfma_f32_16x16x32_bf16 v[122:125], v[192:195], v[216:219], v[122:125]
	v_mfma_f32_16x16x32_bf16 v[110:113], v[184:187], v[224:227], v[110:113]
	v_mfma_f32_16x16x32_bf16 v[106:109], v[192:195], v[224:227], v[106:109]
	v_mfma_f32_16x16x32_bf16 v[94:97], v[184:187], v[232:235], v[94:97]
	v_mfma_f32_16x16x32_bf16 v[90:93], v[192:195], v[232:235], v[90:93]
	v_mfma_f32_16x16x32_bf16 v[78:81], v[184:187], v[240:243], v[78:81]
	v_mfma_f32_16x16x32_bf16 v[74:77], v[192:195], v[240:243], v[74:77]
	v_mfma_f32_16x16x32_bf16 v[118:121], v[196:199], v[212:215], v[118:121]
	v_mfma_f32_16x16x32_bf16 v[114:117], v[204:207], v[212:215], v[114:117]
	v_mfma_f32_16x16x32_bf16 v[102:105], v[196:199], v[220:223], v[102:105]
	v_mfma_f32_16x16x32_bf16 v[98:101], v[204:207], v[220:223], v[98:101]
	v_mfma_f32_16x16x32_bf16 v[86:89], v[196:199], v[228:231], v[86:89]
	v_mfma_f32_16x16x32_bf16 v[82:85], v[204:207], v[228:231], v[82:85]
	v_mfma_f32_16x16x32_bf16 v[70:73], v[196:199], v[236:239], v[70:73]
	v_mfma_f32_16x16x32_bf16 v[66:69], v[204:207], v[236:239], v[66:69]
	v_mfma_f32_16x16x32_bf16 v[118:121], v[200:203], v[216:219], v[118:121]
	v_mfma_f32_16x16x32_bf16 v[114:117], v[208:211], v[216:219], v[114:117]
	s_barrier
	s_setprio 2
	v_mfma_f32_16x16x32_bf16 v[102:105], v[200:203], v[224:227], v[102:105]
	v_mfma_f32_16x16x32_bf16 v[98:101], v[208:211], v[224:227], v[98:101]
	v_mfma_f32_16x16x32_bf16 v[86:89], v[200:203], v[232:235], v[86:89]
	v_mfma_f32_16x16x32_bf16 v[82:85], v[208:211], v[232:235], v[82:85]
	v_mfma_f32_16x16x32_bf16 v[70:73], v[200:203], v[240:243], v[70:73]
	v_mfma_f32_16x16x32_bf16 v[66:69], v[208:211], v[240:243], v[66:69]
	s_setprio 0
	s_add_i32 s71, s64, s52
	v_lshl_add_u64 v[244:245], s[76:77], 0, v[130:131]
	s_mov_b32 m0, s71
	ds_read_b128 v[212:215], v170 offset:16384
	ds_read_b128 v[216:219], v170 offset:17408
	ds_read_b128 v[220:223], v170 offset:18432
	ds_read_b128 v[224:227], v170 offset:19456
	ds_read_b128 v[228:231], v170 offset:20480
	ds_read_b128 v[232:235], v170 offset:21504
	ds_read_b128 v[236:239], v170 offset:22528
	ds_read_b128 v[240:243], v170 offset:23552
	global_load_lds_dwordx4 v[244:245], off
	v_lshl_add_u64 v[246:247], v[244:245], 0, s[0:1]
	s_add_i32 m0, s71, 0x2000
	s_add_i32 s71, s65, s52
	global_load_lds_dwordx4 v[246:247], off
	v_lshl_add_u64 v[246:247], v[244:245], 0, s[14:15]
	s_mov_b32 m0, s71
	s_nop 0
	global_load_lds_dwordx4 v[246:247], off
	v_lshl_add_u64 v[246:247], v[244:245], 0, s[18:19]
	s_add_i32 m0, s71, 0x2000
	s_nop 0
	global_load_lds_dwordx4 v[246:247], off
	v_lshl_add_u64 v[246:247], s[74:75], 0, v[130:131]
	s_mov_b32 m0, s53
	v_lshl_add_u64 v[248:249], v[246:247], 0, s[0:1]
	global_load_lds_dwordx4 v[246:247], off
	s_mov_b32 m0, s54
	s_nop 0
	global_load_lds_dwordx4 v[248:249], off
	s_waitcnt vmcnt(8)
	s_waitcnt lgkmcnt(0)
	s_barrier
; #define PG8_STAGE(bufoff, gbase, voff) do { if constexpr (!pg8_noload<Epi>::value) { _Pragma("unroll") for (int _i = 0; _i < 2; ++_i) \
;         __builtin_amdgcn_global_load_lds((const unsigned*)((const char*)(gbase) + (size_t)_i * pstep + (voff)[0]), (PG8_LAS unsigned*)(lds + (bufoff) + ldsw + _i * 8192), 16, 0, 0); } } while (0)
; #define PG8_LDA(dst, b, h) do { _Pragma("unroll") for (int m = 0; m < 4; ++m) _Pragma("unroll") for (int k = 0; k < 2; ++k) dst[m][k] = *(const PG8_LAS bf16x8*)(lds + PG8_SA(b, h) + aoff + m * 2048 + k * 1024); } while (0)
; #define PG8_LDB(dst, b, h) do { _Pragma("unroll") for (int n = 0; n < 2; ++n) _Pragma("unroll") for (int k = 0; k < 2; ++k) dst[n][k] = *(const PG8_LAS bf16x8*)(lds + PG8_SB(b, h) + boff + n * 2048 + k * 1024); } while (0)
; #define PG8_MMA(ai, bj, At, Bt) do { __builtin_amdgcn_s_setprio(1); _Pragma("unroll") for (int m = 0; m < 4; ++m) _Pragma("unroll") for (int n = 0; n < 2; ++n) _Pragma("unroll") for (int k = 0; k < 2; ++k) \
;         acc[ai][bj][m][n] = __builtin_amdgcn_mfma_f32_16x16x32_bf16(Bt[n][k], At[m][k], acc[ai][bj][m][n], 0, 0, 0); __builtin_amdgcn_s_setprio(0); } while (0)
; #define PG8_WAIT_V(n) asm volatile("s_waitcnt vmcnt(" #n ")" ::: "memory")
; #define PG8_WAIT_L(n) asm volatile("s_waitcnt lgkmcnt(" #n ")" ::: "memory")
; #define PG8_BAR __builtin_amdgcn_s_barrier()
; #define PG8_SCHED __builtin_amdgcn_sched_barrier(0)
; template <class Epi, class Sched, bool ALIGN_EPI = false, bool SP2 = false, bool ABLK = false>
; __device__ __forceinline__ void gemm_phase(PG8_LAS unsigned char* lds, const Gemm g, const Sched& S, const Epi& E) {
;     ...
;             PG8_WAIT_V(8); PG8_WAIT_L(0); PG8_BAR; PG8_MMA(1, 0, At, B0); PG8_MMA(1, 1, At, B1); PG8_BAR; PG8_SCHED;
;             PG8_LDB(B0, 1, 0); PG8_LDB(B1, 1, 1); PG8_SCHED; PG8_LDA(At, 1, 0); PG8_STAGE(PG8_SA(0, 1), a2 + hstep, voffA);
;             PG8_WAIT_V(8); PG8_WAIT_L(0); PG8_BAR; PG8_MMA(0, 0, At, B0); PG8_MMA(0, 1, At, B1); PG8_BAR; PG8_SCHED;
	s_setprio 1
	s_waitcnt lgkmcnt(0)
	v_mfma_f32_16x16x32_bf16 v[62:65], v[144:147], v[212:215], v[62:65]
	v_mfma_f32_16x16x32_bf16 v[58:61], v[188:191], v[212:215], v[58:61]
	v_mfma_f32_16x16x32_bf16 v[46:49], v[144:147], v[220:223], v[46:49]
	v_mfma_f32_16x16x32_bf16 v[42:45], v[188:191], v[220:223], v[42:45]
	v_mfma_f32_16x16x32_bf16 v[30:33], v[144:147], v[228:231], v[30:33]
	v_mfma_f32_16x16x32_bf16 v[26:29], v[188:191], v[228:231], v[26:29]
	v_mfma_f32_16x16x32_bf16 v[14:17], v[144:147], v[236:239], v[14:17]
	v_mfma_f32_16x16x32_bf16 v[10:13], v[188:191], v[236:239], v[10:13]
	v_mfma_f32_16x16x32_bf16 v[62:65], v[184:187], v[216:219], v[62:65]
	v_mfma_f32_16x16x32_bf16 v[58:61], v[192:195], v[216:219], v[58:61]
	v_mfma_f32_16x16x32_bf16 v[46:49], v[184:187], v[224:227], v[46:49]
	v_mfma_f32_16x16x32_bf16 v[42:45], v[192:195], v[224:227], v[42:45]
	v_mfma_f32_16x16x32_bf16 v[30:33], v[184:187], v[232:235], v[30:33]
	v_mfma_f32_16x16x32_bf16 v[26:29], v[192:195], v[232:235], v[26:29]
	v_mfma_f32_16x16x32_bf16 v[14:17], v[184:187], v[240:243], v[14:17]
	v_mfma_f32_16x16x32_bf16 v[10:13], v[192:195], v[240:243], v[10:13]
	v_mfma_f32_16x16x32_bf16 v[54:57], v[196:199], v[212:215], v[54:57]
	v_mfma_f32_16x16x32_bf16 v[50:53], v[204:207], v[212:215], v[50:53]
	v_mfma_f32_16x16x32_bf16 v[38:41], v[196:199], v[220:223], v[38:41]
	v_mfma_f32_16x16x32_bf16 v[34:37], v[204:207], v[220:223], v[34:37]
	v_mfma_f32_16x16x32_bf16 v[22:25], v[196:199], v[228:231], v[22:25]
	v_mfma_f32_16x16x32_bf16 v[18:21], v[204:207], v[228:231], v[18:21]
	v_mfma_f32_16x16x32_bf16 v[6:9], v[196:199], v[236:239], v[6:9]
	v_mfma_f32_16x16x32_bf16 v[2:5], v[204:207], v[236:239], v[2:5]
	v_mfma_f32_16x16x32_bf16 v[54:57], v[200:203], v[216:219], v[54:57]
	v_mfma_f32_16x16x32_bf16 v[50:53], v[208:211], v[216:219], v[50:53]
	v_mfma_f32_16x16x32_bf16 v[38:41], v[200:203], v[224:227], v[38:41]
	v_mfma_f32_16x16x32_bf16 v[34:37], v[208:211], v[224:227], v[34:37]
	v_mfma_f32_16x16x32_bf16 v[22:25], v[200:203], v[232:235], v[22:25]
	v_mfma_f32_16x16x32_bf16 v[18:21], v[208:211], v[232:235], v[18:21]
	s_barrier
	s_setprio 2
	v_mfma_f32_16x16x32_bf16 v[6:9], v[200:203], v[240:243], v[6:9]
	v_mfma_f32_16x16x32_bf16 v[2:5], v[208:211], v[240:243], v[2:5]
	s_setprio 0
	s_add_i32 s71, 0, 0x18000
	v_add_u32_e32 v133, s71, v149
	s_add_i32 s73, 0, 0x1c000
	ds_read_b128 v[144:147], v133
	ds_read_b128 v[184:187], v133 offset:1024
	ds_read_b128 v[188:191], v133 offset:2048
	ds_read_b128 v[192:195], v133 offset:3072
	v_add_u32_e32 v133, s73, v149
	ds_read_b128 v[196:199], v133
	ds_read_b128 v[200:203], v133 offset:1024
	ds_read_b128 v[204:207], v133 offset:2048
	ds_read_b128 v[208:211], v133 offset:3072
	s_mov_b32 m0, s55
	v_lshl_add_u64 v[248:249], v[246:247], 0, s[14:15]
	ds_read_b128 v[212:215], v170 offset:32768
	ds_read_b128 v[216:219], v170 offset:33792
	ds_read_b128 v[220:223], v170 offset:34816
	ds_read_b128 v[224:227], v170 offset:35840
	ds_read_b128 v[228:231], v170 offset:36864
	ds_read_b128 v[232:235], v170 offset:37888
	ds_read_b128 v[236:239], v170 offset:38912
	ds_read_b128 v[240:243], v170 offset:39936
	global_load_lds_dwordx4 v[248:249], off
	v_lshl_add_u64 v[248:249], v[246:247], 0, s[18:19]
	s_mov_b32 m0, s56
	s_nop 0
	global_load_lds_dwordx4 v[248:249], off
	s_waitcnt vmcnt(8)
	s_waitcnt lgkmcnt(0)
	s_barrier
	s_setprio 1
	s_waitcnt lgkmcnt(0)
	v_mfma_f32_16x16x32_bf16 v[126:129], v[144:147], v[212:215], v[126:129]
	v_mfma_f32_16x16x32_bf16 v[122:125], v[188:191], v[212:215], v[122:125]
	v_mfma_f32_16x16x32_bf16 v[110:113], v[144:147], v[220:223], v[110:113]
	v_mfma_f32_16x16x32_bf16 v[106:109], v[188:191], v[220:223], v[106:109]
	v_mfma_f32_16x16x32_bf16 v[94:97], v[144:147], v[228:231], v[94:97]
	v_mfma_f32_16x16x32_bf16 v[90:93], v[188:191], v[228:231], v[90:93]
	v_mfma_f32_16x16x32_bf16 v[78:81], v[144:147], v[236:239], v[78:81]
	v_mfma_f32_16x16x32_bf16 v[74:77], v[188:191], v[236:239], v[74:77]
	v_mfma_f32_16x16x32_bf16 v[126:129], v[184:187], v[216:219], v[126:129]
	v_mfma_f32_16x16x32_bf16 v[122:125], v[192:195], v[216:219], v[122:125]
	v_mfma_f32_16x16x32_bf16 v[110:113], v[184:187], v[224:227], v[110:113]
	v_mfma_f32_16x16x32_bf16 v[106:109], v[192:195], v[224:227], v[106:109]
	v_mfma_f32_16x16x32_bf16 v[94:97], v[184:187], v[232:235], v[94:97]
	v_mfma_f32_16x16x32_bf16 v[90:93], v[192:195], v[232:235], v[90:93]
	v_mfma_f32_16x16x32_bf16 v[78:81], v[184:187], v[240:243], v[78:81]
	v_mfma_f32_16x16x32_bf16 v[74:77], v[192:195], v[240:243], v[74:77]
	v_mfma_f32_16x16x32_bf16 v[118:121], v[196:199], v[212:215], v[118:121]
	v_mfma_f32_16x16x32_bf16 v[114:117], v[204:207], v[212:215], v[114:117]
	v_mfma_f32_16x16x32_bf16 v[102:105], v[196:199], v[220:223], v[102:105]
	v_mfma_f32_16x16x32_bf16 v[98:101], v[204:207], v[220:223], v[98:101]
	v_mfma_f32_16x16x32_bf16 v[86:89], v[196:199], v[228:231], v[86:89]
	v_mfma_f32_16x16x32_bf16 v[82:85], v[204:207], v[228:231], v[82:85]
	v_mfma_f32_16x16x32_bf16 v[70:73], v[196:199], v[236:239], v[70:73]
	v_mfma_f32_16x16x32_bf16 v[66:69], v[204:207], v[236:239], v[66:69]
	v_mfma_f32_16x16x32_bf16 v[118:121], v[200:203], v[216:219], v[118:121]
	v_mfma_f32_16x16x32_bf16 v[114:117], v[208:211], v[216:219], v[114:117]
	s_barrier
; #define PG8_STAGE(bufoff, gbase, voff) do { if constexpr (!pg8_noload<Epi>::value) { _Pragma("unroll") for (int _i = 0; _i < 2; ++_i) \
;         __builtin_amdgcn_global_load_lds((const unsigned*)((const char*)(gbase) + (size_t)_i * pstep + (voff)[0]), (PG8_LAS unsigned*)(lds + (bufoff) + ldsw + _i * 8192), 16, 0, 0); } } while (0)
; #define PG8_LDA(dst, b, h) do { _Pragma("unroll") for (int m = 0; m < 4; ++m) _Pragma("unroll") for (int k = 0; k < 2; ++k) dst[m][k] = *(const PG8_LAS bf16x8*)(lds + PG8_SA(b, h) + aoff + m * 2048 + k * 1024); } while (0)
; #define PG8_MMA(ai, bj, At, Bt) do { __builtin_amdgcn_s_setprio(1); _Pragma("unroll") for (int m = 0; m < 4; ++m) _Pragma("unroll") for (int n = 0; n < 2; ++n) _Pragma("unroll") for (int k = 0; k < 2; ++k) \
;         acc[ai][bj][m][n] = __builtin_amdgcn_mfma_f32_16x16x32_bf16(Bt[n][k], At[m][k], acc[ai][bj][m][n], 0, 0, 0); __builtin_amdgcn_s_setprio(0); } while (0)
; #define PG8_WAIT_V(n) asm volatile("s_waitcnt vmcnt(" #n ")" ::: "memory")
; #define PG8_WAIT_L(n) asm volatile("s_waitcnt lgkmcnt(" #n ")" ::: "memory")
; #define PG8_BAR __builtin_amdgcn_s_barrier()
; #define PG8_SCHED __builtin_amdgcn_sched_barrier(0)
; template <class Epi, class Sched, bool ALIGN_EPI = false, bool SP2 = false, bool ABLK = false>
; __device__ __forceinline__ void gemm_phase(PG8_LAS unsigned char* lds, const Gemm g, const Sched& S, const Epi& E) {
;     ...
;             PG8_WAIT_V(8); PG8_WAIT_L(0); PG8_BAR; PG8_MMA(0, 0, At, B0); PG8_MMA(0, 1, At, B1); PG8_BAR; PG8_SCHED;
;             PG8_LDA(At, 1, 1); PG8_STAGE(PG8_SB(1, 0), b3, voffB); PG8_STAGE(PG8_SB(1, 1), b3 + hstep, voffB); PG8_STAGE(PG8_SA(1, 0), a3, voffA);
;             PG8_WAIT_V(8); PG8_WAIT_L(0); PG8_BAR; PG8_MMA(1, 0, At, B0); PG8_MMA(1, 1, At, B1); PG8_BAR; PG8_SCHED;
	s_setprio 2
	v_mfma_f32_16x16x32_bf16 v[102:105], v[200:203], v[224:227], v[102:105]
	v_mfma_f32_16x16x32_bf16 v[98:101], v[208:211], v[224:227], v[98:101]
	v_mfma_f32_16x16x32_bf16 v[86:89], v[200:203], v[232:235], v[86:89]
	v_mfma_f32_16x16x32_bf16 v[82:85], v[208:211], v[232:235], v[82:85]
	v_mfma_f32_16x16x32_bf16 v[70:73], v[200:203], v[240:243], v[70:73]
	v_mfma_f32_16x16x32_bf16 v[66:69], v[208:211], v[240:243], v[66:69]
	s_setprio 0
	s_add_i32 s71, s71, s52
	v_lshl_add_u64 v[248:249], v[244:245], 0, s[28:29]
	s_mov_b32 m0, s71
	ds_read_b128 v[212:215], v170 offset:49152
	ds_read_b128 v[216:219], v170 offset:50176
	ds_read_b128 v[220:223], v170 offset:51200
	ds_read_b128 v[224:227], v170 offset:52224
	ds_read_b128 v[228:231], v170 offset:53248
	ds_read_b128 v[232:235], v170 offset:54272
	ds_read_b128 v[236:239], v170 offset:55296
	ds_read_b128 v[240:243], v170 offset:56320
	global_load_lds_dwordx4 v[248:249], off
	v_lshl_add_u64 v[248:249], v[244:245], 0, s[30:31]
	s_add_i32 m0, s71, 0x2000
	s_add_i32 s71, s73, s52
	global_load_lds_dwordx4 v[248:249], off
	v_lshl_add_u64 v[248:249], v[244:245], 0, s[34:35]
	s_mov_b32 m0, s71
	v_lshl_add_u64 v[244:245], v[244:245], 0, s[36:37]
	global_load_lds_dwordx4 v[248:249], off
	s_add_i32 m0, s71, 0x2000
	s_nop 0
	global_load_lds_dwordx4 v[244:245], off
	v_lshl_add_u64 v[244:245], v[246:247], 0, s[28:29]
	s_mov_b32 m0, s59
	s_nop 0
	global_load_lds_dwordx4 v[244:245], off
	v_lshl_add_u64 v[244:245], v[246:247], 0, s[30:31]
	s_mov_b32 m0, s60
	s_nop 0
	global_load_lds_dwordx4 v[244:245], off
	s_waitcnt vmcnt(8)
	s_waitcnt lgkmcnt(0)
	s_barrier
	s_setprio 1
	s_waitcnt lgkmcnt(0)
	v_mfma_f32_16x16x32_bf16 v[62:65], v[144:147], v[212:215], v[62:65]
	v_mfma_f32_16x16x32_bf16 v[58:61], v[188:191], v[212:215], v[58:61]
	v_mfma_f32_16x16x32_bf16 v[46:49], v[144:147], v[220:223], v[46:49]
	v_mfma_f32_16x16x32_bf16 v[42:45], v[188:191], v[220:223], v[42:45]
	v_mfma_f32_16x16x32_bf16 v[30:33], v[144:147], v[228:231], v[30:33]
	v_mfma_f32_16x16x32_bf16 v[26:29], v[188:191], v[228:231], v[26:29]
	v_mfma_f32_16x16x32_bf16 v[14:17], v[144:147], v[236:239], v[14:17]
	v_mfma_f32_16x16x32_bf16 v[10:13], v[188:191], v[236:239], v[10:13]
	v_mfma_f32_16x16x32_bf16 v[62:65], v[184:187], v[216:219], v[62:65]
	v_mfma_f32_16x16x32_bf16 v[58:61], v[192:195], v[216:219], v[58:61]
	v_mfma_f32_16x16x32_bf16 v[46:49], v[184:187], v[224:227], v[46:49]
	v_mfma_f32_16x16x32_bf16 v[42:45], v[192:195], v[224:227], v[42:45]
	v_mfma_f32_16x16x32_bf16 v[30:33], v[184:187], v[232:235], v[30:33]
	v_mfma_f32_16x16x32_bf16 v[26:29], v[192:195], v[232:235], v[26:29]
	v_mfma_f32_16x16x32_bf16 v[14:17], v[184:187], v[240:243], v[14:17]
	v_mfma_f32_16x16x32_bf16 v[10:13], v[192:195], v[240:243], v[10:13]
	v_mfma_f32_16x16x32_bf16 v[54:57], v[196:199], v[212:215], v[54:57]
	v_mfma_f32_16x16x32_bf16 v[50:53], v[204:207], v[212:215], v[50:53]
	v_mfma_f32_16x16x32_bf16 v[38:41], v[196:199], v[220:223], v[38:41]
	v_mfma_f32_16x16x32_bf16 v[34:37], v[204:207], v[220:223], v[34:37]
	v_mfma_f32_16x16x32_bf16 v[22:25], v[196:199], v[228:231], v[22:25]
	v_mfma_f32_16x16x32_bf16 v[18:21], v[204:207], v[228:231], v[18:21]
	v_mfma_f32_16x16x32_bf16 v[6:9], v[196:199], v[236:239], v[6:9]
	v_mfma_f32_16x16x32_bf16 v[2:5], v[204:207], v[236:239], v[2:5]
	v_mfma_f32_16x16x32_bf16 v[54:57], v[200:203], v[216:219], v[54:57]
	v_mfma_f32_16x16x32_bf16 v[50:53], v[208:211], v[216:219], v[50:53]
	v_mfma_f32_16x16x32_bf16 v[38:41], v[200:203], v[224:227], v[38:41]
	v_mfma_f32_16x16x32_bf16 v[34:37], v[208:211], v[224:227], v[34:37]
	v_mfma_f32_16x16x32_bf16 v[22:25], v[200:203], v[232:235], v[22:25]
	v_mfma_f32_16x16x32_bf16 v[18:21], v[208:211], v[232:235], v[18:21]
	s_barrier
	s_setprio 2
	v_mfma_f32_16x16x32_bf16 v[6:9], v[200:203], v[240:243], v[6:9]
	v_mfma_f32_16x16x32_bf16 v[2:5], v[208:211], v[240:243], v[2:5]
	s_setprio 0
	s_add_i32 s70, s70, 2
	s_add_u32 vcc_lo, vcc_lo, 0x1000
	s_addc_u32 vcc_hi, vcc_hi, 0
	s_add_u32 s16, s16, 0x1000
	s_addc_u32 s17, s17, 0
	s_cmp_gt_u32 s70, 29
	s_cbranch_scc0 .LBB0_114
	s_and_b64 vcc, exec, s[38:39]
	s_cbranch_vccz .LBB0_117
	s_barrier

; #define PG8_STAGE(bufoff, gbase, voff) do { if constexpr (!pg8_noload<Epi>::value) { _Pragma("unroll") for (int _i = 0; _i < 2; ++_i) \
;         __builtin_amdgcn_global_load_lds((const unsigned*)((const char*)(gbase) + (size_t)_i * pstep + (voff)[0]), (PG8_LAS unsigned*)(lds + (bufoff) + ldsw + _i * 8192), 16, 0, 0); } } while (0)
; #define PG8_LDA(dst, b, h) do { _Pragma("unroll") for (int m = 0; m < 4; ++m) _Pragma("unroll") for (int k = 0; k < 2; ++k) dst[m][k] = *(const PG8_LAS bf16x8*)(lds + PG8_SA(b, h) + aoff + m * 2048 + k * 1024); } while (0)
; #define PG8_LDB(dst, b, h) do { _Pragma("unroll") for (int n = 0; n < 2; ++n) _Pragma("unroll") for (int k = 0; k < 2; ++k) dst[n][k] = *(const PG8_LAS bf16x8*)(lds + PG8_SB(b, h) + boff + n * 2048 + k * 1024); } while (0)
; #define PG8_MMA(ai, bj, At, Bt) do { __builtin_amdgcn_s_setprio(1); _Pragma("unroll") for (int m = 0; m < 4; ++m) _Pragma("unroll") for (int n = 0; n < 2; ++n) _Pragma("unroll") for (int k = 0; k < 2; ++k) \
;         acc[ai][bj][m][n] = __builtin_amdgcn_mfma_f32_16x16x32_bf16(Bt[n][k], At[m][k], acc[ai][bj][m][n], 0, 0, 0); __builtin_amdgcn_s_setprio(0); } while (0)
; #define PG8_WAIT_V(n) asm volatile("s_waitcnt vmcnt(" #n ")" ::: "memory")
; #define PG8_WAIT_L(n) asm volatile("s_waitcnt lgkmcnt(" #n ")" ::: "memory")
; #define PG8_BAR __builtin_amdgcn_s_barrier()
; #define PG8_SCHED __builtin_amdgcn_sched_barrier(0)
; template <class Epi, class Sched, bool ALIGN_EPI = false, bool SP2 = false, bool ABLK = false>
; __device__ __forceinline__ void gemm_phase(PG8_LAS unsigned char* lds, const Gemm g, const Sched& S, const Epi& E) {
;     ...
;             PG8_LDB(B0, 0, 0); PG8_LDB(B1, 0, 1); PG8_SCHED; PG8_LDA(At, 0, 0); PG8_STAGE(PG8_SA(1, 1), a1 + hstep, voffA);
;             PG8_WAIT_V(8); PG8_WAIT_L(0); PG8_BAR; PG8_MMA(0, 0, At, B0); PG8_MMA(0, 1, At, B1); PG8_BAR; PG8_SCHED;
;             PG8_LDA(At, 0, 1); PG8_STAGE(PG8_SB(0, 0), b2, voffB); PG8_STAGE(PG8_SB(0, 1), b2 + hstep, voffB); PG8_STAGE(PG8_SA(0, 0), a2, voffA);
;             PG8_WAIT_V(8); PG8_WAIT_L(0); PG8_BAR; PG8_MMA(1, 0, At, B0); PG8_MMA(1, 1, At, B1); PG8_BAR; PG8_SCHED;
.LBB0_487:
	ds_read_b128 v[114:117], v167
	ds_read_b128 v[126:129], v167 offset:1024
	ds_read_b128 v[130:133], v167 offset:2048
	ds_read_b128 v[142:145], v167 offset:3072
	ds_read_b128 v[146:149], v168
	ds_read_b128 v[150:153], v168 offset:1024
	ds_read_b128 v[174:177], v168 offset:2048
	ds_read_b128 v[178:181], v168 offset:3072
	s_add_i32 s65, s39, 2
	s_add_u32 s68, s92, 0xfff00800
	s_addc_u32 s69, s93, -1
	s_cmp_eq_u32 s3, s39
	s_cselect_b32 s69, s79, s69
	s_cselect_b32 s68, s78, s68
	s_cselect_b32 s71, s89, s37
	s_cselect_b32 s70, s88, s11
	v_lshl_add_u64 v[162:163], s[92:93], 0, v[158:159]
	s_add_i32 m0, s56, 0xc000
	ds_read_b128 v[184:187], v169
	ds_read_b128 v[188:191], v169 offset:1024
	ds_read_b128 v[192:195], v169 offset:2048
	ds_read_b128 v[196:199], v169 offset:3072
	ds_read_b128 v[200:203], v169 offset:4096
	ds_read_b128 v[204:207], v169 offset:5120
	ds_read_b128 v[208:211], v169 offset:6144
	ds_read_b128 v[212:215], v169 offset:7168
	global_load_lds_dwordx4 v[162:163], off
	v_lshl_add_u64 v[162:163], v[162:163], 0, s[12:13]
	s_add_i32 m0, s56, 0xe000
	s_nop 0
	global_load_lds_dwordx4 v[162:163], off
	s_waitcnt vmcnt(8)
	s_waitcnt lgkmcnt(0)
	s_barrier
	s_setprio 1
	s_waitcnt lgkmcnt(0)
	v_mfma_f32_16x16x32_bf16 v[138:141], v[114:117], v[184:187], v[138:141]
	v_mfma_f32_16x16x32_bf16 v[134:137], v[130:133], v[184:187], v[134:137]
	v_mfma_f32_16x16x32_bf16 v[110:113], v[114:117], v[192:195], v[110:113]
	v_mfma_f32_16x16x32_bf16 v[106:109], v[130:133], v[192:195], v[106:109]
	v_mfma_f32_16x16x32_bf16 v[94:97], v[114:117], v[200:203], v[94:97]
	v_mfma_f32_16x16x32_bf16 v[90:93], v[130:133], v[200:203], v[90:93]
	v_mfma_f32_16x16x32_bf16 v[78:81], v[114:117], v[208:211], v[78:81]
	v_mfma_f32_16x16x32_bf16 v[74:77], v[130:133], v[208:211], v[74:77]
	v_mfma_f32_16x16x32_bf16 v[138:141], v[126:129], v[188:191], v[138:141]
	v_mfma_f32_16x16x32_bf16 v[134:137], v[142:145], v[188:191], v[134:137]
	v_mfma_f32_16x16x32_bf16 v[110:113], v[126:129], v[196:199], v[110:113]
	v_mfma_f32_16x16x32_bf16 v[106:109], v[142:145], v[196:199], v[106:109]
	v_mfma_f32_16x16x32_bf16 v[94:97], v[126:129], v[204:207], v[94:97]
	v_mfma_f32_16x16x32_bf16 v[90:93], v[142:145], v[204:207], v[90:93]
	v_mfma_f32_16x16x32_bf16 v[78:81], v[126:129], v[212:215], v[78:81]
	v_mfma_f32_16x16x32_bf16 v[74:77], v[142:145], v[212:215], v[74:77]
	v_mfma_f32_16x16x32_bf16 v[122:125], v[146:149], v[184:187], v[122:125]
	v_mfma_f32_16x16x32_bf16 v[118:121], v[174:177], v[184:187], v[118:121]
	v_mfma_f32_16x16x32_bf16 v[102:105], v[146:149], v[192:195], v[102:105]
	v_mfma_f32_16x16x32_bf16 v[98:101], v[174:177], v[192:195], v[98:101]
	v_mfma_f32_16x16x32_bf16 v[86:89], v[146:149], v[200:203], v[86:89]
	v_mfma_f32_16x16x32_bf16 v[82:85], v[174:177], v[200:203], v[82:85]
	v_mfma_f32_16x16x32_bf16 v[70:73], v[146:149], v[208:211], v[70:73]
	v_mfma_f32_16x16x32_bf16 v[66:69], v[174:177], v[208:211], v[66:69]
	v_mfma_f32_16x16x32_bf16 v[122:125], v[150:153], v[188:191], v[122:125]
	v_mfma_f32_16x16x32_bf16 v[118:121], v[178:181], v[188:191], v[118:121]
	s_barrier
	s_setprio 2
	v_mfma_f32_16x16x32_bf16 v[102:105], v[150:153], v[196:199], v[102:105]
	v_mfma_f32_16x16x32_bf16 v[98:101], v[178:181], v[196:199], v[98:101]
	v_mfma_f32_16x16x32_bf16 v[86:89], v[150:153], v[204:207], v[86:89]
	v_mfma_f32_16x16x32_bf16 v[82:85], v[178:181], v[204:207], v[82:85]
	v_mfma_f32_16x16x32_bf16 v[70:73], v[150:153], v[212:215], v[70:73]
	v_mfma_f32_16x16x32_bf16 v[66:69], v[178:181], v[212:215], v[66:69]
	s_setprio 0
	s_add_i32 s39, s73, s55
	v_lshl_add_u64 v[162:163], s[70:71], 0, v[154:155]
	s_mov_b32 m0, s39
	ds_read_b128 v[184:187], v169 offset:16384
	ds_read_b128 v[188:191], v169 offset:17408
	ds_read_b128 v[192:195], v169 offset:18432
	ds_read_b128 v[196:199], v169 offset:19456
	ds_read_b128 v[200:203], v169 offset:20480
	ds_read_b128 v[204:207], v169 offset:21504
	ds_read_b128 v[208:211], v169 offset:22528
	ds_read_b128 v[212:215], v169 offset:23552
	global_load_lds_dwordx4 v[162:163], off
	v_lshl_add_u64 v[216:217], v[162:163], 0, s[12:13]
	s_add_i32 m0, s39, 0x2000
	s_add_i32 s39, s74, s55
	global_load_lds_dwordx4 v[216:217], off
	v_lshl_add_u64 v[216:217], v[162:163], 0, s[14:15]
	s_mov_b32 m0, s39
	s_nop 0
	global_load_lds_dwordx4 v[216:217], off
	v_lshl_add_u64 v[216:217], v[162:163], 0, s[16:17]
	s_add_i32 m0, s39, 0x2000
	s_nop 0
	global_load_lds_dwordx4 v[216:217], off
	v_lshl_add_u64 v[216:217], s[68:69], 0, v[154:155]
	s_mov_b32 m0, s56
	v_lshl_add_u64 v[218:219], v[216:217], 0, s[12:13]
	global_load_lds_dwordx4 v[216:217], off
	s_mov_b32 m0, s57
	s_nop 0
	global_load_lds_dwordx4 v[218:219], off
	s_waitcnt vmcnt(8)
	s_waitcnt lgkmcnt(0)
	s_barrier
; #define PG8_STAGE(bufoff, gbase, voff) do { if constexpr (!pg8_noload<Epi>::value) { _Pragma("unroll") for (int _i = 0; _i < 2; ++_i) \
;         __builtin_amdgcn_global_load_lds((const unsigned*)((const char*)(gbase) + (size_t)_i * pstep + (voff)[0]), (PG8_LAS unsigned*)(lds + (bufoff) + ldsw + _i * 8192), 16, 0, 0); } } while (0)
; #define PG8_LDA(dst, b, h) do { _Pragma("unroll") for (int m = 0; m < 4; ++m) _Pragma("unroll") for (int k = 0; k < 2; ++k) dst[m][k] = *(const PG8_LAS bf16x8*)(lds + PG8_SA(b, h) + aoff + m * 2048 + k * 1024); } while (0)
; #define PG8_LDB(dst, b, h) do { _Pragma("unroll") for (int n = 0; n < 2; ++n) _Pragma("unroll") for (int k = 0; k < 2; ++k) dst[n][k] = *(const PG8_LAS bf16x8*)(lds + PG8_SB(b, h) + boff + n * 2048 + k * 1024); } while (0)
; #define PG8_MMA(ai, bj, At, Bt) do { __builtin_amdgcn_s_setprio(1); _Pragma("unroll") for (int m = 0; m < 4; ++m) _Pragma("unroll") for (int n = 0; n < 2; ++n) _Pragma("unroll") for (int k = 0; k < 2; ++k) \
;         acc[ai][bj][m][n] = __builtin_amdgcn_mfma_f32_16x16x32_bf16(Bt[n][k], At[m][k], acc[ai][bj][m][n], 0, 0, 0); __builtin_amdgcn_s_setprio(0); } while (0)
; #define PG8_WAIT_V(n) asm volatile("s_waitcnt vmcnt(" #n ")" ::: "memory")
; #define PG8_WAIT_L(n) asm volatile("s_waitcnt lgkmcnt(" #n ")" ::: "memory")
; #define PG8_BAR __builtin_amdgcn_s_barrier()
; #define PG8_SCHED __builtin_amdgcn_sched_barrier(0)
; template <class Epi, class Sched, bool ALIGN_EPI = false, bool SP2 = false, bool ABLK = false>
; __device__ __forceinline__ void gemm_phase(PG8_LAS unsigned char* lds, const Gemm g, const Sched& S, const Epi& E) {
;     ...
;             PG8_WAIT_V(8); PG8_WAIT_L(0); PG8_BAR; PG8_MMA(1, 0, At, B0); PG8_MMA(1, 1, At, B1); PG8_BAR; PG8_SCHED;
;             PG8_LDB(B0, 1, 0); PG8_LDB(B1, 1, 1); PG8_SCHED; PG8_LDA(At, 1, 0); PG8_STAGE(PG8_SA(0, 1), a2 + hstep, voffA);
;             PG8_WAIT_V(8); PG8_WAIT_L(0); PG8_BAR; PG8_MMA(0, 0, At, B0); PG8_MMA(0, 1, At, B1); PG8_BAR; PG8_SCHED;
	s_setprio 1
	s_waitcnt lgkmcnt(0)
	v_mfma_f32_16x16x32_bf16 v[62:65], v[114:117], v[184:187], v[62:65]
	v_mfma_f32_16x16x32_bf16 v[58:61], v[130:133], v[184:187], v[58:61]
	v_mfma_f32_16x16x32_bf16 v[46:49], v[114:117], v[192:195], v[46:49]
	v_mfma_f32_16x16x32_bf16 v[42:45], v[130:133], v[192:195], v[42:45]
	v_mfma_f32_16x16x32_bf16 v[30:33], v[114:117], v[200:203], v[30:33]
	v_mfma_f32_16x16x32_bf16 v[26:29], v[130:133], v[200:203], v[26:29]
	v_mfma_f32_16x16x32_bf16 v[14:17], v[114:117], v[208:211], v[14:17]
	v_mfma_f32_16x16x32_bf16 v[10:13], v[130:133], v[208:211], v[10:13]
	v_mfma_f32_16x16x32_bf16 v[62:65], v[126:129], v[188:191], v[62:65]
	v_mfma_f32_16x16x32_bf16 v[58:61], v[142:145], v[188:191], v[58:61]
	v_mfma_f32_16x16x32_bf16 v[46:49], v[126:129], v[196:199], v[46:49]
	v_mfma_f32_16x16x32_bf16 v[42:45], v[142:145], v[196:199], v[42:45]
	v_mfma_f32_16x16x32_bf16 v[30:33], v[126:129], v[204:207], v[30:33]
	v_mfma_f32_16x16x32_bf16 v[26:29], v[142:145], v[204:207], v[26:29]
	v_mfma_f32_16x16x32_bf16 v[14:17], v[126:129], v[212:215], v[14:17]
	v_mfma_f32_16x16x32_bf16 v[10:13], v[142:145], v[212:215], v[10:13]
	v_mfma_f32_16x16x32_bf16 v[54:57], v[146:149], v[184:187], v[54:57]
	v_mfma_f32_16x16x32_bf16 v[50:53], v[174:177], v[184:187], v[50:53]
	v_mfma_f32_16x16x32_bf16 v[38:41], v[146:149], v[192:195], v[38:41]
	v_mfma_f32_16x16x32_bf16 v[34:37], v[174:177], v[192:195], v[34:37]
	v_mfma_f32_16x16x32_bf16 v[22:25], v[146:149], v[200:203], v[22:25]
	v_mfma_f32_16x16x32_bf16 v[18:21], v[174:177], v[200:203], v[18:21]
	v_mfma_f32_16x16x32_bf16 v[6:9], v[146:149], v[208:211], v[6:9]
	v_mfma_f32_16x16x32_bf16 v[2:5], v[174:177], v[208:211], v[2:5]
	v_mfma_f32_16x16x32_bf16 v[54:57], v[150:153], v[188:191], v[54:57]
	v_mfma_f32_16x16x32_bf16 v[50:53], v[178:181], v[188:191], v[50:53]
	v_mfma_f32_16x16x32_bf16 v[38:41], v[150:153], v[196:199], v[38:41]
	v_mfma_f32_16x16x32_bf16 v[34:37], v[178:181], v[196:199], v[34:37]
	v_mfma_f32_16x16x32_bf16 v[22:25], v[150:153], v[204:207], v[22:25]
	v_mfma_f32_16x16x32_bf16 v[18:21], v[178:181], v[204:207], v[18:21]
	s_barrier
	s_setprio 2
	v_mfma_f32_16x16x32_bf16 v[6:9], v[150:153], v[212:215], v[6:9]
	v_mfma_f32_16x16x32_bf16 v[2:5], v[178:181], v[212:215], v[2:5]
	s_setprio 0
	s_add_i32 s39, 0, 0x18000
	s_add_i32 s68, 0, 0x1c000
	v_add_u32_e32 v142, s39, v1
	v_add_u32_e32 v173, s68, v1
	ds_read_b128 v[114:117], v142
	ds_read_b128 v[126:129], v142 offset:1024
	ds_read_b128 v[130:133], v142 offset:2048
	ds_read_b128 v[142:145], v142 offset:3072
	ds_read_b128 v[146:149], v173
	ds_read_b128 v[150:153], v173 offset:1024
	ds_read_b128 v[174:177], v173 offset:2048
	ds_read_b128 v[178:181], v173 offset:3072
	s_mov_b32 m0, s58
	v_lshl_add_u64 v[218:219], v[216:217], 0, s[14:15]
	ds_read_b128 v[184:187], v169 offset:32768
	ds_read_b128 v[188:191], v169 offset:33792
	ds_read_b128 v[192:195], v169 offset:34816
	ds_read_b128 v[196:199], v169 offset:35840
	ds_read_b128 v[200:203], v169 offset:36864
	ds_read_b128 v[204:207], v169 offset:37888
	ds_read_b128 v[208:211], v169 offset:38912
	ds_read_b128 v[212:215], v169 offset:39936
	global_load_lds_dwordx4 v[218:219], off
	v_lshl_add_u64 v[218:219], v[216:217], 0, s[16:17]
	s_mov_b32 m0, s59
	s_nop 0
	global_load_lds_dwordx4 v[218:219], off
	s_waitcnt vmcnt(8)
	s_waitcnt lgkmcnt(0)
	s_barrier
	s_setprio 1
	s_waitcnt lgkmcnt(0)
	v_mfma_f32_16x16x32_bf16 v[138:141], v[114:117], v[184:187], v[138:141]
	v_mfma_f32_16x16x32_bf16 v[134:137], v[130:133], v[184:187], v[134:137]
	v_mfma_f32_16x16x32_bf16 v[110:113], v[114:117], v[192:195], v[110:113]
	v_mfma_f32_16x16x32_bf16 v[106:109], v[130:133], v[192:195], v[106:109]
	v_mfma_f32_16x16x32_bf16 v[94:97], v[114:117], v[200:203], v[94:97]
	v_mfma_f32_16x16x32_bf16 v[90:93], v[130:133], v[200:203], v[90:93]
	v_mfma_f32_16x16x32_bf16 v[78:81], v[114:117], v[208:211], v[78:81]
	v_mfma_f32_16x16x32_bf16 v[74:77], v[130:133], v[208:211], v[74:77]
	v_mfma_f32_16x16x32_bf16 v[138:141], v[126:129], v[188:191], v[138:141]
	v_mfma_f32_16x16x32_bf16 v[134:137], v[142:145], v[188:191], v[134:137]
	v_mfma_f32_16x16x32_bf16 v[110:113], v[126:129], v[196:199], v[110:113]
	v_mfma_f32_16x16x32_bf16 v[106:109], v[142:145], v[196:199], v[106:109]
	v_mfma_f32_16x16x32_bf16 v[94:97], v[126:129], v[204:207], v[94:97]
	v_mfma_f32_16x16x32_bf16 v[90:93], v[142:145], v[204:207], v[90:93]
	v_mfma_f32_16x16x32_bf16 v[78:81], v[126:129], v[212:215], v[78:81]
	v_mfma_f32_16x16x32_bf16 v[74:77], v[142:145], v[212:215], v[74:77]
	v_mfma_f32_16x16x32_bf16 v[122:125], v[146:149], v[184:187], v[122:125]
	v_mfma_f32_16x16x32_bf16 v[118:121], v[174:177], v[184:187], v[118:121]
	v_mfma_f32_16x16x32_bf16 v[102:105], v[146:149], v[192:195], v[102:105]
	v_mfma_f32_16x16x32_bf16 v[98:101], v[174:177], v[192:195], v[98:101]
	v_mfma_f32_16x16x32_bf16 v[86:89], v[146:149], v[200:203], v[86:89]
	v_mfma_f32_16x16x32_bf16 v[82:85], v[174:177], v[200:203], v[82:85]
	v_mfma_f32_16x16x32_bf16 v[70:73], v[146:149], v[208:211], v[70:73]
	v_mfma_f32_16x16x32_bf16 v[66:69], v[174:177], v[208:211], v[66:69]
	v_mfma_f32_16x16x32_bf16 v[122:125], v[150:153], v[188:191], v[122:125]
	v_mfma_f32_16x16x32_bf16 v[118:121], v[178:181], v[188:191], v[118:121]
	s_barrier
; #define PG8_STAGE(bufoff, gbase, voff) do { if constexpr (!pg8_noload<Epi>::value) { _Pragma("unroll") for (int _i = 0; _i < 2; ++_i) \
;         __builtin_amdgcn_global_load_lds((const unsigned*)((const char*)(gbase) + (size_t)_i * pstep + (voff)[0]), (PG8_LAS unsigned*)(lds + (bufoff) + ldsw + _i * 8192), 16, 0, 0); } } while (0)
; #define PG8_LDA(dst, b, h) do { _Pragma("unroll") for (int m = 0; m < 4; ++m) _Pragma("unroll") for (int k = 0; k < 2; ++k) dst[m][k] = *(const PG8_LAS bf16x8*)(lds + PG8_SA(b, h) + aoff + m * 2048 + k * 1024); } while (0)
; #define PG8_MMA(ai, bj, At, Bt) do { __builtin_amdgcn_s_setprio(1); _Pragma("unroll") for (int m = 0; m < 4; ++m) _Pragma("unroll") for (int n = 0; n < 2; ++n) _Pragma("unroll") for (int k = 0; k < 2; ++k) \
;         acc[ai][bj][m][n] = __builtin_amdgcn_mfma_f32_16x16x32_bf16(Bt[n][k], At[m][k], acc[ai][bj][m][n], 0, 0, 0); __builtin_amdgcn_s_setprio(0); } while (0)
; #define PG8_WAIT_V(n) asm volatile("s_waitcnt vmcnt(" #n ")" ::: "memory")
; #define PG8_WAIT_L(n) asm volatile("s_waitcnt lgkmcnt(" #n ")" ::: "memory")
; #define PG8_BAR __builtin_amdgcn_s_barrier()
; #define PG8_SCHED __builtin_amdgcn_sched_barrier(0)
; template <class Epi, class Sched, bool ALIGN_EPI = false, bool SP2 = false, bool ABLK = false>
; __device__ __forceinline__ void gemm_phase(PG8_LAS unsigned char* lds, const Gemm g, const Sched& S, const Epi& E) {
;     ...
;             PG8_WAIT_V(8); PG8_WAIT_L(0); PG8_BAR; PG8_MMA(0, 0, At, B0); PG8_MMA(0, 1, At, B1); PG8_BAR; PG8_SCHED;
;             PG8_LDA(At, 1, 1); PG8_STAGE(PG8_SB(1, 0), b3, voffB); PG8_STAGE(PG8_SB(1, 1), b3 + hstep, voffB); PG8_STAGE(PG8_SA(1, 0), a3, voffA);
;             PG8_WAIT_V(8); PG8_WAIT_L(0); PG8_BAR; PG8_MMA(1, 0, At, B0); PG8_MMA(1, 1, At, B1); PG8_BAR; PG8_SCHED;
	s_setprio 2
	v_mfma_f32_16x16x32_bf16 v[102:105], v[150:153], v[196:199], v[102:105]
	v_mfma_f32_16x16x32_bf16 v[98:101], v[178:181], v[196:199], v[98:101]
	v_mfma_f32_16x16x32_bf16 v[86:89], v[150:153], v[204:207], v[86:89]
	v_mfma_f32_16x16x32_bf16 v[82:85], v[178:181], v[204:207], v[82:85]
	v_mfma_f32_16x16x32_bf16 v[70:73], v[150:153], v[212:215], v[70:73]
	v_mfma_f32_16x16x32_bf16 v[66:69], v[178:181], v[212:215], v[66:69]
	s_setprio 0
	s_add_i32 s39, s39, s55
	v_lshl_add_u64 v[218:219], v[162:163], 0, s[24:25]
	s_mov_b32 m0, s39
	ds_read_b128 v[184:187], v169 offset:49152
	ds_read_b128 v[188:191], v169 offset:50176
	ds_read_b128 v[192:195], v169 offset:51200
	ds_read_b128 v[196:199], v169 offset:52224
	ds_read_b128 v[200:203], v169 offset:53248
	ds_read_b128 v[204:207], v169 offset:54272
	ds_read_b128 v[208:211], v169 offset:55296
	ds_read_b128 v[212:215], v169 offset:56320
	global_load_lds_dwordx4 v[218:219], off
	v_lshl_add_u64 v[218:219], v[162:163], 0, s[26:27]
	s_add_i32 m0, s39, 0x2000
	s_add_i32 s39, s68, s55
	global_load_lds_dwordx4 v[218:219], off
	v_lshl_add_u64 v[218:219], v[162:163], 0, s[28:29]
	s_mov_b32 m0, s39
	v_lshl_add_u64 v[162:163], v[162:163], 0, s[30:31]
	global_load_lds_dwordx4 v[218:219], off
	s_add_i32 m0, s39, 0x2000
	s_nop 0
	global_load_lds_dwordx4 v[162:163], off
	v_lshl_add_u64 v[162:163], v[216:217], 0, s[24:25]
	s_mov_b32 m0, s62
	s_nop 0
	global_load_lds_dwordx4 v[162:163], off
	v_lshl_add_u64 v[162:163], v[216:217], 0, s[26:27]
	s_mov_b32 m0, s63
	s_nop 0
	global_load_lds_dwordx4 v[162:163], off
	s_waitcnt vmcnt(8)
	s_waitcnt lgkmcnt(0)
	s_barrier
	s_setprio 1
	s_waitcnt lgkmcnt(0)
	v_mfma_f32_16x16x32_bf16 v[62:65], v[114:117], v[184:187], v[62:65]
	v_mfma_f32_16x16x32_bf16 v[58:61], v[130:133], v[184:187], v[58:61]
	v_mfma_f32_16x16x32_bf16 v[46:49], v[114:117], v[192:195], v[46:49]
	v_mfma_f32_16x16x32_bf16 v[42:45], v[130:133], v[192:195], v[42:45]
	v_mfma_f32_16x16x32_bf16 v[30:33], v[114:117], v[200:203], v[30:33]
	v_mfma_f32_16x16x32_bf16 v[26:29], v[130:133], v[200:203], v[26:29]
	v_mfma_f32_16x16x32_bf16 v[14:17], v[114:117], v[208:211], v[14:17]
	v_mfma_f32_16x16x32_bf16 v[10:13], v[130:133], v[208:211], v[10:13]
	v_mfma_f32_16x16x32_bf16 v[62:65], v[126:129], v[188:191], v[62:65]
	v_mfma_f32_16x16x32_bf16 v[58:61], v[142:145], v[188:191], v[58:61]
	v_mfma_f32_16x16x32_bf16 v[46:49], v[126:129], v[196:199], v[46:49]
	v_mfma_f32_16x16x32_bf16 v[42:45], v[142:145], v[196:199], v[42:45]
	v_mfma_f32_16x16x32_bf16 v[30:33], v[126:129], v[204:207], v[30:33]
	v_mfma_f32_16x16x32_bf16 v[26:29], v[142:145], v[204:207], v[26:29]
	v_mfma_f32_16x16x32_bf16 v[14:17], v[126:129], v[212:215], v[14:17]
	v_mfma_f32_16x16x32_bf16 v[10:13], v[142:145], v[212:215], v[10:13]
	v_mfma_f32_16x16x32_bf16 v[54:57], v[146:149], v[184:187], v[54:57]
	v_mfma_f32_16x16x32_bf16 v[50:53], v[174:177], v[184:187], v[50:53]
	v_mfma_f32_16x16x32_bf16 v[38:41], v[146:149], v[192:195], v[38:41]
	v_mfma_f32_16x16x32_bf16 v[34:37], v[174:177], v[192:195], v[34:37]
	v_mfma_f32_16x16x32_bf16 v[22:25], v[146:149], v[200:203], v[22:25]
	v_mfma_f32_16x16x32_bf16 v[18:21], v[174:177], v[200:203], v[18:21]
	v_mfma_f32_16x16x32_bf16 v[6:9], v[146:149], v[208:211], v[6:9]
	v_mfma_f32_16x16x32_bf16 v[2:5], v[174:177], v[208:211], v[2:5]
	v_mfma_f32_16x16x32_bf16 v[54:57], v[150:153], v[188:191], v[54:57]
	v_mfma_f32_16x16x32_bf16 v[50:53], v[178:181], v[188:191], v[50:53]
	v_mfma_f32_16x16x32_bf16 v[38:41], v[150:153], v[196:199], v[38:41]
	v_mfma_f32_16x16x32_bf16 v[34:37], v[178:181], v[196:199], v[34:37]
	v_mfma_f32_16x16x32_bf16 v[22:25], v[150:153], v[204:207], v[22:25]
	v_mfma_f32_16x16x32_bf16 v[18:21], v[178:181], v[204:207], v[18:21]
	s_barrier
	s_setprio 2
	v_mfma_f32_16x16x32_bf16 v[6:9], v[150:153], v[212:215], v[6:9]
	v_mfma_f32_16x16x32_bf16 v[2:5], v[178:181], v[212:215], v[2:5]
	s_setprio 0
	s_add_u32 s92, s92, 0x1000
	s_addc_u32 s93, s93, 0
	s_add_u32 s11, s11, 0x1000
	s_addc_u32 s37, s37, 0
	s_cmp_ge_i32 s65, s80
	s_mov_b32 s39, s65
	s_cbranch_scc0 .LBB0_487
	s_and_b64 vcc, exec, s[34:35]
	s_cbranch_vccnz .LBB0_492
	s_lshl_b32 s11, s2, 8
	s_cmp_gt_i32 s2, 63
	s_mov_b64 s[68:69], -1
	s_cbranch_scc1 .LBB0_493

; #define PG8_STAGE(bufoff, gbase, voff) do { if constexpr (!pg8_noload<Epi>::value) { _Pragma("unroll") for (int _i = 0; _i < 2; ++_i) \
;         __builtin_amdgcn_global_load_lds((const unsigned*)((const char*)(gbase) + (size_t)_i * pstep + (voff)[0]), (PG8_LAS unsigned*)(lds + (bufoff) + ldsw + _i * 8192), 16, 0, 0); } } while (0)
; #define PG8_LDA(dst, b, h) do { _Pragma("unroll") for (int m = 0; m < 4; ++m) _Pragma("unroll") for (int k = 0; k < 2; ++k) dst[m][k] = *(const PG8_LAS bf16x8*)(lds + PG8_SA(b, h) + aoff + m * 2048 + k * 1024); } while (0)
; #define PG8_LDB(dst, b, h) do { _Pragma("unroll") for (int n = 0; n < 2; ++n) _Pragma("unroll") for (int k = 0; k < 2; ++k) dst[n][k] = *(const PG8_LAS bf16x8*)(lds + PG8_SB(b, h) + boff + n * 2048 + k * 1024); } while (0)
; #define PG8_MMA(ai, bj, At, Bt) do { __builtin_amdgcn_s_setprio(1); _Pragma("unroll") for (int m = 0; m < 4; ++m) _Pragma("unroll") for (int n = 0; n < 2; ++n) _Pragma("unroll") for (int k = 0; k < 2; ++k) \
;         acc[ai][bj][m][n] = __builtin_amdgcn_mfma_f32_16x16x32_bf16(Bt[n][k], At[m][k], acc[ai][bj][m][n], 0, 0, 0); __builtin_amdgcn_s_setprio(0); } while (0)
; #define PG8_WAIT_V(n) asm volatile("s_waitcnt vmcnt(" #n ")" ::: "memory")
; #define PG8_WAIT_L(n) asm volatile("s_waitcnt lgkmcnt(" #n ")" ::: "memory")
; #define PG8_BAR __builtin_amdgcn_s_barrier()
; #define PG8_SCHED __builtin_amdgcn_sched_barrier(0)
; template <class Epi, class Sched, bool ALIGN_EPI = false, bool SP2 = false, bool ABLK = false>
; __device__ __forceinline__ void gemm_phase(PG8_LAS unsigned char* lds, const Gemm g, const Sched& S, const Epi& E) {
;     ...
;             PG8_LDB(B0, 0, 0); PG8_LDB(B1, 0, 1); PG8_SCHED; PG8_LDA(At, 0, 0); PG8_STAGE(PG8_SA(1, 1), a1 + hstep, voffA);
;             PG8_WAIT_V(8); PG8_WAIT_L(0); PG8_BAR; PG8_MMA(0, 0, At, B0); PG8_MMA(0, 1, At, B1); PG8_BAR; PG8_SCHED;
;             PG8_LDA(At, 0, 1); PG8_STAGE(PG8_SB(0, 0), b2, voffB); PG8_STAGE(PG8_SB(0, 1), b2 + hstep, voffB); PG8_STAGE(PG8_SA(0, 0), a2, voffA);
;             PG8_WAIT_V(8); PG8_WAIT_L(0); PG8_BAR; PG8_MMA(1, 0, At, B0); PG8_MMA(1, 1, At, B1); PG8_BAR; PG8_SCHED;
.LBB0_619:
	s_or_b32 s28, s57, 1
	s_lshl_b64 s[58:59], s[28:29], 11
	s_add_u32 s58, s2, s58
	s_addc_u32 s59, s3, s59
	s_add_i32 s28, s57, 2
	v_add_u32_e32 v160, s78, v168
	v_add_u32_e32 v180, s79, v168
	s_lshl_b64 s[60:61], s[28:29], 11
	ds_read_b128 v[130:133], v160
	ds_read_b128 v[134:137], v160 offset:1024
	ds_read_b128 v[156:159], v160 offset:2048
	ds_read_b128 v[160:163], v160 offset:3072
	ds_read_b128 v[164:167], v180
	ds_read_b128 v[176:179], v180 offset:1024
	ds_read_b128 v[184:187], v180 offset:2048
	ds_read_b128 v[188:191], v180 offset:3072
	s_add_u32 s66, s2, s60
	s_addc_u32 s67, s3, s61
	s_and_b64 s[62:63], s[68:69], exec
	s_cselect_b32 s73, s67, s7
	s_cselect_b32 s72, s66, s15
	s_add_u32 s62, s16, s60
	s_addc_u32 s63, s17, s61
	s_and_b64 s[60:61], s[68:69], exec
	s_cselect_b32 s61, s63, s9
	s_cselect_b32 s60, s62, s56
	v_lshl_add_u64 v[180:181], s[58:59], 0, v[138:139]
	v_lshl_add_u64 v[224:225], v[180:181], 0, s[24:25]
	s_add_i32 m0, s70, 0xc000
	ds_read_b128 v[192:195], v173
	ds_read_b128 v[196:199], v173 offset:1024
	ds_read_b128 v[200:203], v173 offset:2048
	ds_read_b128 v[204:207], v173 offset:3072
	ds_read_b128 v[208:211], v173 offset:4096
	ds_read_b128 v[212:215], v173 offset:5120
	ds_read_b128 v[216:219], v173 offset:6144
	ds_read_b128 v[220:223], v173 offset:7168
	global_load_lds_dwordx4 v[224:225], off
	v_lshl_add_u64 v[180:181], v[180:181], 0, s[26:27]
	s_add_i32 m0, s70, 0xe000
	s_nop 0
	global_load_lds_dwordx4 v[180:181], off
	s_waitcnt vmcnt(8)
	s_waitcnt lgkmcnt(0)
	s_barrier
	s_setprio 1
	s_waitcnt lgkmcnt(0)
	v_mfma_f32_16x16x32_bf16 v[126:129], v[130:133], v[192:195], v[126:129]
	v_mfma_f32_16x16x32_bf16 v[122:125], v[156:159], v[192:195], v[122:125]
	v_mfma_f32_16x16x32_bf16 v[110:113], v[130:133], v[200:203], v[110:113]
	v_mfma_f32_16x16x32_bf16 v[106:109], v[156:159], v[200:203], v[106:109]
	v_mfma_f32_16x16x32_bf16 v[94:97], v[130:133], v[208:211], v[94:97]
	v_mfma_f32_16x16x32_bf16 v[90:93], v[156:159], v[208:211], v[90:93]
	v_mfma_f32_16x16x32_bf16 v[78:81], v[130:133], v[216:219], v[78:81]
	v_mfma_f32_16x16x32_bf16 v[74:77], v[156:159], v[216:219], v[74:77]
	v_mfma_f32_16x16x32_bf16 v[126:129], v[134:137], v[196:199], v[126:129]
	v_mfma_f32_16x16x32_bf16 v[122:125], v[160:163], v[196:199], v[122:125]
	v_mfma_f32_16x16x32_bf16 v[110:113], v[134:137], v[204:207], v[110:113]
	v_mfma_f32_16x16x32_bf16 v[106:109], v[160:163], v[204:207], v[106:109]
	v_mfma_f32_16x16x32_bf16 v[94:97], v[134:137], v[212:215], v[94:97]
	v_mfma_f32_16x16x32_bf16 v[90:93], v[160:163], v[212:215], v[90:93]
	v_mfma_f32_16x16x32_bf16 v[78:81], v[134:137], v[220:223], v[78:81]
	v_mfma_f32_16x16x32_bf16 v[74:77], v[160:163], v[220:223], v[74:77]
	v_mfma_f32_16x16x32_bf16 v[118:121], v[164:167], v[192:195], v[118:121]
	v_mfma_f32_16x16x32_bf16 v[114:117], v[184:187], v[192:195], v[114:117]
	v_mfma_f32_16x16x32_bf16 v[102:105], v[164:167], v[200:203], v[102:105]
	v_mfma_f32_16x16x32_bf16 v[98:101], v[184:187], v[200:203], v[98:101]
	v_mfma_f32_16x16x32_bf16 v[86:89], v[164:167], v[208:211], v[86:89]
	v_mfma_f32_16x16x32_bf16 v[82:85], v[184:187], v[208:211], v[82:85]
	v_mfma_f32_16x16x32_bf16 v[70:73], v[164:167], v[216:219], v[70:73]
	v_mfma_f32_16x16x32_bf16 v[66:69], v[184:187], v[216:219], v[66:69]
	v_mfma_f32_16x16x32_bf16 v[118:121], v[176:179], v[196:199], v[118:121]
	v_mfma_f32_16x16x32_bf16 v[114:117], v[188:191], v[196:199], v[114:117]
	s_barrier
	s_setprio 2
	v_mfma_f32_16x16x32_bf16 v[102:105], v[176:179], v[204:207], v[102:105]
	v_mfma_f32_16x16x32_bf16 v[98:101], v[188:191], v[204:207], v[98:101]
	v_mfma_f32_16x16x32_bf16 v[86:89], v[176:179], v[212:215], v[86:89]
	v_mfma_f32_16x16x32_bf16 v[82:85], v[188:191], v[212:215], v[82:85]
	v_mfma_f32_16x16x32_bf16 v[70:73], v[176:179], v[220:223], v[70:73]
	v_mfma_f32_16x16x32_bf16 v[66:69], v[188:191], v[220:223], v[66:69]
	s_setprio 0
	s_add_i32 s58, s78, s91
	v_lshl_add_u64 v[180:181], s[60:61], 0, v[138:139]
	s_mov_b32 m0, s58
	ds_read_b128 v[192:195], v173 offset:16384
	ds_read_b128 v[196:199], v173 offset:17408
	ds_read_b128 v[200:203], v173 offset:18432
	ds_read_b128 v[204:207], v173 offset:19456
	ds_read_b128 v[208:211], v173 offset:20480
	ds_read_b128 v[212:215], v173 offset:21504
	ds_read_b128 v[216:219], v173 offset:22528
	ds_read_b128 v[220:223], v173 offset:23552
	global_load_lds_dwordx4 v[180:181], off
	v_lshl_add_u64 v[224:225], v[180:181], 0, s[22:23]
	s_add_i32 m0, s58, 0x2000
	s_add_i32 s58, s79, s91
	global_load_lds_dwordx4 v[224:225], off
	v_lshl_add_u64 v[224:225], v[180:181], 0, s[24:25]
	s_mov_b32 m0, s58
	s_nop 0
	global_load_lds_dwordx4 v[224:225], off
	v_lshl_add_u64 v[224:225], v[180:181], 0, s[26:27]
	s_add_i32 m0, s58, 0x2000
	s_nop 0
	global_load_lds_dwordx4 v[224:225], off
	v_lshl_add_u64 v[224:225], s[72:73], 0, v[138:139]
	s_mov_b32 m0, s70
	v_lshl_add_u64 v[226:227], v[224:225], 0, s[22:23]
	global_load_lds_dwordx4 v[224:225], off
	s_mov_b32 m0, s71
	s_nop 0
	global_load_lds_dwordx4 v[226:227], off
	s_waitcnt vmcnt(8)
	s_waitcnt lgkmcnt(0)
	s_barrier
; #define PG8_STAGE(bufoff, gbase, voff) do { if constexpr (!pg8_noload<Epi>::value) { _Pragma("unroll") for (int _i = 0; _i < 2; ++_i) \
;         __builtin_amdgcn_global_load_lds((const unsigned*)((const char*)(gbase) + (size_t)_i * pstep + (voff)[0]), (PG8_LAS unsigned*)(lds + (bufoff) + ldsw + _i * 8192), 16, 0, 0); } } while (0)
; #define PG8_LDA(dst, b, h) do { _Pragma("unroll") for (int m = 0; m < 4; ++m) _Pragma("unroll") for (int k = 0; k < 2; ++k) dst[m][k] = *(const PG8_LAS bf16x8*)(lds + PG8_SA(b, h) + aoff + m * 2048 + k * 1024); } while (0)
; #define PG8_LDB(dst, b, h) do { _Pragma("unroll") for (int n = 0; n < 2; ++n) _Pragma("unroll") for (int k = 0; k < 2; ++k) dst[n][k] = *(const PG8_LAS bf16x8*)(lds + PG8_SB(b, h) + boff + n * 2048 + k * 1024); } while (0)
; #define PG8_MMA(ai, bj, At, Bt) do { __builtin_amdgcn_s_setprio(1); _Pragma("unroll") for (int m = 0; m < 4; ++m) _Pragma("unroll") for (int n = 0; n < 2; ++n) _Pragma("unroll") for (int k = 0; k < 2; ++k) \
;         acc[ai][bj][m][n] = __builtin_amdgcn_mfma_f32_16x16x32_bf16(Bt[n][k], At[m][k], acc[ai][bj][m][n], 0, 0, 0); __builtin_amdgcn_s_setprio(0); } while (0)
; #define PG8_WAIT_V(n) asm volatile("s_waitcnt vmcnt(" #n ")" ::: "memory")
; #define PG8_WAIT_L(n) asm volatile("s_waitcnt lgkmcnt(" #n ")" ::: "memory")
; #define PG8_BAR __builtin_amdgcn_s_barrier()
; #define PG8_SCHED __builtin_amdgcn_sched_barrier(0)
; template <class Epi, class Sched, bool ALIGN_EPI = false, bool SP2 = false, bool ABLK = false>
; __device__ __forceinline__ void gemm_phase(PG8_LAS unsigned char* lds, const Gemm g, const Sched& S, const Epi& E) {
;     ...
;             PG8_WAIT_V(8); PG8_WAIT_L(0); PG8_BAR; PG8_MMA(1, 0, At, B0); PG8_MMA(1, 1, At, B1); PG8_BAR; PG8_SCHED;
;             PG8_LDB(B0, 1, 0); PG8_LDB(B1, 1, 1); PG8_SCHED; PG8_LDA(At, 1, 0); PG8_STAGE(PG8_SA(0, 1), a2 + hstep, voffA);
;             PG8_WAIT_V(8); PG8_WAIT_L(0); PG8_BAR; PG8_MMA(0, 0, At, B0); PG8_MMA(0, 1, At, B1); PG8_BAR; PG8_SCHED;
	s_setprio 1
	s_waitcnt lgkmcnt(0)
	v_mfma_f32_16x16x32_bf16 v[62:65], v[130:133], v[192:195], v[62:65]
	v_mfma_f32_16x16x32_bf16 v[58:61], v[156:159], v[192:195], v[58:61]
	v_mfma_f32_16x16x32_bf16 v[46:49], v[130:133], v[200:203], v[46:49]
	v_mfma_f32_16x16x32_bf16 v[42:45], v[156:159], v[200:203], v[42:45]
	v_mfma_f32_16x16x32_bf16 v[30:33], v[130:133], v[208:211], v[30:33]
	v_mfma_f32_16x16x32_bf16 v[26:29], v[156:159], v[208:211], v[26:29]
	v_mfma_f32_16x16x32_bf16 v[14:17], v[130:133], v[216:219], v[14:17]
	v_mfma_f32_16x16x32_bf16 v[10:13], v[156:159], v[216:219], v[10:13]
	v_mfma_f32_16x16x32_bf16 v[62:65], v[134:137], v[196:199], v[62:65]
	v_mfma_f32_16x16x32_bf16 v[58:61], v[160:163], v[196:199], v[58:61]
	v_mfma_f32_16x16x32_bf16 v[46:49], v[134:137], v[204:207], v[46:49]
	v_mfma_f32_16x16x32_bf16 v[42:45], v[160:163], v[204:207], v[42:45]
	v_mfma_f32_16x16x32_bf16 v[30:33], v[134:137], v[212:215], v[30:33]
	v_mfma_f32_16x16x32_bf16 v[26:29], v[160:163], v[212:215], v[26:29]
	v_mfma_f32_16x16x32_bf16 v[14:17], v[134:137], v[220:223], v[14:17]
	v_mfma_f32_16x16x32_bf16 v[10:13], v[160:163], v[220:223], v[10:13]
	v_mfma_f32_16x16x32_bf16 v[54:57], v[164:167], v[192:195], v[54:57]
	v_mfma_f32_16x16x32_bf16 v[50:53], v[184:187], v[192:195], v[50:53]
	v_mfma_f32_16x16x32_bf16 v[38:41], v[164:167], v[200:203], v[38:41]
	v_mfma_f32_16x16x32_bf16 v[34:37], v[184:187], v[200:203], v[34:37]
	v_mfma_f32_16x16x32_bf16 v[22:25], v[164:167], v[208:211], v[22:25]
	v_mfma_f32_16x16x32_bf16 v[18:21], v[184:187], v[208:211], v[18:21]
	v_mfma_f32_16x16x32_bf16 v[6:9], v[164:167], v[216:219], v[6:9]
	v_mfma_f32_16x16x32_bf16 v[2:5], v[184:187], v[216:219], v[2:5]
	v_mfma_f32_16x16x32_bf16 v[54:57], v[176:179], v[196:199], v[54:57]
	v_mfma_f32_16x16x32_bf16 v[50:53], v[188:191], v[196:199], v[50:53]
	v_mfma_f32_16x16x32_bf16 v[38:41], v[176:179], v[204:207], v[38:41]
	v_mfma_f32_16x16x32_bf16 v[34:37], v[188:191], v[204:207], v[34:37]
	v_mfma_f32_16x16x32_bf16 v[22:25], v[176:179], v[212:215], v[22:25]
	v_mfma_f32_16x16x32_bf16 v[18:21], v[188:191], v[212:215], v[18:21]
	s_barrier
	s_setprio 2
	v_mfma_f32_16x16x32_bf16 v[6:9], v[176:179], v[220:223], v[6:9]
	v_mfma_f32_16x16x32_bf16 v[2:5], v[188:191], v[220:223], v[2:5]
	s_setprio 0
	s_add_i32 s58, 0, 0x18000
	s_add_i32 s59, 0, 0x1c000
	v_add_u32_e32 v160, s58, v168
	v_add_u32_e32 v188, s59, v168
	ds_read_b128 v[130:133], v160
	ds_read_b128 v[134:137], v160 offset:1024
	ds_read_b128 v[156:159], v160 offset:2048
	ds_read_b128 v[160:163], v160 offset:3072
	ds_read_b128 v[164:167], v188
	ds_read_b128 v[176:179], v188 offset:1024
	ds_read_b128 v[184:187], v188 offset:2048
	ds_read_b128 v[188:191], v188 offset:3072
	s_mov_b32 m0, s34
	v_lshl_add_u64 v[226:227], v[224:225], 0, s[24:25]
	ds_read_b128 v[192:195], v173 offset:32768
	ds_read_b128 v[196:199], v173 offset:33792
	ds_read_b128 v[200:203], v173 offset:34816
	ds_read_b128 v[204:207], v173 offset:35840
	ds_read_b128 v[208:211], v173 offset:36864
	ds_read_b128 v[212:215], v173 offset:37888
	ds_read_b128 v[216:219], v173 offset:38912
	ds_read_b128 v[220:223], v173 offset:39936
	global_load_lds_dwordx4 v[226:227], off
	v_lshl_add_u64 v[226:227], v[224:225], 0, s[26:27]
	s_mov_b32 m0, s35
	s_nop 0
	global_load_lds_dwordx4 v[226:227], off
	s_waitcnt vmcnt(8)
	s_waitcnt lgkmcnt(0)
	s_barrier
	s_setprio 1
	s_waitcnt lgkmcnt(0)
	v_mfma_f32_16x16x32_bf16 v[126:129], v[130:133], v[192:195], v[126:129]
	v_mfma_f32_16x16x32_bf16 v[122:125], v[156:159], v[192:195], v[122:125]
	v_mfma_f32_16x16x32_bf16 v[110:113], v[130:133], v[200:203], v[110:113]
	v_mfma_f32_16x16x32_bf16 v[106:109], v[156:159], v[200:203], v[106:109]
	v_mfma_f32_16x16x32_bf16 v[94:97], v[130:133], v[208:211], v[94:97]
	v_mfma_f32_16x16x32_bf16 v[90:93], v[156:159], v[208:211], v[90:93]
	v_mfma_f32_16x16x32_bf16 v[78:81], v[130:133], v[216:219], v[78:81]
	v_mfma_f32_16x16x32_bf16 v[74:77], v[156:159], v[216:219], v[74:77]
	v_mfma_f32_16x16x32_bf16 v[126:129], v[134:137], v[196:199], v[126:129]
	v_mfma_f32_16x16x32_bf16 v[122:125], v[160:163], v[196:199], v[122:125]
	v_mfma_f32_16x16x32_bf16 v[110:113], v[134:137], v[204:207], v[110:113]
	v_mfma_f32_16x16x32_bf16 v[106:109], v[160:163], v[204:207], v[106:109]
	v_mfma_f32_16x16x32_bf16 v[94:97], v[134:137], v[212:215], v[94:97]
	v_mfma_f32_16x16x32_bf16 v[90:93], v[160:163], v[212:215], v[90:93]
	v_mfma_f32_16x16x32_bf16 v[78:81], v[134:137], v[220:223], v[78:81]
	v_mfma_f32_16x16x32_bf16 v[74:77], v[160:163], v[220:223], v[74:77]
	v_mfma_f32_16x16x32_bf16 v[118:121], v[164:167], v[192:195], v[118:121]
	v_mfma_f32_16x16x32_bf16 v[114:117], v[184:187], v[192:195], v[114:117]
	v_mfma_f32_16x16x32_bf16 v[102:105], v[164:167], v[200:203], v[102:105]
	v_mfma_f32_16x16x32_bf16 v[98:101], v[184:187], v[200:203], v[98:101]
	v_mfma_f32_16x16x32_bf16 v[86:89], v[164:167], v[208:211], v[86:89]
	v_mfma_f32_16x16x32_bf16 v[82:85], v[184:187], v[208:211], v[82:85]
	v_mfma_f32_16x16x32_bf16 v[70:73], v[164:167], v[216:219], v[70:73]
	v_mfma_f32_16x16x32_bf16 v[66:69], v[184:187], v[216:219], v[66:69]
	v_mfma_f32_16x16x32_bf16 v[118:121], v[176:179], v[196:199], v[118:121]
	v_mfma_f32_16x16x32_bf16 v[114:117], v[188:191], v[196:199], v[114:117]
	s_barrier
; #define PG8_STAGE(bufoff, gbase, voff) do { if constexpr (!pg8_noload<Epi>::value) { _Pragma("unroll") for (int _i = 0; _i < 2; ++_i) \
;         __builtin_amdgcn_global_load_lds((const unsigned*)((const char*)(gbase) + (size_t)_i * pstep + (voff)[0]), (PG8_LAS unsigned*)(lds + (bufoff) + ldsw + _i * 8192), 16, 0, 0); } } while (0)
; #define PG8_LDA(dst, b, h) do { _Pragma("unroll") for (int m = 0; m < 4; ++m) _Pragma("unroll") for (int k = 0; k < 2; ++k) dst[m][k] = *(const PG8_LAS bf16x8*)(lds + PG8_SA(b, h) + aoff + m * 2048 + k * 1024); } while (0)
; #define PG8_MMA(ai, bj, At, Bt) do { __builtin_amdgcn_s_setprio(1); _Pragma("unroll") for (int m = 0; m < 4; ++m) _Pragma("unroll") for (int n = 0; n < 2; ++n) _Pragma("unroll") for (int k = 0; k < 2; ++k) \
;         acc[ai][bj][m][n] = __builtin_amdgcn_mfma_f32_16x16x32_bf16(Bt[n][k], At[m][k], acc[ai][bj][m][n], 0, 0, 0); __builtin_amdgcn_s_setprio(0); } while (0)
; #define PG8_WAIT_V(n) asm volatile("s_waitcnt vmcnt(" #n ")" ::: "memory")
; #define PG8_WAIT_L(n) asm volatile("s_waitcnt lgkmcnt(" #n ")" ::: "memory")
; #define PG8_BAR __builtin_amdgcn_s_barrier()
; #define PG8_SCHED __builtin_amdgcn_sched_barrier(0)
; template <class Epi, class Sched, bool ALIGN_EPI = false, bool SP2 = false, bool ABLK = false>
; __device__ __forceinline__ void gemm_phase(PG8_LAS unsigned char* lds, const Gemm g, const Sched& S, const Epi& E) {
;     ...
;             PG8_WAIT_V(8); PG8_WAIT_L(0); PG8_BAR; PG8_MMA(0, 0, At, B0); PG8_MMA(0, 1, At, B1); PG8_BAR; PG8_SCHED;
;             PG8_LDA(At, 1, 1); PG8_STAGE(PG8_SB(1, 0), b3, voffB); PG8_STAGE(PG8_SB(1, 1), b3 + hstep, voffB); PG8_STAGE(PG8_SA(1, 0), a3, voffA);
;             PG8_WAIT_V(8); PG8_WAIT_L(0); PG8_BAR; PG8_MMA(1, 0, At, B0); PG8_MMA(1, 1, At, B1); PG8_BAR; PG8_SCHED;
	s_setprio 2
	v_mfma_f32_16x16x32_bf16 v[102:105], v[176:179], v[204:207], v[102:105]
	v_mfma_f32_16x16x32_bf16 v[98:101], v[188:191], v[204:207], v[98:101]
	v_mfma_f32_16x16x32_bf16 v[86:89], v[176:179], v[212:215], v[86:89]
	v_mfma_f32_16x16x32_bf16 v[82:85], v[188:191], v[212:215], v[82:85]
	v_mfma_f32_16x16x32_bf16 v[70:73], v[176:179], v[220:223], v[70:73]
	v_mfma_f32_16x16x32_bf16 v[66:69], v[188:191], v[220:223], v[66:69]
	s_setprio 0
	s_add_i32 s58, s58, s91
	v_lshl_add_u64 v[226:227], v[180:181], 0, s[92:93]
	s_mov_b32 m0, s58
	ds_read_b128 v[192:195], v173 offset:49152
	ds_read_b128 v[196:199], v173 offset:50176
	ds_read_b128 v[200:203], v173 offset:51200
	ds_read_b128 v[204:207], v173 offset:52224
	ds_read_b128 v[208:211], v173 offset:53248
	ds_read_b128 v[212:215], v173 offset:54272
	ds_read_b128 v[216:219], v173 offset:55296
	ds_read_b128 v[220:223], v173 offset:56320
	global_load_lds_dwordx4 v[226:227], off
	v_lshl_add_u64 v[226:227], v[180:181], 0, s[94:95]
	s_add_i32 m0, s58, 0x2000
	s_add_i32 s58, s59, s91
	global_load_lds_dwordx4 v[226:227], off
	v_lshl_add_u64 v[226:227], v[180:181], 0, s[96:97]
	s_mov_b32 m0, s58
	v_lshl_add_u64 v[180:181], v[180:181], 0, s[88:89]
	global_load_lds_dwordx4 v[226:227], off
	s_add_i32 m0, s58, 0x2000
	s_nop 0
	global_load_lds_dwordx4 v[180:181], off
	v_lshl_add_u64 v[180:181], v[224:225], 0, s[92:93]
	s_mov_b32 m0, s10
	s_nop 0
	global_load_lds_dwordx4 v[180:181], off
	v_lshl_add_u64 v[180:181], v[224:225], 0, s[94:95]
	s_mov_b32 m0, s11
	s_nop 0
	global_load_lds_dwordx4 v[180:181], off
	s_waitcnt vmcnt(8)
	s_waitcnt lgkmcnt(0)
	s_barrier
	s_setprio 1
	s_waitcnt lgkmcnt(0)
	v_mfma_f32_16x16x32_bf16 v[62:65], v[130:133], v[192:195], v[62:65]
	v_mfma_f32_16x16x32_bf16 v[58:61], v[156:159], v[192:195], v[58:61]
	v_mfma_f32_16x16x32_bf16 v[46:49], v[130:133], v[200:203], v[46:49]
	v_mfma_f32_16x16x32_bf16 v[42:45], v[156:159], v[200:203], v[42:45]
	v_mfma_f32_16x16x32_bf16 v[30:33], v[130:133], v[208:211], v[30:33]
	v_mfma_f32_16x16x32_bf16 v[26:29], v[156:159], v[208:211], v[26:29]
	v_mfma_f32_16x16x32_bf16 v[14:17], v[130:133], v[216:219], v[14:17]
	v_mfma_f32_16x16x32_bf16 v[10:13], v[156:159], v[216:219], v[10:13]
	v_mfma_f32_16x16x32_bf16 v[62:65], v[134:137], v[196:199], v[62:65]
	v_mfma_f32_16x16x32_bf16 v[58:61], v[160:163], v[196:199], v[58:61]
	v_mfma_f32_16x16x32_bf16 v[46:49], v[134:137], v[204:207], v[46:49]
	v_mfma_f32_16x16x32_bf16 v[42:45], v[160:163], v[204:207], v[42:45]
	v_mfma_f32_16x16x32_bf16 v[30:33], v[134:137], v[212:215], v[30:33]
	v_mfma_f32_16x16x32_bf16 v[26:29], v[160:163], v[212:215], v[26:29]
	v_mfma_f32_16x16x32_bf16 v[14:17], v[134:137], v[220:223], v[14:17]
	v_mfma_f32_16x16x32_bf16 v[10:13], v[160:163], v[220:223], v[10:13]
	v_mfma_f32_16x16x32_bf16 v[54:57], v[164:167], v[192:195], v[54:57]
	v_mfma_f32_16x16x32_bf16 v[50:53], v[184:187], v[192:195], v[50:53]
	v_mfma_f32_16x16x32_bf16 v[38:41], v[164:167], v[200:203], v[38:41]
	v_mfma_f32_16x16x32_bf16 v[34:37], v[184:187], v[200:203], v[34:37]
	v_mfma_f32_16x16x32_bf16 v[22:25], v[164:167], v[208:211], v[22:25]
	v_mfma_f32_16x16x32_bf16 v[18:21], v[184:187], v[208:211], v[18:21]
	v_mfma_f32_16x16x32_bf16 v[6:9], v[164:167], v[216:219], v[6:9]
	v_mfma_f32_16x16x32_bf16 v[2:5], v[184:187], v[216:219], v[2:5]
	v_mfma_f32_16x16x32_bf16 v[54:57], v[176:179], v[196:199], v[54:57]
	v_mfma_f32_16x16x32_bf16 v[50:53], v[188:191], v[196:199], v[50:53]
	v_mfma_f32_16x16x32_bf16 v[38:41], v[176:179], v[204:207], v[38:41]
	v_mfma_f32_16x16x32_bf16 v[34:37], v[188:191], v[204:207], v[34:37]
	v_mfma_f32_16x16x32_bf16 v[22:25], v[176:179], v[212:215], v[22:25]
	v_mfma_f32_16x16x32_bf16 v[18:21], v[188:191], v[212:215], v[18:21]
	s_barrier
	s_setprio 2
	v_mfma_f32_16x16x32_bf16 v[6:9], v[176:179], v[220:223], v[6:9]
	v_mfma_f32_16x16x32_bf16 v[2:5], v[188:191], v[220:223], v[2:5]
	s_setprio 0
	s_cmp_gt_u32 s57, 29
	s_mov_b32 s57, s28
	s_cbranch_scc1 .LBB0_631

; #define PG8_STAGE(bufoff, gbase, voff) do { if constexpr (!pg8_noload<Epi>::value) { _Pragma("unroll") for (int _i = 0; _i < 2; ++_i) \
;         __builtin_amdgcn_global_load_lds((const unsigned*)((const char*)(gbase) + (size_t)_i * pstep + (voff)[0]), (PG8_LAS unsigned*)(lds + (bufoff) + ldsw + _i * 8192), 16, 0, 0); } } while (0)
; #define PG8_LDA(dst, b, h) do { _Pragma("unroll") for (int m = 0; m < 4; ++m) _Pragma("unroll") for (int k = 0; k < 2; ++k) dst[m][k] = *(const PG8_LAS bf16x8*)(lds + PG8_SA(b, h) + aoff + m * 2048 + k * 1024); } while (0)
; #define PG8_LDB(dst, b, h) do { _Pragma("unroll") for (int n = 0; n < 2; ++n) _Pragma("unroll") for (int k = 0; k < 2; ++k) dst[n][k] = *(const PG8_LAS bf16x8*)(lds + PG8_SB(b, h) + boff + n * 2048 + k * 1024); } while (0)
; #define PG8_MMA(ai, bj, At, Bt) do { __builtin_amdgcn_s_setprio(1); _Pragma("unroll") for (int m = 0; m < 4; ++m) _Pragma("unroll") for (int n = 0; n < 2; ++n) _Pragma("unroll") for (int k = 0; k < 2; ++k) \
;         acc[ai][bj][m][n] = __builtin_amdgcn_mfma_f32_16x16x32_bf16(Bt[n][k], At[m][k], acc[ai][bj][m][n], 0, 0, 0); __builtin_amdgcn_s_setprio(0); } while (0)
; #define PG8_WAIT_V(n) asm volatile("s_waitcnt vmcnt(" #n ")" ::: "memory")
; #define PG8_WAIT_L(n) asm volatile("s_waitcnt lgkmcnt(" #n ")" ::: "memory")
; #define PG8_BAR __builtin_amdgcn_s_barrier()
; #define PG8_SCHED __builtin_amdgcn_sched_barrier(0)
; template <class Epi, class Sched, bool ALIGN_EPI = false, bool SP2 = false, bool ABLK = false>
; __device__ __forceinline__ void gemm_phase(PG8_LAS unsigned char* lds, const Gemm g, const Sched& S, const Epi& E) {
;     ...
;             PG8_LDB(B0, 0, 0); PG8_LDB(B1, 0, 1); PG8_SCHED; PG8_LDA(At, 0, 0); PG8_STAGE(PG8_SA(1, 1), a1 + hstep, voffA);
;             PG8_WAIT_V(8); PG8_WAIT_L(0); PG8_BAR; PG8_MMA(0, 0, At, B0); PG8_MMA(0, 1, At, B1); PG8_BAR; PG8_SCHED;
;             PG8_LDA(At, 0, 1); PG8_STAGE(PG8_SB(0, 0), b2, voffB); PG8_STAGE(PG8_SB(0, 1), b2 + hstep, voffB); PG8_STAGE(PG8_SA(0, 0), a2, voffA);
;             PG8_WAIT_V(8); PG8_WAIT_L(0); PG8_BAR; PG8_MMA(1, 0, At, B0); PG8_MMA(1, 1, At, B1); PG8_BAR; PG8_SCHED;
.LBB0_1533:
	ds_read_b128 v[114:117], v167
	ds_read_b128 v[126:129], v167 offset:1024
	ds_read_b128 v[130:133], v167 offset:2048
	ds_read_b128 v[142:145], v167 offset:3072
	ds_read_b128 v[146:149], v168
	ds_read_b128 v[150:153], v168 offset:1024
	ds_read_b128 v[174:177], v168 offset:2048
	ds_read_b128 v[178:181], v168 offset:3072
	s_add_i32 s41, s39, 2
	s_add_u32 s70, s68, 0xfff00800
	s_addc_u32 s71, s69, -1
	s_cmp_eq_u32 s3, s39
	s_cselect_b32 s71, s43, s71
	s_cselect_b32 s70, s42, s70
	s_cselect_b32 s81, s65, s37
	s_cselect_b32 s80, s64, s11
	v_lshl_add_u64 v[162:163], s[68:69], 0, v[158:159]
	s_add_i32 m0, s56, 0xc000
	ds_read_b128 v[184:187], v169
	ds_read_b128 v[188:191], v169 offset:1024
	ds_read_b128 v[192:195], v169 offset:2048
	ds_read_b128 v[196:199], v169 offset:3072
	ds_read_b128 v[200:203], v169 offset:4096
	ds_read_b128 v[204:207], v169 offset:5120
	ds_read_b128 v[208:211], v169 offset:6144
	ds_read_b128 v[212:215], v169 offset:7168
	global_load_lds_dwordx4 v[162:163], off
	v_lshl_add_u64 v[162:163], v[162:163], 0, s[12:13]
	s_add_i32 m0, s56, 0xe000
	s_nop 0
	global_load_lds_dwordx4 v[162:163], off
	s_waitcnt vmcnt(8)
	s_waitcnt lgkmcnt(0)
	s_barrier
	s_setprio 1
	s_waitcnt lgkmcnt(0)
	v_mfma_f32_16x16x32_bf16 v[138:141], v[114:117], v[184:187], v[138:141]
	v_mfma_f32_16x16x32_bf16 v[134:137], v[130:133], v[184:187], v[134:137]
	v_mfma_f32_16x16x32_bf16 v[110:113], v[114:117], v[192:195], v[110:113]
	v_mfma_f32_16x16x32_bf16 v[106:109], v[130:133], v[192:195], v[106:109]
	v_mfma_f32_16x16x32_bf16 v[94:97], v[114:117], v[200:203], v[94:97]
	v_mfma_f32_16x16x32_bf16 v[90:93], v[130:133], v[200:203], v[90:93]
	v_mfma_f32_16x16x32_bf16 v[78:81], v[114:117], v[208:211], v[78:81]
	v_mfma_f32_16x16x32_bf16 v[74:77], v[130:133], v[208:211], v[74:77]
	v_mfma_f32_16x16x32_bf16 v[138:141], v[126:129], v[188:191], v[138:141]
	v_mfma_f32_16x16x32_bf16 v[134:137], v[142:145], v[188:191], v[134:137]
	v_mfma_f32_16x16x32_bf16 v[110:113], v[126:129], v[196:199], v[110:113]
	v_mfma_f32_16x16x32_bf16 v[106:109], v[142:145], v[196:199], v[106:109]
	v_mfma_f32_16x16x32_bf16 v[94:97], v[126:129], v[204:207], v[94:97]
	v_mfma_f32_16x16x32_bf16 v[90:93], v[142:145], v[204:207], v[90:93]
	v_mfma_f32_16x16x32_bf16 v[78:81], v[126:129], v[212:215], v[78:81]
	v_mfma_f32_16x16x32_bf16 v[74:77], v[142:145], v[212:215], v[74:77]
	v_mfma_f32_16x16x32_bf16 v[122:125], v[146:149], v[184:187], v[122:125]
	v_mfma_f32_16x16x32_bf16 v[118:121], v[174:177], v[184:187], v[118:121]
	v_mfma_f32_16x16x32_bf16 v[102:105], v[146:149], v[192:195], v[102:105]
	v_mfma_f32_16x16x32_bf16 v[98:101], v[174:177], v[192:195], v[98:101]
	v_mfma_f32_16x16x32_bf16 v[86:89], v[146:149], v[200:203], v[86:89]
	v_mfma_f32_16x16x32_bf16 v[82:85], v[174:177], v[200:203], v[82:85]
	v_mfma_f32_16x16x32_bf16 v[70:73], v[146:149], v[208:211], v[70:73]
	v_mfma_f32_16x16x32_bf16 v[66:69], v[174:177], v[208:211], v[66:69]
	v_mfma_f32_16x16x32_bf16 v[122:125], v[150:153], v[188:191], v[122:125]
	v_mfma_f32_16x16x32_bf16 v[118:121], v[178:181], v[188:191], v[118:121]
	s_barrier
	s_setprio 2
	v_mfma_f32_16x16x32_bf16 v[102:105], v[150:153], v[196:199], v[102:105]
	v_mfma_f32_16x16x32_bf16 v[98:101], v[178:181], v[196:199], v[98:101]
	v_mfma_f32_16x16x32_bf16 v[86:89], v[150:153], v[204:207], v[86:89]
	v_mfma_f32_16x16x32_bf16 v[82:85], v[178:181], v[204:207], v[82:85]
	v_mfma_f32_16x16x32_bf16 v[70:73], v[150:153], v[212:215], v[70:73]
	v_mfma_f32_16x16x32_bf16 v[66:69], v[178:181], v[212:215], v[66:69]
	s_setprio 0
	s_add_i32 s39, s74, s55
	v_lshl_add_u64 v[162:163], s[80:81], 0, v[154:155]
	s_mov_b32 m0, s39
	ds_read_b128 v[184:187], v169 offset:16384
	ds_read_b128 v[188:191], v169 offset:17408
	ds_read_b128 v[192:195], v169 offset:18432
	ds_read_b128 v[196:199], v169 offset:19456
	ds_read_b128 v[200:203], v169 offset:20480
	ds_read_b128 v[204:207], v169 offset:21504
	ds_read_b128 v[208:211], v169 offset:22528
	ds_read_b128 v[212:215], v169 offset:23552
	global_load_lds_dwordx4 v[162:163], off
	v_lshl_add_u64 v[216:217], v[162:163], 0, s[12:13]
	s_add_i32 m0, s39, 0x2000
	s_add_i32 s39, s75, s55
	global_load_lds_dwordx4 v[216:217], off
	v_lshl_add_u64 v[216:217], v[162:163], 0, s[14:15]
	s_mov_b32 m0, s39
	s_nop 0
	global_load_lds_dwordx4 v[216:217], off
	v_lshl_add_u64 v[216:217], v[162:163], 0, s[16:17]
	s_add_i32 m0, s39, 0x2000
	s_nop 0
	global_load_lds_dwordx4 v[216:217], off
	v_lshl_add_u64 v[216:217], s[70:71], 0, v[154:155]
	s_mov_b32 m0, s56
	v_lshl_add_u64 v[218:219], v[216:217], 0, s[12:13]
	global_load_lds_dwordx4 v[216:217], off
	s_mov_b32 m0, s57
	s_nop 0
	global_load_lds_dwordx4 v[218:219], off
	s_waitcnt vmcnt(8)
	s_waitcnt lgkmcnt(0)
	s_barrier
; #define PG8_STAGE(bufoff, gbase, voff) do { if constexpr (!pg8_noload<Epi>::value) { _Pragma("unroll") for (int _i = 0; _i < 2; ++_i) \
;         __builtin_amdgcn_global_load_lds((const unsigned*)((const char*)(gbase) + (size_t)_i * pstep + (voff)[0]), (PG8_LAS unsigned*)(lds + (bufoff) + ldsw + _i * 8192), 16, 0, 0); } } while (0)
; #define PG8_LDA(dst, b, h) do { _Pragma("unroll") for (int m = 0; m < 4; ++m) _Pragma("unroll") for (int k = 0; k < 2; ++k) dst[m][k] = *(const PG8_LAS bf16x8*)(lds + PG8_SA(b, h) + aoff + m * 2048 + k * 1024); } while (0)
; #define PG8_LDB(dst, b, h) do { _Pragma("unroll") for (int n = 0; n < 2; ++n) _Pragma("unroll") for (int k = 0; k < 2; ++k) dst[n][k] = *(const PG8_LAS bf16x8*)(lds + PG8_SB(b, h) + boff + n * 2048 + k * 1024); } while (0)
; #define PG8_MMA(ai, bj, At, Bt) do { __builtin_amdgcn_s_setprio(1); _Pragma("unroll") for (int m = 0; m < 4; ++m) _Pragma("unroll") for (int n = 0; n < 2; ++n) _Pragma("unroll") for (int k = 0; k < 2; ++k) \
;         acc[ai][bj][m][n] = __builtin_amdgcn_mfma_f32_16x16x32_bf16(Bt[n][k], At[m][k], acc[ai][bj][m][n], 0, 0, 0); __builtin_amdgcn_s_setprio(0); } while (0)
; #define PG8_WAIT_V(n) asm volatile("s_waitcnt vmcnt(" #n ")" ::: "memory")
; #define PG8_WAIT_L(n) asm volatile("s_waitcnt lgkmcnt(" #n ")" ::: "memory")
; #define PG8_BAR __builtin_amdgcn_s_barrier()
; #define PG8_SCHED __builtin_amdgcn_sched_barrier(0)
; template <class Epi, class Sched, bool ALIGN_EPI = false, bool SP2 = false, bool ABLK = false>
; __device__ __forceinline__ void gemm_phase(PG8_LAS unsigned char* lds, const Gemm g, const Sched& S, const Epi& E) {
;     ...
;             PG8_WAIT_V(8); PG8_WAIT_L(0); PG8_BAR; PG8_MMA(1, 0, At, B0); PG8_MMA(1, 1, At, B1); PG8_BAR; PG8_SCHED;
;             PG8_LDB(B0, 1, 0); PG8_LDB(B1, 1, 1); PG8_SCHED; PG8_LDA(At, 1, 0); PG8_STAGE(PG8_SA(0, 1), a2 + hstep, voffA);
;             PG8_WAIT_V(8); PG8_WAIT_L(0); PG8_BAR; PG8_MMA(0, 0, At, B0); PG8_MMA(0, 1, At, B1); PG8_BAR; PG8_SCHED;
	s_setprio 1
	s_waitcnt lgkmcnt(0)
	v_mfma_f32_16x16x32_bf16 v[62:65], v[114:117], v[184:187], v[62:65]
	v_mfma_f32_16x16x32_bf16 v[58:61], v[130:133], v[184:187], v[58:61]
	v_mfma_f32_16x16x32_bf16 v[46:49], v[114:117], v[192:195], v[46:49]
	v_mfma_f32_16x16x32_bf16 v[42:45], v[130:133], v[192:195], v[42:45]
	v_mfma_f32_16x16x32_bf16 v[30:33], v[114:117], v[200:203], v[30:33]
	v_mfma_f32_16x16x32_bf16 v[26:29], v[130:133], v[200:203], v[26:29]
	v_mfma_f32_16x16x32_bf16 v[14:17], v[114:117], v[208:211], v[14:17]
	v_mfma_f32_16x16x32_bf16 v[10:13], v[130:133], v[208:211], v[10:13]
	v_mfma_f32_16x16x32_bf16 v[62:65], v[126:129], v[188:191], v[62:65]
	v_mfma_f32_16x16x32_bf16 v[58:61], v[142:145], v[188:191], v[58:61]
	v_mfma_f32_16x16x32_bf16 v[46:49], v[126:129], v[196:199], v[46:49]
	v_mfma_f32_16x16x32_bf16 v[42:45], v[142:145], v[196:199], v[42:45]
	v_mfma_f32_16x16x32_bf16 v[30:33], v[126:129], v[204:207], v[30:33]
	v_mfma_f32_16x16x32_bf16 v[26:29], v[142:145], v[204:207], v[26:29]
	v_mfma_f32_16x16x32_bf16 v[14:17], v[126:129], v[212:215], v[14:17]
	v_mfma_f32_16x16x32_bf16 v[10:13], v[142:145], v[212:215], v[10:13]
	v_mfma_f32_16x16x32_bf16 v[54:57], v[146:149], v[184:187], v[54:57]
	v_mfma_f32_16x16x32_bf16 v[50:53], v[174:177], v[184:187], v[50:53]
	v_mfma_f32_16x16x32_bf16 v[38:41], v[146:149], v[192:195], v[38:41]
	v_mfma_f32_16x16x32_bf16 v[34:37], v[174:177], v[192:195], v[34:37]
	v_mfma_f32_16x16x32_bf16 v[22:25], v[146:149], v[200:203], v[22:25]
	v_mfma_f32_16x16x32_bf16 v[18:21], v[174:177], v[200:203], v[18:21]
	v_mfma_f32_16x16x32_bf16 v[6:9], v[146:149], v[208:211], v[6:9]
	v_mfma_f32_16x16x32_bf16 v[2:5], v[174:177], v[208:211], v[2:5]
	v_mfma_f32_16x16x32_bf16 v[54:57], v[150:153], v[188:191], v[54:57]
	v_mfma_f32_16x16x32_bf16 v[50:53], v[178:181], v[188:191], v[50:53]
	v_mfma_f32_16x16x32_bf16 v[38:41], v[150:153], v[196:199], v[38:41]
	v_mfma_f32_16x16x32_bf16 v[34:37], v[178:181], v[196:199], v[34:37]
	v_mfma_f32_16x16x32_bf16 v[22:25], v[150:153], v[204:207], v[22:25]
	v_mfma_f32_16x16x32_bf16 v[18:21], v[178:181], v[204:207], v[18:21]
	s_barrier
	s_setprio 2
	v_mfma_f32_16x16x32_bf16 v[6:9], v[150:153], v[212:215], v[6:9]
	v_mfma_f32_16x16x32_bf16 v[2:5], v[178:181], v[212:215], v[2:5]
	s_setprio 0
	s_add_i32 s39, 0, 0x18000
	s_add_i32 s70, 0, 0x1c000
	v_add_u32_e32 v142, s39, v1
	v_add_u32_e32 v173, s70, v1
	ds_read_b128 v[114:117], v142
	ds_read_b128 v[126:129], v142 offset:1024
	ds_read_b128 v[130:133], v142 offset:2048
	ds_read_b128 v[142:145], v142 offset:3072
	ds_read_b128 v[146:149], v173
	ds_read_b128 v[150:153], v173 offset:1024
	ds_read_b128 v[174:177], v173 offset:2048
	ds_read_b128 v[178:181], v173 offset:3072
	s_mov_b32 m0, s58
	v_lshl_add_u64 v[218:219], v[216:217], 0, s[14:15]
	ds_read_b128 v[184:187], v169 offset:32768
	ds_read_b128 v[188:191], v169 offset:33792
	ds_read_b128 v[192:195], v169 offset:34816
	ds_read_b128 v[196:199], v169 offset:35840
	ds_read_b128 v[200:203], v169 offset:36864
	ds_read_b128 v[204:207], v169 offset:37888
	ds_read_b128 v[208:211], v169 offset:38912
	ds_read_b128 v[212:215], v169 offset:39936
	global_load_lds_dwordx4 v[218:219], off
	v_lshl_add_u64 v[218:219], v[216:217], 0, s[16:17]
	s_mov_b32 m0, s59
	s_nop 0
	global_load_lds_dwordx4 v[218:219], off
	s_waitcnt vmcnt(8)
	s_waitcnt lgkmcnt(0)
	s_barrier
	s_setprio 1
	s_waitcnt lgkmcnt(0)
	v_mfma_f32_16x16x32_bf16 v[138:141], v[114:117], v[184:187], v[138:141]
	v_mfma_f32_16x16x32_bf16 v[134:137], v[130:133], v[184:187], v[134:137]
	v_mfma_f32_16x16x32_bf16 v[110:113], v[114:117], v[192:195], v[110:113]
	v_mfma_f32_16x16x32_bf16 v[106:109], v[130:133], v[192:195], v[106:109]
	v_mfma_f32_16x16x32_bf16 v[94:97], v[114:117], v[200:203], v[94:97]
	v_mfma_f32_16x16x32_bf16 v[90:93], v[130:133], v[200:203], v[90:93]
	v_mfma_f32_16x16x32_bf16 v[78:81], v[114:117], v[208:211], v[78:81]
	v_mfma_f32_16x16x32_bf16 v[74:77], v[130:133], v[208:211], v[74:77]
	v_mfma_f32_16x16x32_bf16 v[138:141], v[126:129], v[188:191], v[138:141]
	v_mfma_f32_16x16x32_bf16 v[134:137], v[142:145], v[188:191], v[134:137]
	v_mfma_f32_16x16x32_bf16 v[110:113], v[126:129], v[196:199], v[110:113]
	v_mfma_f32_16x16x32_bf16 v[106:109], v[142:145], v[196:199], v[106:109]
	v_mfma_f32_16x16x32_bf16 v[94:97], v[126:129], v[204:207], v[94:97]
	v_mfma_f32_16x16x32_bf16 v[90:93], v[142:145], v[204:207], v[90:93]
	v_mfma_f32_16x16x32_bf16 v[78:81], v[126:129], v[212:215], v[78:81]
	v_mfma_f32_16x16x32_bf16 v[74:77], v[142:145], v[212:215], v[74:77]
	v_mfma_f32_16x16x32_bf16 v[122:125], v[146:149], v[184:187], v[122:125]
	v_mfma_f32_16x16x32_bf16 v[118:121], v[174:177], v[184:187], v[118:121]
	v_mfma_f32_16x16x32_bf16 v[102:105], v[146:149], v[192:195], v[102:105]
	v_mfma_f32_16x16x32_bf16 v[98:101], v[174:177], v[192:195], v[98:101]
	v_mfma_f32_16x16x32_bf16 v[86:89], v[146:149], v[200:203], v[86:89]
	v_mfma_f32_16x16x32_bf16 v[82:85], v[174:177], v[200:203], v[82:85]
	v_mfma_f32_16x16x32_bf16 v[70:73], v[146:149], v[208:211], v[70:73]
	v_mfma_f32_16x16x32_bf16 v[66:69], v[174:177], v[208:211], v[66:69]
	v_mfma_f32_16x16x32_bf16 v[122:125], v[150:153], v[188:191], v[122:125]
	v_mfma_f32_16x16x32_bf16 v[118:121], v[178:181], v[188:191], v[118:121]
	s_barrier
; #define PG8_STAGE(bufoff, gbase, voff) do { if constexpr (!pg8_noload<Epi>::value) { _Pragma("unroll") for (int _i = 0; _i < 2; ++_i) \
;         __builtin_amdgcn_global_load_lds((const unsigned*)((const char*)(gbase) + (size_t)_i * pstep + (voff)[0]), (PG8_LAS unsigned*)(lds + (bufoff) + ldsw + _i * 8192), 16, 0, 0); } } while (0)
; #define PG8_LDA(dst, b, h) do { _Pragma("unroll") for (int m = 0; m < 4; ++m) _Pragma("unroll") for (int k = 0; k < 2; ++k) dst[m][k] = *(const PG8_LAS bf16x8*)(lds + PG8_SA(b, h) + aoff + m * 2048 + k * 1024); } while (0)
; #define PG8_MMA(ai, bj, At, Bt) do { __builtin_amdgcn_s_setprio(1); _Pragma("unroll") for (int m = 0; m < 4; ++m) _Pragma("unroll") for (int n = 0; n < 2; ++n) _Pragma("unroll") for (int k = 0; k < 2; ++k) \
;         acc[ai][bj][m][n] = __builtin_amdgcn_mfma_f32_16x16x32_bf16(Bt[n][k], At[m][k], acc[ai][bj][m][n], 0, 0, 0); __builtin_amdgcn_s_setprio(0); } while (0)
; #define PG8_WAIT_V(n) asm volatile("s_waitcnt vmcnt(" #n ")" ::: "memory")
; #define PG8_WAIT_L(n) asm volatile("s_waitcnt lgkmcnt(" #n ")" ::: "memory")
; #define PG8_BAR __builtin_amdgcn_s_barrier()
; #define PG8_SCHED __builtin_amdgcn_sched_barrier(0)
; template <class Epi, class Sched, bool ALIGN_EPI = false, bool SP2 = false, bool ABLK = false>
; __device__ __forceinline__ void gemm_phase(PG8_LAS unsigned char* lds, const Gemm g, const Sched& S, const Epi& E) {
;     ...
;             PG8_WAIT_V(8); PG8_WAIT_L(0); PG8_BAR; PG8_MMA(0, 0, At, B0); PG8_MMA(0, 1, At, B1); PG8_BAR; PG8_SCHED;
;             PG8_LDA(At, 1, 1); PG8_STAGE(PG8_SB(1, 0), b3, voffB); PG8_STAGE(PG8_SB(1, 1), b3 + hstep, voffB); PG8_STAGE(PG8_SA(1, 0), a3, voffA);
;             PG8_WAIT_V(8); PG8_WAIT_L(0); PG8_BAR; PG8_MMA(1, 0, At, B0); PG8_MMA(1, 1, At, B1); PG8_BAR; PG8_SCHED;
	s_setprio 2
	v_mfma_f32_16x16x32_bf16 v[102:105], v[150:153], v[196:199], v[102:105]
	v_mfma_f32_16x16x32_bf16 v[98:101], v[178:181], v[196:199], v[98:101]
	v_mfma_f32_16x16x32_bf16 v[86:89], v[150:153], v[204:207], v[86:89]
	v_mfma_f32_16x16x32_bf16 v[82:85], v[178:181], v[204:207], v[82:85]
	v_mfma_f32_16x16x32_bf16 v[70:73], v[150:153], v[212:215], v[70:73]
	v_mfma_f32_16x16x32_bf16 v[66:69], v[178:181], v[212:215], v[66:69]
	s_setprio 0
	s_add_i32 s39, s39, s55
	v_lshl_add_u64 v[218:219], v[162:163], 0, s[24:25]
	s_mov_b32 m0, s39
	ds_read_b128 v[184:187], v169 offset:49152
	ds_read_b128 v[188:191], v169 offset:50176
	ds_read_b128 v[192:195], v169 offset:51200
	ds_read_b128 v[196:199], v169 offset:52224
	ds_read_b128 v[200:203], v169 offset:53248
	ds_read_b128 v[204:207], v169 offset:54272
	ds_read_b128 v[208:211], v169 offset:55296
	ds_read_b128 v[212:215], v169 offset:56320
	global_load_lds_dwordx4 v[218:219], off
	v_lshl_add_u64 v[218:219], v[162:163], 0, s[26:27]
	s_add_i32 m0, s39, 0x2000
	s_add_i32 s39, s70, s55
	global_load_lds_dwordx4 v[218:219], off
	v_lshl_add_u64 v[218:219], v[162:163], 0, s[28:29]
	s_mov_b32 m0, s39
	v_lshl_add_u64 v[162:163], v[162:163], 0, s[30:31]
	global_load_lds_dwordx4 v[218:219], off
	s_add_i32 m0, s39, 0x2000
	s_nop 0
	global_load_lds_dwordx4 v[162:163], off
	v_lshl_add_u64 v[162:163], v[216:217], 0, s[24:25]
	s_mov_b32 m0, s62
	s_nop 0
	global_load_lds_dwordx4 v[162:163], off
	v_lshl_add_u64 v[162:163], v[216:217], 0, s[26:27]
	s_mov_b32 m0, s63
	s_nop 0
	global_load_lds_dwordx4 v[162:163], off
	s_waitcnt vmcnt(8)
	s_waitcnt lgkmcnt(0)
	s_barrier
	s_setprio 1
	s_waitcnt lgkmcnt(0)
	v_mfma_f32_16x16x32_bf16 v[62:65], v[114:117], v[184:187], v[62:65]
	v_mfma_f32_16x16x32_bf16 v[58:61], v[130:133], v[184:187], v[58:61]
	v_mfma_f32_16x16x32_bf16 v[46:49], v[114:117], v[192:195], v[46:49]
	v_mfma_f32_16x16x32_bf16 v[42:45], v[130:133], v[192:195], v[42:45]
	v_mfma_f32_16x16x32_bf16 v[30:33], v[114:117], v[200:203], v[30:33]
	v_mfma_f32_16x16x32_bf16 v[26:29], v[130:133], v[200:203], v[26:29]
	v_mfma_f32_16x16x32_bf16 v[14:17], v[114:117], v[208:211], v[14:17]
	v_mfma_f32_16x16x32_bf16 v[10:13], v[130:133], v[208:211], v[10:13]
	v_mfma_f32_16x16x32_bf16 v[62:65], v[126:129], v[188:191], v[62:65]
	v_mfma_f32_16x16x32_bf16 v[58:61], v[142:145], v[188:191], v[58:61]
	v_mfma_f32_16x16x32_bf16 v[46:49], v[126:129], v[196:199], v[46:49]
	v_mfma_f32_16x16x32_bf16 v[42:45], v[142:145], v[196:199], v[42:45]
	v_mfma_f32_16x16x32_bf16 v[30:33], v[126:129], v[204:207], v[30:33]
	v_mfma_f32_16x16x32_bf16 v[26:29], v[142:145], v[204:207], v[26:29]
	v_mfma_f32_16x16x32_bf16 v[14:17], v[126:129], v[212:215], v[14:17]
	v_mfma_f32_16x16x32_bf16 v[10:13], v[142:145], v[212:215], v[10:13]
	v_mfma_f32_16x16x32_bf16 v[54:57], v[146:149], v[184:187], v[54:57]
	v_mfma_f32_16x16x32_bf16 v[50:53], v[174:177], v[184:187], v[50:53]
	v_mfma_f32_16x16x32_bf16 v[38:41], v[146:149], v[192:195], v[38:41]
	v_mfma_f32_16x16x32_bf16 v[34:37], v[174:177], v[192:195], v[34:37]
	v_mfma_f32_16x16x32_bf16 v[22:25], v[146:149], v[200:203], v[22:25]
	v_mfma_f32_16x16x32_bf16 v[18:21], v[174:177], v[200:203], v[18:21]
	v_mfma_f32_16x16x32_bf16 v[6:9], v[146:149], v[208:211], v[6:9]
	v_mfma_f32_16x16x32_bf16 v[2:5], v[174:177], v[208:211], v[2:5]
	v_mfma_f32_16x16x32_bf16 v[54:57], v[150:153], v[188:191], v[54:57]
	v_mfma_f32_16x16x32_bf16 v[50:53], v[178:181], v[188:191], v[50:53]
	v_mfma_f32_16x16x32_bf16 v[38:41], v[150:153], v[196:199], v[38:41]
	v_mfma_f32_16x16x32_bf16 v[34:37], v[178:181], v[196:199], v[34:37]
	v_mfma_f32_16x16x32_bf16 v[22:25], v[150:153], v[204:207], v[22:25]
	v_mfma_f32_16x16x32_bf16 v[18:21], v[178:181], v[204:207], v[18:21]
	s_barrier
	s_setprio 2
	v_mfma_f32_16x16x32_bf16 v[6:9], v[150:153], v[212:215], v[6:9]
	v_mfma_f32_16x16x32_bf16 v[2:5], v[178:181], v[212:215], v[2:5]
	s_setprio 0
	s_add_u32 s68, s68, 0x1000
	s_addc_u32 s69, s69, 0
	s_add_u32 s11, s11, 0x1000
	s_addc_u32 s37, s37, 0
	s_cmp_ge_i32 s41, s79
	s_mov_b32 s39, s41
	s_cbranch_scc0 .LBB0_1533
	s_and_b64 vcc, exec, s[34:35]
	s_cbranch_vccnz .LBB0_1538
	s_lshl_b32 s11, s2, 8
	s_cmp_gt_i32 s2, 63
	s_mov_b64 s[68:69], -1
	s_cbranch_scc1 .LBB0_1539

; #define PG8_STAGE(bufoff, gbase, voff) do { if constexpr (!pg8_noload<Epi>::value) { _Pragma("unroll") for (int _i = 0; _i < 2; ++_i) \
;         __builtin_amdgcn_global_load_lds((const unsigned*)((const char*)(gbase) + (size_t)_i * pstep + (voff)[0]), (PG8_LAS unsigned*)(lds + (bufoff) + ldsw + _i * 8192), 16, 0, 0); } } while (0)
; #define PG8_LDA(dst, b, h) do { _Pragma("unroll") for (int m = 0; m < 4; ++m) _Pragma("unroll") for (int k = 0; k < 2; ++k) dst[m][k] = *(const PG8_LAS bf16x8*)(lds + PG8_SA(b, h) + aoff + m * 2048 + k * 1024); } while (0)
; #define PG8_LDB(dst, b, h) do { _Pragma("unroll") for (int n = 0; n < 2; ++n) _Pragma("unroll") for (int k = 0; k < 2; ++k) dst[n][k] = *(const PG8_LAS bf16x8*)(lds + PG8_SB(b, h) + boff + n * 2048 + k * 1024); } while (0)
; #define PG8_MMA(ai, bj, At, Bt) do { __builtin_amdgcn_s_setprio(1); _Pragma("unroll") for (int m = 0; m < 4; ++m) _Pragma("unroll") for (int n = 0; n < 2; ++n) _Pragma("unroll") for (int k = 0; k < 2; ++k) \
;         acc[ai][bj][m][n] = __builtin_amdgcn_mfma_f32_16x16x32_bf16(Bt[n][k], At[m][k], acc[ai][bj][m][n], 0, 0, 0); __builtin_amdgcn_s_setprio(0); } while (0)
; #define PG8_WAIT_V(n) asm volatile("s_waitcnt vmcnt(" #n ")" ::: "memory")
; #define PG8_WAIT_L(n) asm volatile("s_waitcnt lgkmcnt(" #n ")" ::: "memory")
; #define PG8_BAR __builtin_amdgcn_s_barrier()
; #define PG8_SCHED __builtin_amdgcn_sched_barrier(0)
; template <class Epi, class Sched, bool ALIGN_EPI = false, bool SP2 = false, bool ABLK = false>
; __device__ __forceinline__ void gemm_phase(PG8_LAS unsigned char* lds, const Gemm g, const Sched& S, const Epi& E) {
;     ...
;             PG8_LDB(B0, 0, 0); PG8_LDB(B1, 0, 1); PG8_SCHED; PG8_LDA(At, 0, 0); PG8_STAGE(PG8_SA(1, 1), a1 + hstep, voffA);
;             PG8_WAIT_V(8); PG8_WAIT_L(0); PG8_BAR; PG8_MMA(0, 0, At, B0); PG8_MMA(0, 1, At, B1); PG8_BAR; PG8_SCHED;
;             PG8_LDA(At, 0, 1); PG8_STAGE(PG8_SB(0, 0), b2, voffB); PG8_STAGE(PG8_SB(0, 1), b2 + hstep, voffB); PG8_STAGE(PG8_SA(0, 0), a2, voffA);
;             PG8_WAIT_V(8); PG8_WAIT_L(0); PG8_BAR; PG8_MMA(1, 0, At, B0); PG8_MMA(1, 1, At, B1); PG8_BAR; PG8_SCHED;
.LBB0_1657:
	s_or_b32 s26, s94, 1
	s_lshl_b64 s[82:83], s[26:27], 11
	s_add_u32 s88, s74, s82
	v_add_u32_e32 v140, s12, v173
	s_addc_u32 s89, s75, s83
	s_add_i32 s26, s94, 2
	ds_read_b128 v[130:133], v140
	ds_read_b128 v[134:137], v140 offset:1024
	ds_read_b128 v[154:157], v140 offset:2048
	ds_read_b128 v[158:161], v140 offset:3072
	v_add_u32_e32 v140, s13, v173
	s_lshl_b64 s[90:91], s[26:27], 11
	ds_read_b128 v[162:165], v140
	ds_read_b128 v[166:169], v140 offset:1024
	ds_read_b128 v[184:187], v140 offset:2048
	ds_read_b128 v[188:191], v140 offset:3072
	s_add_u32 s92, s74, s90
	s_addc_u32 s93, s75, s91
	s_and_b64 s[82:83], s[80:81], exec
	s_cselect_b32 s83, s93, s3
	s_cselect_b32 s82, s92, s25
	s_add_u32 s90, s76, s90
	s_addc_u32 s91, s77, s91
	s_and_b64 s[80:81], s[80:81], exec
	s_cselect_b32 s81, s91, s65
	s_cselect_b32 s80, s90, s67
	v_lshl_add_u64 v[170:171], s[88:89], 0, v[138:139]
	v_lshl_add_u64 v[224:225], v[170:171], 0, s[20:21]
	s_add_i32 m0, s56, 0xc000
	ds_read_b128 v[192:195], v178
	ds_read_b128 v[196:199], v178 offset:1024
	ds_read_b128 v[200:203], v178 offset:2048
	ds_read_b128 v[204:207], v178 offset:3072
	ds_read_b128 v[208:211], v178 offset:4096
	ds_read_b128 v[212:215], v178 offset:5120
	ds_read_b128 v[216:219], v178 offset:6144
	ds_read_b128 v[220:223], v178 offset:7168
	global_load_lds_dwordx4 v[224:225], off
	v_lshl_add_u64 v[170:171], v[170:171], 0, s[22:23]
	s_add_i32 m0, s56, 0xe000
	s_nop 0
	global_load_lds_dwordx4 v[170:171], off
	s_waitcnt vmcnt(8)
	s_waitcnt lgkmcnt(0)
	s_barrier
	s_setprio 1
	s_waitcnt lgkmcnt(0)
	v_mfma_f32_16x16x32_bf16 v[126:129], v[130:133], v[192:195], v[126:129]
	v_mfma_f32_16x16x32_bf16 v[122:125], v[154:157], v[192:195], v[122:125]
	v_mfma_f32_16x16x32_bf16 v[110:113], v[130:133], v[200:203], v[110:113]
	v_mfma_f32_16x16x32_bf16 v[106:109], v[154:157], v[200:203], v[106:109]
	v_mfma_f32_16x16x32_bf16 v[94:97], v[130:133], v[208:211], v[94:97]
	v_mfma_f32_16x16x32_bf16 v[90:93], v[154:157], v[208:211], v[90:93]
	v_mfma_f32_16x16x32_bf16 v[78:81], v[130:133], v[216:219], v[78:81]
	v_mfma_f32_16x16x32_bf16 v[74:77], v[154:157], v[216:219], v[74:77]
	v_mfma_f32_16x16x32_bf16 v[126:129], v[134:137], v[196:199], v[126:129]
	v_mfma_f32_16x16x32_bf16 v[122:125], v[158:161], v[196:199], v[122:125]
	v_mfma_f32_16x16x32_bf16 v[110:113], v[134:137], v[204:207], v[110:113]
	v_mfma_f32_16x16x32_bf16 v[106:109], v[158:161], v[204:207], v[106:109]
	v_mfma_f32_16x16x32_bf16 v[94:97], v[134:137], v[212:215], v[94:97]
	v_mfma_f32_16x16x32_bf16 v[90:93], v[158:161], v[212:215], v[90:93]
	v_mfma_f32_16x16x32_bf16 v[78:81], v[134:137], v[220:223], v[78:81]
	v_mfma_f32_16x16x32_bf16 v[74:77], v[158:161], v[220:223], v[74:77]
	v_mfma_f32_16x16x32_bf16 v[118:121], v[162:165], v[192:195], v[118:121]
	v_mfma_f32_16x16x32_bf16 v[114:117], v[184:187], v[192:195], v[114:117]
	v_mfma_f32_16x16x32_bf16 v[102:105], v[162:165], v[200:203], v[102:105]
	v_mfma_f32_16x16x32_bf16 v[98:101], v[184:187], v[200:203], v[98:101]
	v_mfma_f32_16x16x32_bf16 v[86:89], v[162:165], v[208:211], v[86:89]
	v_mfma_f32_16x16x32_bf16 v[82:85], v[184:187], v[208:211], v[82:85]
	v_mfma_f32_16x16x32_bf16 v[70:73], v[162:165], v[216:219], v[70:73]
	v_mfma_f32_16x16x32_bf16 v[66:69], v[184:187], v[216:219], v[66:69]
	v_mfma_f32_16x16x32_bf16 v[118:121], v[166:169], v[196:199], v[118:121]
	v_mfma_f32_16x16x32_bf16 v[114:117], v[188:191], v[196:199], v[114:117]
	s_barrier
	s_setprio 2
	v_mfma_f32_16x16x32_bf16 v[102:105], v[166:169], v[204:207], v[102:105]
	v_mfma_f32_16x16x32_bf16 v[98:101], v[188:191], v[204:207], v[98:101]
	v_mfma_f32_16x16x32_bf16 v[86:89], v[166:169], v[212:215], v[86:89]
	v_mfma_f32_16x16x32_bf16 v[82:85], v[188:191], v[212:215], v[82:85]
	v_mfma_f32_16x16x32_bf16 v[70:73], v[166:169], v[220:223], v[70:73]
	v_mfma_f32_16x16x32_bf16 v[66:69], v[188:191], v[220:223], v[66:69]
	s_setprio 0
	v_lshl_add_u64 v[170:171], s[80:81], 0, v[138:139]
	s_add_i32 s80, s12, s55
	s_mov_b32 m0, s80
	ds_read_b128 v[192:195], v178 offset:16384
	ds_read_b128 v[196:199], v178 offset:17408
	ds_read_b128 v[200:203], v178 offset:18432
	ds_read_b128 v[204:207], v178 offset:19456
	ds_read_b128 v[208:211], v178 offset:20480
	ds_read_b128 v[212:215], v178 offset:21504
	ds_read_b128 v[216:219], v178 offset:22528
	ds_read_b128 v[220:223], v178 offset:23552
	global_load_lds_dwordx4 v[170:171], off
	v_lshl_add_u64 v[224:225], v[170:171], 0, s[18:19]
	s_add_i32 m0, s80, 0x2000
	s_add_i32 s80, s13, s55
	global_load_lds_dwordx4 v[224:225], off
	v_lshl_add_u64 v[224:225], v[170:171], 0, s[20:21]
	s_mov_b32 m0, s80
	s_nop 0
	global_load_lds_dwordx4 v[224:225], off
	v_lshl_add_u64 v[224:225], v[170:171], 0, s[22:23]
	s_add_i32 m0, s80, 0x2000
	s_nop 0
	global_load_lds_dwordx4 v[224:225], off
	v_lshl_add_u64 v[224:225], s[82:83], 0, v[138:139]
	s_mov_b32 m0, s56
	v_lshl_add_u64 v[226:227], v[224:225], 0, s[18:19]
	global_load_lds_dwordx4 v[224:225], off
	s_mov_b32 m0, s57
	s_nop 0
	global_load_lds_dwordx4 v[226:227], off
	s_waitcnt vmcnt(8)
	s_waitcnt lgkmcnt(0)
	s_barrier
; #define PG8_STAGE(bufoff, gbase, voff) do { if constexpr (!pg8_noload<Epi>::value) { _Pragma("unroll") for (int _i = 0; _i < 2; ++_i) \
;         __builtin_amdgcn_global_load_lds((const unsigned*)((const char*)(gbase) + (size_t)_i * pstep + (voff)[0]), (PG8_LAS unsigned*)(lds + (bufoff) + ldsw + _i * 8192), 16, 0, 0); } } while (0)
; #define PG8_LDA(dst, b, h) do { _Pragma("unroll") for (int m = 0; m < 4; ++m) _Pragma("unroll") for (int k = 0; k < 2; ++k) dst[m][k] = *(const PG8_LAS bf16x8*)(lds + PG8_SA(b, h) + aoff + m * 2048 + k * 1024); } while (0)
; #define PG8_LDB(dst, b, h) do { _Pragma("unroll") for (int n = 0; n < 2; ++n) _Pragma("unroll") for (int k = 0; k < 2; ++k) dst[n][k] = *(const PG8_LAS bf16x8*)(lds + PG8_SB(b, h) + boff + n * 2048 + k * 1024); } while (0)
; #define PG8_MMA(ai, bj, At, Bt) do { __builtin_amdgcn_s_setprio(1); _Pragma("unroll") for (int m = 0; m < 4; ++m) _Pragma("unroll") for (int n = 0; n < 2; ++n) _Pragma("unroll") for (int k = 0; k < 2; ++k) \
;         acc[ai][bj][m][n] = __builtin_amdgcn_mfma_f32_16x16x32_bf16(Bt[n][k], At[m][k], acc[ai][bj][m][n], 0, 0, 0); __builtin_amdgcn_s_setprio(0); } while (0)
; #define PG8_WAIT_V(n) asm volatile("s_waitcnt vmcnt(" #n ")" ::: "memory")
; #define PG8_WAIT_L(n) asm volatile("s_waitcnt lgkmcnt(" #n ")" ::: "memory")
; #define PG8_BAR __builtin_amdgcn_s_barrier()
; #define PG8_SCHED __builtin_amdgcn_sched_barrier(0)
; template <class Epi, class Sched, bool ALIGN_EPI = false, bool SP2 = false, bool ABLK = false>
; __device__ __forceinline__ void gemm_phase(PG8_LAS unsigned char* lds, const Gemm g, const Sched& S, const Epi& E) {
;     ...
;             PG8_WAIT_V(8); PG8_WAIT_L(0); PG8_BAR; PG8_MMA(1, 0, At, B0); PG8_MMA(1, 1, At, B1); PG8_BAR; PG8_SCHED;
;             PG8_LDB(B0, 1, 0); PG8_LDB(B1, 1, 1); PG8_SCHED; PG8_LDA(At, 1, 0); PG8_STAGE(PG8_SA(0, 1), a2 + hstep, voffA);
;             PG8_WAIT_V(8); PG8_WAIT_L(0); PG8_BAR; PG8_MMA(0, 0, At, B0); PG8_MMA(0, 1, At, B1); PG8_BAR; PG8_SCHED;
	s_setprio 1
	s_waitcnt lgkmcnt(0)
	v_mfma_f32_16x16x32_bf16 v[62:65], v[130:133], v[192:195], v[62:65]
	v_mfma_f32_16x16x32_bf16 v[58:61], v[154:157], v[192:195], v[58:61]
	v_mfma_f32_16x16x32_bf16 v[46:49], v[130:133], v[200:203], v[46:49]
	v_mfma_f32_16x16x32_bf16 v[42:45], v[154:157], v[200:203], v[42:45]
	v_mfma_f32_16x16x32_bf16 v[30:33], v[130:133], v[208:211], v[30:33]
	v_mfma_f32_16x16x32_bf16 v[26:29], v[154:157], v[208:211], v[26:29]
	v_mfma_f32_16x16x32_bf16 v[14:17], v[130:133], v[216:219], v[14:17]
	v_mfma_f32_16x16x32_bf16 v[10:13], v[154:157], v[216:219], v[10:13]
	v_mfma_f32_16x16x32_bf16 v[62:65], v[134:137], v[196:199], v[62:65]
	v_mfma_f32_16x16x32_bf16 v[58:61], v[158:161], v[196:199], v[58:61]
	v_mfma_f32_16x16x32_bf16 v[46:49], v[134:137], v[204:207], v[46:49]
	v_mfma_f32_16x16x32_bf16 v[42:45], v[158:161], v[204:207], v[42:45]
	v_mfma_f32_16x16x32_bf16 v[30:33], v[134:137], v[212:215], v[30:33]
	v_mfma_f32_16x16x32_bf16 v[26:29], v[158:161], v[212:215], v[26:29]
	v_mfma_f32_16x16x32_bf16 v[14:17], v[134:137], v[220:223], v[14:17]
	v_mfma_f32_16x16x32_bf16 v[10:13], v[158:161], v[220:223], v[10:13]
	v_mfma_f32_16x16x32_bf16 v[54:57], v[162:165], v[192:195], v[54:57]
	v_mfma_f32_16x16x32_bf16 v[50:53], v[184:187], v[192:195], v[50:53]
	v_mfma_f32_16x16x32_bf16 v[38:41], v[162:165], v[200:203], v[38:41]
	v_mfma_f32_16x16x32_bf16 v[34:37], v[184:187], v[200:203], v[34:37]
	v_mfma_f32_16x16x32_bf16 v[22:25], v[162:165], v[208:211], v[22:25]
	v_mfma_f32_16x16x32_bf16 v[18:21], v[184:187], v[208:211], v[18:21]
	v_mfma_f32_16x16x32_bf16 v[6:9], v[162:165], v[216:219], v[6:9]
	v_mfma_f32_16x16x32_bf16 v[2:5], v[184:187], v[216:219], v[2:5]
	v_mfma_f32_16x16x32_bf16 v[54:57], v[166:169], v[196:199], v[54:57]
	v_mfma_f32_16x16x32_bf16 v[50:53], v[188:191], v[196:199], v[50:53]
	v_mfma_f32_16x16x32_bf16 v[38:41], v[166:169], v[204:207], v[38:41]
	v_mfma_f32_16x16x32_bf16 v[34:37], v[188:191], v[204:207], v[34:37]
	v_mfma_f32_16x16x32_bf16 v[22:25], v[166:169], v[212:215], v[22:25]
	v_mfma_f32_16x16x32_bf16 v[18:21], v[188:191], v[212:215], v[18:21]
	s_barrier
	s_setprio 2
	v_mfma_f32_16x16x32_bf16 v[6:9], v[166:169], v[220:223], v[6:9]
	v_mfma_f32_16x16x32_bf16 v[2:5], v[188:191], v[220:223], v[2:5]
	s_setprio 0
	s_add_i32 s80, 0, 0x18000
	v_add_u32_e32 v140, s80, v173
	s_add_i32 s81, 0, 0x1c000
	ds_read_b128 v[130:133], v140
	ds_read_b128 v[134:137], v140 offset:1024
	ds_read_b128 v[154:157], v140 offset:2048
	ds_read_b128 v[158:161], v140 offset:3072
	v_add_u32_e32 v140, s81, v173
	ds_read_b128 v[162:165], v140
	ds_read_b128 v[166:169], v140 offset:1024
	ds_read_b128 v[184:187], v140 offset:2048
	ds_read_b128 v[188:191], v140 offset:3072
	s_mov_b32 m0, s58
	v_lshl_add_u64 v[226:227], v[224:225], 0, s[20:21]
	ds_read_b128 v[192:195], v178 offset:32768
	ds_read_b128 v[196:199], v178 offset:33792
	ds_read_b128 v[200:203], v178 offset:34816
	ds_read_b128 v[204:207], v178 offset:35840
	ds_read_b128 v[208:211], v178 offset:36864
	ds_read_b128 v[212:215], v178 offset:37888
	ds_read_b128 v[216:219], v178 offset:38912
	ds_read_b128 v[220:223], v178 offset:39936
	global_load_lds_dwordx4 v[226:227], off
	v_lshl_add_u64 v[226:227], v[224:225], 0, s[22:23]
	s_mov_b32 m0, s59
	s_nop 0
	global_load_lds_dwordx4 v[226:227], off
	s_waitcnt vmcnt(8)
	s_waitcnt lgkmcnt(0)
	s_barrier
	s_setprio 1
	s_waitcnt lgkmcnt(0)
	v_mfma_f32_16x16x32_bf16 v[126:129], v[130:133], v[192:195], v[126:129]
	v_mfma_f32_16x16x32_bf16 v[122:125], v[154:157], v[192:195], v[122:125]
	v_mfma_f32_16x16x32_bf16 v[110:113], v[130:133], v[200:203], v[110:113]
	v_mfma_f32_16x16x32_bf16 v[106:109], v[154:157], v[200:203], v[106:109]
	v_mfma_f32_16x16x32_bf16 v[94:97], v[130:133], v[208:211], v[94:97]
	v_mfma_f32_16x16x32_bf16 v[90:93], v[154:157], v[208:211], v[90:93]
	v_mfma_f32_16x16x32_bf16 v[78:81], v[130:133], v[216:219], v[78:81]
	v_mfma_f32_16x16x32_bf16 v[74:77], v[154:157], v[216:219], v[74:77]
	v_mfma_f32_16x16x32_bf16 v[126:129], v[134:137], v[196:199], v[126:129]
	v_mfma_f32_16x16x32_bf16 v[122:125], v[158:161], v[196:199], v[122:125]
	v_mfma_f32_16x16x32_bf16 v[110:113], v[134:137], v[204:207], v[110:113]
	v_mfma_f32_16x16x32_bf16 v[106:109], v[158:161], v[204:207], v[106:109]
	v_mfma_f32_16x16x32_bf16 v[94:97], v[134:137], v[212:215], v[94:97]
	v_mfma_f32_16x16x32_bf16 v[90:93], v[158:161], v[212:215], v[90:93]
	v_mfma_f32_16x16x32_bf16 v[78:81], v[134:137], v[220:223], v[78:81]
	v_mfma_f32_16x16x32_bf16 v[74:77], v[158:161], v[220:223], v[74:77]
	v_mfma_f32_16x16x32_bf16 v[118:121], v[162:165], v[192:195], v[118:121]
	v_mfma_f32_16x16x32_bf16 v[114:117], v[184:187], v[192:195], v[114:117]
	v_mfma_f32_16x16x32_bf16 v[102:105], v[162:165], v[200:203], v[102:105]
	v_mfma_f32_16x16x32_bf16 v[98:101], v[184:187], v[200:203], v[98:101]
	v_mfma_f32_16x16x32_bf16 v[86:89], v[162:165], v[208:211], v[86:89]
	v_mfma_f32_16x16x32_bf16 v[82:85], v[184:187], v[208:211], v[82:85]
	v_mfma_f32_16x16x32_bf16 v[70:73], v[162:165], v[216:219], v[70:73]
	v_mfma_f32_16x16x32_bf16 v[66:69], v[184:187], v[216:219], v[66:69]
	v_mfma_f32_16x16x32_bf16 v[118:121], v[166:169], v[196:199], v[118:121]
	v_mfma_f32_16x16x32_bf16 v[114:117], v[188:191], v[196:199], v[114:117]
	s_barrier
; #define PG8_STAGE(bufoff, gbase, voff) do { if constexpr (!pg8_noload<Epi>::value) { _Pragma("unroll") for (int _i = 0; _i < 2; ++_i) \
;         __builtin_amdgcn_global_load_lds((const unsigned*)((const char*)(gbase) + (size_t)_i * pstep + (voff)[0]), (PG8_LAS unsigned*)(lds + (bufoff) + ldsw + _i * 8192), 16, 0, 0); } } while (0)
; #define PG8_LDA(dst, b, h) do { _Pragma("unroll") for (int m = 0; m < 4; ++m) _Pragma("unroll") for (int k = 0; k < 2; ++k) dst[m][k] = *(const PG8_LAS bf16x8*)(lds + PG8_SA(b, h) + aoff + m * 2048 + k * 1024); } while (0)
; #define PG8_MMA(ai, bj, At, Bt) do { __builtin_amdgcn_s_setprio(1); _Pragma("unroll") for (int m = 0; m < 4; ++m) _Pragma("unroll") for (int n = 0; n < 2; ++n) _Pragma("unroll") for (int k = 0; k < 2; ++k) \
;         acc[ai][bj][m][n] = __builtin_amdgcn_mfma_f32_16x16x32_bf16(Bt[n][k], At[m][k], acc[ai][bj][m][n], 0, 0, 0); __builtin_amdgcn_s_setprio(0); } while (0)
; #define PG8_WAIT_V(n) asm volatile("s_waitcnt vmcnt(" #n ")" ::: "memory")
; #define PG8_WAIT_L(n) asm volatile("s_waitcnt lgkmcnt(" #n ")" ::: "memory")
; #define PG8_BAR __builtin_amdgcn_s_barrier()
; #define PG8_SCHED __builtin_amdgcn_sched_barrier(0)
; template <class Epi, class Sched, bool ALIGN_EPI = false, bool SP2 = false, bool ABLK = false>
; __device__ __forceinline__ void gemm_phase(PG8_LAS unsigned char* lds, const Gemm g, const Sched& S, const Epi& E) {
;     ...
;             PG8_WAIT_V(8); PG8_WAIT_L(0); PG8_BAR; PG8_MMA(0, 0, At, B0); PG8_MMA(0, 1, At, B1); PG8_BAR; PG8_SCHED;
;             PG8_LDA(At, 1, 1); PG8_STAGE(PG8_SB(1, 0), b3, voffB); PG8_STAGE(PG8_SB(1, 1), b3 + hstep, voffB); PG8_STAGE(PG8_SA(1, 0), a3, voffA);
;             PG8_WAIT_V(8); PG8_WAIT_L(0); PG8_BAR; PG8_MMA(1, 0, At, B0); PG8_MMA(1, 1, At, B1); PG8_BAR; PG8_SCHED;
	s_setprio 2
	v_mfma_f32_16x16x32_bf16 v[102:105], v[166:169], v[204:207], v[102:105]
	v_mfma_f32_16x16x32_bf16 v[98:101], v[188:191], v[204:207], v[98:101]
	v_mfma_f32_16x16x32_bf16 v[86:89], v[166:169], v[212:215], v[86:89]
	v_mfma_f32_16x16x32_bf16 v[82:85], v[188:191], v[212:215], v[82:85]
	v_mfma_f32_16x16x32_bf16 v[70:73], v[166:169], v[220:223], v[70:73]
	v_mfma_f32_16x16x32_bf16 v[66:69], v[188:191], v[220:223], v[66:69]
	s_setprio 0
	s_add_i32 s80, s80, s55
	v_lshl_add_u64 v[226:227], v[170:171], 0, s[30:31]
	s_mov_b32 m0, s80
	ds_read_b128 v[192:195], v178 offset:49152
	ds_read_b128 v[196:199], v178 offset:50176
	ds_read_b128 v[200:203], v178 offset:51200
	ds_read_b128 v[204:207], v178 offset:52224
	ds_read_b128 v[208:211], v178 offset:53248
	ds_read_b128 v[212:215], v178 offset:54272
	ds_read_b128 v[216:219], v178 offset:55296
	ds_read_b128 v[220:223], v178 offset:56320
	global_load_lds_dwordx4 v[226:227], off
	v_lshl_add_u64 v[226:227], v[170:171], 0, s[34:35]
	s_add_i32 m0, s80, 0x2000
	s_add_i32 s80, s81, s55
	global_load_lds_dwordx4 v[226:227], off
	v_lshl_add_u64 v[226:227], v[170:171], 0, s[36:37]
	s_mov_b32 m0, s80
	v_lshl_add_u64 v[170:171], v[170:171], 0, s[38:39]
	global_load_lds_dwordx4 v[226:227], off
	s_add_i32 m0, s80, 0x2000
	s_nop 0
	global_load_lds_dwordx4 v[170:171], off
	v_lshl_add_u64 v[170:171], v[224:225], 0, s[30:31]
	s_mov_b32 m0, s63
	s_nop 0
	global_load_lds_dwordx4 v[170:171], off
	v_lshl_add_u64 v[170:171], v[224:225], 0, s[34:35]
	s_mov_b32 m0, s73
	s_nop 0
	global_load_lds_dwordx4 v[170:171], off
	s_waitcnt vmcnt(8)
	s_waitcnt lgkmcnt(0)
	s_barrier
	s_setprio 1
	s_waitcnt lgkmcnt(0)
	v_mfma_f32_16x16x32_bf16 v[62:65], v[130:133], v[192:195], v[62:65]
	v_mfma_f32_16x16x32_bf16 v[58:61], v[154:157], v[192:195], v[58:61]
	v_mfma_f32_16x16x32_bf16 v[46:49], v[130:133], v[200:203], v[46:49]
	v_mfma_f32_16x16x32_bf16 v[42:45], v[154:157], v[200:203], v[42:45]
	v_mfma_f32_16x16x32_bf16 v[30:33], v[130:133], v[208:211], v[30:33]
	v_mfma_f32_16x16x32_bf16 v[26:29], v[154:157], v[208:211], v[26:29]
	v_mfma_f32_16x16x32_bf16 v[14:17], v[130:133], v[216:219], v[14:17]
	v_mfma_f32_16x16x32_bf16 v[10:13], v[154:157], v[216:219], v[10:13]
	v_mfma_f32_16x16x32_bf16 v[62:65], v[134:137], v[196:199], v[62:65]
	v_mfma_f32_16x16x32_bf16 v[58:61], v[158:161], v[196:199], v[58:61]
	v_mfma_f32_16x16x32_bf16 v[46:49], v[134:137], v[204:207], v[46:49]
	v_mfma_f32_16x16x32_bf16 v[42:45], v[158:161], v[204:207], v[42:45]
	v_mfma_f32_16x16x32_bf16 v[30:33], v[134:137], v[212:215], v[30:33]
	v_mfma_f32_16x16x32_bf16 v[26:29], v[158:161], v[212:215], v[26:29]
	v_mfma_f32_16x16x32_bf16 v[14:17], v[134:137], v[220:223], v[14:17]
	v_mfma_f32_16x16x32_bf16 v[10:13], v[158:161], v[220:223], v[10:13]
	v_mfma_f32_16x16x32_bf16 v[54:57], v[162:165], v[192:195], v[54:57]
	v_mfma_f32_16x16x32_bf16 v[50:53], v[184:187], v[192:195], v[50:53]
	v_mfma_f32_16x16x32_bf16 v[38:41], v[162:165], v[200:203], v[38:41]
	v_mfma_f32_16x16x32_bf16 v[34:37], v[184:187], v[200:203], v[34:37]
	v_mfma_f32_16x16x32_bf16 v[22:25], v[162:165], v[208:211], v[22:25]
	v_mfma_f32_16x16x32_bf16 v[18:21], v[184:187], v[208:211], v[18:21]
	v_mfma_f32_16x16x32_bf16 v[6:9], v[162:165], v[216:219], v[6:9]
	v_mfma_f32_16x16x32_bf16 v[2:5], v[184:187], v[216:219], v[2:5]
	v_mfma_f32_16x16x32_bf16 v[54:57], v[166:169], v[196:199], v[54:57]
	v_mfma_f32_16x16x32_bf16 v[50:53], v[188:191], v[196:199], v[50:53]
	v_mfma_f32_16x16x32_bf16 v[38:41], v[166:169], v[204:207], v[38:41]
	v_mfma_f32_16x16x32_bf16 v[34:37], v[188:191], v[204:207], v[34:37]
	v_mfma_f32_16x16x32_bf16 v[22:25], v[166:169], v[212:215], v[22:25]
	v_mfma_f32_16x16x32_bf16 v[18:21], v[188:191], v[212:215], v[18:21]
	s_barrier
	s_setprio 2
	v_mfma_f32_16x16x32_bf16 v[6:9], v[166:169], v[220:223], v[6:9]
	v_mfma_f32_16x16x32_bf16 v[2:5], v[188:191], v[220:223], v[2:5]
	s_setprio 0
	s_cmp_gt_u32 s94, 29
	s_mov_b32 s94, s26
	s_cbranch_scc1 .LBB0_1669

; #define PG8_STAGE(bufoff, gbase, voff) do { if constexpr (!pg8_noload<Epi>::value) { _Pragma("unroll") for (int _i = 0; _i < 2; ++_i) \
;         __builtin_amdgcn_global_load_lds((const unsigned*)((const char*)(gbase) + (size_t)_i * pstep + (voff)[0]), (PG8_LAS unsigned*)(lds + (bufoff) + ldsw + _i * 8192), 16, 0, 0); } } while (0)
; #define PG8_LDA(dst, b, h) do { _Pragma("unroll") for (int m = 0; m < 4; ++m) _Pragma("unroll") for (int k = 0; k < 2; ++k) dst[m][k] = *(const PG8_LAS bf16x8*)(lds + PG8_SA(b, h) + aoff + m * 2048 + k * 1024); } while (0)
; #define PG8_LDB(dst, b, h) do { _Pragma("unroll") for (int n = 0; n < 2; ++n) _Pragma("unroll") for (int k = 0; k < 2; ++k) dst[n][k] = *(const PG8_LAS bf16x8*)(lds + PG8_SB(b, h) + boff + n * 2048 + k * 1024); } while (0)
; #define PG8_MMA(ai, bj, At, Bt) do { __builtin_amdgcn_s_setprio(1); _Pragma("unroll") for (int m = 0; m < 4; ++m) _Pragma("unroll") for (int n = 0; n < 2; ++n) _Pragma("unroll") for (int k = 0; k < 2; ++k) \
;         acc[ai][bj][m][n] = __builtin_amdgcn_mfma_f32_16x16x32_bf16(Bt[n][k], At[m][k], acc[ai][bj][m][n], 0, 0, 0); __builtin_amdgcn_s_setprio(0); } while (0)
; #define PG8_WAIT_V(n) asm volatile("s_waitcnt vmcnt(" #n ")" ::: "memory")
; #define PG8_WAIT_L(n) asm volatile("s_waitcnt lgkmcnt(" #n ")" ::: "memory")
; #define PG8_BAR __builtin_amdgcn_s_barrier()
; #define PG8_SCHED __builtin_amdgcn_sched_barrier(0)
; template <class Epi, class Sched, bool ALIGN_EPI = false, bool SP2 = false, bool ABLK = false>
; __device__ __forceinline__ void gemm_phase(PG8_LAS unsigned char* lds, const Gemm g, const Sched& S, const Epi& E) {
;     ...
;             PG8_LDB(B0, 0, 0); PG8_LDB(B1, 0, 1); PG8_SCHED; PG8_LDA(At, 0, 0); PG8_STAGE(PG8_SA(1, 1), a1 + hstep, voffA);
;             PG8_WAIT_V(8); PG8_WAIT_L(0); PG8_BAR; PG8_MMA(0, 0, At, B0); PG8_MMA(0, 1, At, B1); PG8_BAR; PG8_SCHED;
;             PG8_LDA(At, 0, 1); PG8_STAGE(PG8_SB(0, 0), b2, voffB); PG8_STAGE(PG8_SB(0, 1), b2 + hstep, voffB); PG8_STAGE(PG8_SA(0, 0), a2, voffA);
;             PG8_WAIT_V(8); PG8_WAIT_L(0); PG8_BAR; PG8_MMA(1, 0, At, B0); PG8_MMA(1, 1, At, B1); PG8_BAR; PG8_SCHED;
.LBB0_1997:
	ds_read_b128 v[130:133], v175
	ds_read_b128 v[134:137], v175 offset:1024
	ds_read_b128 v[138:141], v175 offset:2048
	ds_read_b128 v[142:145], v175 offset:3072
	ds_read_b128 v[146:149], v176
	ds_read_b128 v[150:153], v176 offset:1024
	ds_read_b128 v[154:157], v176 offset:2048
	ds_read_b128 v[158:161], v176 offset:3072
	s_add_i32 s43, s41, 2
	s_add_u32 s62, s52, 0xfff80800
	s_addc_u32 s63, s53, -1
	s_cmp_eq_u32 s3, s41
	s_cselect_b32 s63, s45, s63
	s_cselect_b32 s62, s44, s62
	s_cselect_b32 s77, s47, s39
	s_cselect_b32 s76, s46, s11
	v_lshl_add_u64 v[170:171], s[52:53], 0, v[166:167]
	s_add_i32 m0, s49, 0xc000
	ds_read_b128 v[184:187], v177
	ds_read_b128 v[188:191], v177 offset:1024
	ds_read_b128 v[192:195], v177 offset:2048
	ds_read_b128 v[196:199], v177 offset:3072
	ds_read_b128 v[200:203], v177 offset:4096
	ds_read_b128 v[204:207], v177 offset:5120
	ds_read_b128 v[208:211], v177 offset:6144
	ds_read_b128 v[212:215], v177 offset:7168
	global_load_lds_dwordx4 v[170:171], off
	v_lshl_add_u64 v[170:171], v[170:171], 0, s[12:13]
	s_add_i32 m0, s49, 0xe000
	s_nop 0
	global_load_lds_dwordx4 v[170:171], off
	s_waitcnt vmcnt(8)
	s_waitcnt lgkmcnt(0)
	s_barrier
	s_setprio 1
	s_waitcnt lgkmcnt(0)
	v_mfma_f32_16x16x32_bf16 v[126:129], v[130:133], v[184:187], v[126:129]
	v_mfma_f32_16x16x32_bf16 v[122:125], v[138:141], v[184:187], v[122:125]
	v_mfma_f32_16x16x32_bf16 v[110:113], v[130:133], v[192:195], v[110:113]
	v_mfma_f32_16x16x32_bf16 v[106:109], v[138:141], v[192:195], v[106:109]
	v_mfma_f32_16x16x32_bf16 v[94:97], v[130:133], v[200:203], v[94:97]
	v_mfma_f32_16x16x32_bf16 v[90:93], v[138:141], v[200:203], v[90:93]
	v_mfma_f32_16x16x32_bf16 v[78:81], v[130:133], v[208:211], v[78:81]
	v_mfma_f32_16x16x32_bf16 v[74:77], v[138:141], v[208:211], v[74:77]
	v_mfma_f32_16x16x32_bf16 v[126:129], v[134:137], v[188:191], v[126:129]
	v_mfma_f32_16x16x32_bf16 v[122:125], v[142:145], v[188:191], v[122:125]
	v_mfma_f32_16x16x32_bf16 v[110:113], v[134:137], v[196:199], v[110:113]
	v_mfma_f32_16x16x32_bf16 v[106:109], v[142:145], v[196:199], v[106:109]
	v_mfma_f32_16x16x32_bf16 v[94:97], v[134:137], v[204:207], v[94:97]
	v_mfma_f32_16x16x32_bf16 v[90:93], v[142:145], v[204:207], v[90:93]
	v_mfma_f32_16x16x32_bf16 v[78:81], v[134:137], v[212:215], v[78:81]
	v_mfma_f32_16x16x32_bf16 v[74:77], v[142:145], v[212:215], v[74:77]
	v_mfma_f32_16x16x32_bf16 v[118:121], v[146:149], v[184:187], v[118:121]
	v_mfma_f32_16x16x32_bf16 v[114:117], v[154:157], v[184:187], v[114:117]
	v_mfma_f32_16x16x32_bf16 v[102:105], v[146:149], v[192:195], v[102:105]
	v_mfma_f32_16x16x32_bf16 v[98:101], v[154:157], v[192:195], v[98:101]
	v_mfma_f32_16x16x32_bf16 v[86:89], v[146:149], v[200:203], v[86:89]
	v_mfma_f32_16x16x32_bf16 v[82:85], v[154:157], v[200:203], v[82:85]
	v_mfma_f32_16x16x32_bf16 v[70:73], v[146:149], v[208:211], v[70:73]
	v_mfma_f32_16x16x32_bf16 v[66:69], v[154:157], v[208:211], v[66:69]
	v_mfma_f32_16x16x32_bf16 v[118:121], v[150:153], v[188:191], v[118:121]
	v_mfma_f32_16x16x32_bf16 v[114:117], v[158:161], v[188:191], v[114:117]
	s_barrier
	s_setprio 2
	v_mfma_f32_16x16x32_bf16 v[102:105], v[150:153], v[196:199], v[102:105]
	v_mfma_f32_16x16x32_bf16 v[98:101], v[158:161], v[196:199], v[98:101]
	v_mfma_f32_16x16x32_bf16 v[86:89], v[150:153], v[204:207], v[86:89]
	v_mfma_f32_16x16x32_bf16 v[82:85], v[158:161], v[204:207], v[82:85]
	v_mfma_f32_16x16x32_bf16 v[70:73], v[150:153], v[212:215], v[70:73]
	v_mfma_f32_16x16x32_bf16 v[66:69], v[158:161], v[212:215], v[66:69]
	s_setprio 0
	s_add_i32 s41, s70, s57
	v_lshl_add_u64 v[170:171], s[76:77], 0, v[162:163]
	s_mov_b32 m0, s41
	ds_read_b128 v[184:187], v177 offset:16384
	ds_read_b128 v[188:191], v177 offset:17408
	ds_read_b128 v[192:195], v177 offset:18432
	ds_read_b128 v[196:199], v177 offset:19456
	ds_read_b128 v[200:203], v177 offset:20480
	ds_read_b128 v[204:207], v177 offset:21504
	ds_read_b128 v[208:211], v177 offset:22528
	ds_read_b128 v[212:215], v177 offset:23552
	global_load_lds_dwordx4 v[170:171], off
	v_lshl_add_u64 v[216:217], v[170:171], 0, s[12:13]
	s_add_i32 m0, s41, 0x2000
	s_add_i32 s41, s71, s57
	global_load_lds_dwordx4 v[216:217], off
	v_lshl_add_u64 v[216:217], v[170:171], 0, s[14:15]
	s_mov_b32 m0, s41
	s_nop 0
	global_load_lds_dwordx4 v[216:217], off
	v_lshl_add_u64 v[216:217], v[170:171], 0, s[16:17]
	s_add_i32 m0, s41, 0x2000
	s_nop 0
	global_load_lds_dwordx4 v[216:217], off
	v_lshl_add_u64 v[216:217], s[62:63], 0, v[162:163]
	s_mov_b32 m0, s49
	v_lshl_add_u64 v[218:219], v[216:217], 0, s[12:13]
	global_load_lds_dwordx4 v[216:217], off
	s_mov_b32 m0, s58
	s_nop 0
	global_load_lds_dwordx4 v[218:219], off
	s_waitcnt vmcnt(8)
	s_waitcnt lgkmcnt(0)
	s_barrier
; #define PG8_STAGE(bufoff, gbase, voff) do { if constexpr (!pg8_noload<Epi>::value) { _Pragma("unroll") for (int _i = 0; _i < 2; ++_i) \
;         __builtin_amdgcn_global_load_lds((const unsigned*)((const char*)(gbase) + (size_t)_i * pstep + (voff)[0]), (PG8_LAS unsigned*)(lds + (bufoff) + ldsw + _i * 8192), 16, 0, 0); } } while (0)
; #define PG8_LDA(dst, b, h) do { _Pragma("unroll") for (int m = 0; m < 4; ++m) _Pragma("unroll") for (int k = 0; k < 2; ++k) dst[m][k] = *(const PG8_LAS bf16x8*)(lds + PG8_SA(b, h) + aoff + m * 2048 + k * 1024); } while (0)
; #define PG8_LDB(dst, b, h) do { _Pragma("unroll") for (int n = 0; n < 2; ++n) _Pragma("unroll") for (int k = 0; k < 2; ++k) dst[n][k] = *(const PG8_LAS bf16x8*)(lds + PG8_SB(b, h) + boff + n * 2048 + k * 1024); } while (0)
; #define PG8_MMA(ai, bj, At, Bt) do { __builtin_amdgcn_s_setprio(1); _Pragma("unroll") for (int m = 0; m < 4; ++m) _Pragma("unroll") for (int n = 0; n < 2; ++n) _Pragma("unroll") for (int k = 0; k < 2; ++k) \
;         acc[ai][bj][m][n] = __builtin_amdgcn_mfma_f32_16x16x32_bf16(Bt[n][k], At[m][k], acc[ai][bj][m][n], 0, 0, 0); __builtin_amdgcn_s_setprio(0); } while (0)
; #define PG8_WAIT_V(n) asm volatile("s_waitcnt vmcnt(" #n ")" ::: "memory")
; #define PG8_WAIT_L(n) asm volatile("s_waitcnt lgkmcnt(" #n ")" ::: "memory")
; #define PG8_BAR __builtin_amdgcn_s_barrier()
; #define PG8_SCHED __builtin_amdgcn_sched_barrier(0)
; template <class Epi, class Sched, bool ALIGN_EPI = false, bool SP2 = false, bool ABLK = false>
; __device__ __forceinline__ void gemm_phase(PG8_LAS unsigned char* lds, const Gemm g, const Sched& S, const Epi& E) {
;     ...
;             PG8_WAIT_V(8); PG8_WAIT_L(0); PG8_BAR; PG8_MMA(1, 0, At, B0); PG8_MMA(1, 1, At, B1); PG8_BAR; PG8_SCHED;
;             PG8_LDB(B0, 1, 0); PG8_LDB(B1, 1, 1); PG8_SCHED; PG8_LDA(At, 1, 0); PG8_STAGE(PG8_SA(0, 1), a2 + hstep, voffA);
;             PG8_WAIT_V(8); PG8_WAIT_L(0); PG8_BAR; PG8_MMA(0, 0, At, B0); PG8_MMA(0, 1, At, B1); PG8_BAR; PG8_SCHED;
	s_setprio 1
	s_waitcnt lgkmcnt(0)
	v_mfma_f32_16x16x32_bf16 v[62:65], v[130:133], v[184:187], v[62:65]
	v_mfma_f32_16x16x32_bf16 v[58:61], v[138:141], v[184:187], v[58:61]
	v_mfma_f32_16x16x32_bf16 v[46:49], v[130:133], v[192:195], v[46:49]
	v_mfma_f32_16x16x32_bf16 v[42:45], v[138:141], v[192:195], v[42:45]
	v_mfma_f32_16x16x32_bf16 v[30:33], v[130:133], v[200:203], v[30:33]
	v_mfma_f32_16x16x32_bf16 v[26:29], v[138:141], v[200:203], v[26:29]
	v_mfma_f32_16x16x32_bf16 v[14:17], v[130:133], v[208:211], v[14:17]
	v_mfma_f32_16x16x32_bf16 v[10:13], v[138:141], v[208:211], v[10:13]
	v_mfma_f32_16x16x32_bf16 v[62:65], v[134:137], v[188:191], v[62:65]
	v_mfma_f32_16x16x32_bf16 v[58:61], v[142:145], v[188:191], v[58:61]
	v_mfma_f32_16x16x32_bf16 v[46:49], v[134:137], v[196:199], v[46:49]
	v_mfma_f32_16x16x32_bf16 v[42:45], v[142:145], v[196:199], v[42:45]
	v_mfma_f32_16x16x32_bf16 v[30:33], v[134:137], v[204:207], v[30:33]
	v_mfma_f32_16x16x32_bf16 v[26:29], v[142:145], v[204:207], v[26:29]
	v_mfma_f32_16x16x32_bf16 v[14:17], v[134:137], v[212:215], v[14:17]
	v_mfma_f32_16x16x32_bf16 v[10:13], v[142:145], v[212:215], v[10:13]
	v_mfma_f32_16x16x32_bf16 v[54:57], v[146:149], v[184:187], v[54:57]
	v_mfma_f32_16x16x32_bf16 v[50:53], v[154:157], v[184:187], v[50:53]
	v_mfma_f32_16x16x32_bf16 v[38:41], v[146:149], v[192:195], v[38:41]
	v_mfma_f32_16x16x32_bf16 v[34:37], v[154:157], v[192:195], v[34:37]
	v_mfma_f32_16x16x32_bf16 v[22:25], v[146:149], v[200:203], v[22:25]
	v_mfma_f32_16x16x32_bf16 v[18:21], v[154:157], v[200:203], v[18:21]
	v_mfma_f32_16x16x32_bf16 v[6:9], v[146:149], v[208:211], v[6:9]
	v_mfma_f32_16x16x32_bf16 v[2:5], v[154:157], v[208:211], v[2:5]
	v_mfma_f32_16x16x32_bf16 v[54:57], v[150:153], v[188:191], v[54:57]
	v_mfma_f32_16x16x32_bf16 v[50:53], v[158:161], v[188:191], v[50:53]
	v_mfma_f32_16x16x32_bf16 v[38:41], v[150:153], v[196:199], v[38:41]
	v_mfma_f32_16x16x32_bf16 v[34:37], v[158:161], v[196:199], v[34:37]
	v_mfma_f32_16x16x32_bf16 v[22:25], v[150:153], v[204:207], v[22:25]
	v_mfma_f32_16x16x32_bf16 v[18:21], v[158:161], v[204:207], v[18:21]
	s_barrier
	s_setprio 2
	v_mfma_f32_16x16x32_bf16 v[6:9], v[150:153], v[212:215], v[6:9]
	v_mfma_f32_16x16x32_bf16 v[2:5], v[158:161], v[212:215], v[2:5]
	s_setprio 0
	s_add_i32 s41, 0, 0x18000
	s_add_i32 s62, 0, 0x1c000
	v_add_u32_e32 v142, s41, v1
	v_add_u32_e32 v158, s62, v1
	ds_read_b128 v[130:133], v142
	ds_read_b128 v[134:137], v142 offset:1024
	ds_read_b128 v[138:141], v142 offset:2048
	ds_read_b128 v[142:145], v142 offset:3072
	ds_read_b128 v[146:149], v158
	ds_read_b128 v[150:153], v158 offset:1024
	ds_read_b128 v[154:157], v158 offset:2048
	ds_read_b128 v[158:161], v158 offset:3072
	s_mov_b32 m0, s59
	v_lshl_add_u64 v[218:219], v[216:217], 0, s[14:15]
	ds_read_b128 v[184:187], v177 offset:32768
	ds_read_b128 v[188:191], v177 offset:33792
	ds_read_b128 v[192:195], v177 offset:34816
	ds_read_b128 v[196:199], v177 offset:35840
	ds_read_b128 v[200:203], v177 offset:36864
	ds_read_b128 v[204:207], v177 offset:37888
	ds_read_b128 v[208:211], v177 offset:38912
	ds_read_b128 v[212:215], v177 offset:39936
	global_load_lds_dwordx4 v[218:219], off
	v_lshl_add_u64 v[218:219], v[216:217], 0, s[16:17]
	s_mov_b32 m0, s60
	s_nop 0
	global_load_lds_dwordx4 v[218:219], off
	s_waitcnt vmcnt(8)
	s_waitcnt lgkmcnt(0)
	s_barrier
	s_setprio 1
	s_waitcnt lgkmcnt(0)
	v_mfma_f32_16x16x32_bf16 v[126:129], v[130:133], v[184:187], v[126:129]
	v_mfma_f32_16x16x32_bf16 v[122:125], v[138:141], v[184:187], v[122:125]
	v_mfma_f32_16x16x32_bf16 v[110:113], v[130:133], v[192:195], v[110:113]
	v_mfma_f32_16x16x32_bf16 v[106:109], v[138:141], v[192:195], v[106:109]
	v_mfma_f32_16x16x32_bf16 v[94:97], v[130:133], v[200:203], v[94:97]
	v_mfma_f32_16x16x32_bf16 v[90:93], v[138:141], v[200:203], v[90:93]
	v_mfma_f32_16x16x32_bf16 v[78:81], v[130:133], v[208:211], v[78:81]
	v_mfma_f32_16x16x32_bf16 v[74:77], v[138:141], v[208:211], v[74:77]
	v_mfma_f32_16x16x32_bf16 v[126:129], v[134:137], v[188:191], v[126:129]
	v_mfma_f32_16x16x32_bf16 v[122:125], v[142:145], v[188:191], v[122:125]
	v_mfma_f32_16x16x32_bf16 v[110:113], v[134:137], v[196:199], v[110:113]
	v_mfma_f32_16x16x32_bf16 v[106:109], v[142:145], v[196:199], v[106:109]
	v_mfma_f32_16x16x32_bf16 v[94:97], v[134:137], v[204:207], v[94:97]
	v_mfma_f32_16x16x32_bf16 v[90:93], v[142:145], v[204:207], v[90:93]
	v_mfma_f32_16x16x32_bf16 v[78:81], v[134:137], v[212:215], v[78:81]
	v_mfma_f32_16x16x32_bf16 v[74:77], v[142:145], v[212:215], v[74:77]
	v_mfma_f32_16x16x32_bf16 v[118:121], v[146:149], v[184:187], v[118:121]
	v_mfma_f32_16x16x32_bf16 v[114:117], v[154:157], v[184:187], v[114:117]
	v_mfma_f32_16x16x32_bf16 v[102:105], v[146:149], v[192:195], v[102:105]
	v_mfma_f32_16x16x32_bf16 v[98:101], v[154:157], v[192:195], v[98:101]
	v_mfma_f32_16x16x32_bf16 v[86:89], v[146:149], v[200:203], v[86:89]
	v_mfma_f32_16x16x32_bf16 v[82:85], v[154:157], v[200:203], v[82:85]
	v_mfma_f32_16x16x32_bf16 v[70:73], v[146:149], v[208:211], v[70:73]
	v_mfma_f32_16x16x32_bf16 v[66:69], v[154:157], v[208:211], v[66:69]
	v_mfma_f32_16x16x32_bf16 v[118:121], v[150:153], v[188:191], v[118:121]
	v_mfma_f32_16x16x32_bf16 v[114:117], v[158:161], v[188:191], v[114:117]
	s_barrier
; #define PG8_STAGE(bufoff, gbase, voff) do { if constexpr (!pg8_noload<Epi>::value) { _Pragma("unroll") for (int _i = 0; _i < 2; ++_i) \
;         __builtin_amdgcn_global_load_lds((const unsigned*)((const char*)(gbase) + (size_t)_i * pstep + (voff)[0]), (PG8_LAS unsigned*)(lds + (bufoff) + ldsw + _i * 8192), 16, 0, 0); } } while (0)
; #define PG8_LDA(dst, b, h) do { _Pragma("unroll") for (int m = 0; m < 4; ++m) _Pragma("unroll") for (int k = 0; k < 2; ++k) dst[m][k] = *(const PG8_LAS bf16x8*)(lds + PG8_SA(b, h) + aoff + m * 2048 + k * 1024); } while (0)
; #define PG8_MMA(ai, bj, At, Bt) do { __builtin_amdgcn_s_setprio(1); _Pragma("unroll") for (int m = 0; m < 4; ++m) _Pragma("unroll") for (int n = 0; n < 2; ++n) _Pragma("unroll") for (int k = 0; k < 2; ++k) \
;         acc[ai][bj][m][n] = __builtin_amdgcn_mfma_f32_16x16x32_bf16(Bt[n][k], At[m][k], acc[ai][bj][m][n], 0, 0, 0); __builtin_amdgcn_s_setprio(0); } while (0)
; #define PG8_WAIT_V(n) asm volatile("s_waitcnt vmcnt(" #n ")" ::: "memory")
; #define PG8_WAIT_L(n) asm volatile("s_waitcnt lgkmcnt(" #n ")" ::: "memory")
; #define PG8_BAR __builtin_amdgcn_s_barrier()
; #define PG8_SCHED __builtin_amdgcn_sched_barrier(0)
; template <class Epi, class Sched, bool ALIGN_EPI = false, bool SP2 = false, bool ABLK = false>
; __device__ __forceinline__ void gemm_phase(PG8_LAS unsigned char* lds, const Gemm g, const Sched& S, const Epi& E) {
;     ...
;             PG8_WAIT_V(8); PG8_WAIT_L(0); PG8_BAR; PG8_MMA(0, 0, At, B0); PG8_MMA(0, 1, At, B1); PG8_BAR; PG8_SCHED;
;             PG8_LDA(At, 1, 1); PG8_STAGE(PG8_SB(1, 0), b3, voffB); PG8_STAGE(PG8_SB(1, 1), b3 + hstep, voffB); PG8_STAGE(PG8_SA(1, 0), a3, voffA);
;             PG8_WAIT_V(8); PG8_WAIT_L(0); PG8_BAR; PG8_MMA(1, 0, At, B0); PG8_MMA(1, 1, At, B1); PG8_BAR; PG8_SCHED;
	s_setprio 2
	v_mfma_f32_16x16x32_bf16 v[102:105], v[150:153], v[196:199], v[102:105]
	v_mfma_f32_16x16x32_bf16 v[98:101], v[158:161], v[196:199], v[98:101]
	v_mfma_f32_16x16x32_bf16 v[86:89], v[150:153], v[204:207], v[86:89]
	v_mfma_f32_16x16x32_bf16 v[82:85], v[158:161], v[204:207], v[82:85]
	v_mfma_f32_16x16x32_bf16 v[70:73], v[150:153], v[212:215], v[70:73]
	v_mfma_f32_16x16x32_bf16 v[66:69], v[158:161], v[212:215], v[66:69]
	s_setprio 0
	s_add_i32 s41, s41, s57
	v_lshl_add_u64 v[218:219], v[170:171], 0, s[24:25]
	s_mov_b32 m0, s41
	ds_read_b128 v[184:187], v177 offset:49152
	ds_read_b128 v[188:191], v177 offset:50176
	ds_read_b128 v[192:195], v177 offset:51200
	ds_read_b128 v[196:199], v177 offset:52224
	ds_read_b128 v[200:203], v177 offset:53248
	ds_read_b128 v[204:207], v177 offset:54272
	ds_read_b128 v[208:211], v177 offset:55296
	ds_read_b128 v[212:215], v177 offset:56320
	global_load_lds_dwordx4 v[218:219], off
	v_lshl_add_u64 v[218:219], v[170:171], 0, s[26:27]
	s_add_i32 m0, s41, 0x2000
	s_add_i32 s41, s62, s57
	global_load_lds_dwordx4 v[218:219], off
	v_lshl_add_u64 v[218:219], v[170:171], 0, s[28:29]
	s_mov_b32 m0, s41
	v_lshl_add_u64 v[170:171], v[170:171], 0, s[30:31]
	global_load_lds_dwordx4 v[218:219], off
	s_add_i32 m0, s41, 0x2000
	s_nop 0
	global_load_lds_dwordx4 v[170:171], off
	v_lshl_add_u64 v[170:171], v[216:217], 0, s[24:25]
	s_mov_b32 m0, s65
	s_nop 0
	global_load_lds_dwordx4 v[170:171], off
	v_lshl_add_u64 v[170:171], v[216:217], 0, s[26:27]
	s_mov_b32 m0, s66
	s_nop 0
	global_load_lds_dwordx4 v[170:171], off
	s_waitcnt vmcnt(8)
	s_waitcnt lgkmcnt(0)
	s_barrier
	s_setprio 1
	s_waitcnt lgkmcnt(0)
	v_mfma_f32_16x16x32_bf16 v[62:65], v[130:133], v[184:187], v[62:65]
	v_mfma_f32_16x16x32_bf16 v[58:61], v[138:141], v[184:187], v[58:61]
	v_mfma_f32_16x16x32_bf16 v[46:49], v[130:133], v[192:195], v[46:49]
	v_mfma_f32_16x16x32_bf16 v[42:45], v[138:141], v[192:195], v[42:45]
	v_mfma_f32_16x16x32_bf16 v[30:33], v[130:133], v[200:203], v[30:33]
	v_mfma_f32_16x16x32_bf16 v[26:29], v[138:141], v[200:203], v[26:29]
	v_mfma_f32_16x16x32_bf16 v[14:17], v[130:133], v[208:211], v[14:17]
	v_mfma_f32_16x16x32_bf16 v[10:13], v[138:141], v[208:211], v[10:13]
	v_mfma_f32_16x16x32_bf16 v[62:65], v[134:137], v[188:191], v[62:65]
	v_mfma_f32_16x16x32_bf16 v[58:61], v[142:145], v[188:191], v[58:61]
	v_mfma_f32_16x16x32_bf16 v[46:49], v[134:137], v[196:199], v[46:49]
	v_mfma_f32_16x16x32_bf16 v[42:45], v[142:145], v[196:199], v[42:45]
	v_mfma_f32_16x16x32_bf16 v[30:33], v[134:137], v[204:207], v[30:33]
	v_mfma_f32_16x16x32_bf16 v[26:29], v[142:145], v[204:207], v[26:29]
	v_mfma_f32_16x16x32_bf16 v[14:17], v[134:137], v[212:215], v[14:17]
	v_mfma_f32_16x16x32_bf16 v[10:13], v[142:145], v[212:215], v[10:13]
	v_mfma_f32_16x16x32_bf16 v[54:57], v[146:149], v[184:187], v[54:57]
	v_mfma_f32_16x16x32_bf16 v[50:53], v[154:157], v[184:187], v[50:53]
	v_mfma_f32_16x16x32_bf16 v[38:41], v[146:149], v[192:195], v[38:41]
	v_mfma_f32_16x16x32_bf16 v[34:37], v[154:157], v[192:195], v[34:37]
	v_mfma_f32_16x16x32_bf16 v[22:25], v[146:149], v[200:203], v[22:25]
	v_mfma_f32_16x16x32_bf16 v[18:21], v[154:157], v[200:203], v[18:21]
	v_mfma_f32_16x16x32_bf16 v[6:9], v[146:149], v[208:211], v[6:9]
	v_mfma_f32_16x16x32_bf16 v[2:5], v[154:157], v[208:211], v[2:5]
	v_mfma_f32_16x16x32_bf16 v[54:57], v[150:153], v[188:191], v[54:57]
	v_mfma_f32_16x16x32_bf16 v[50:53], v[158:161], v[188:191], v[50:53]
	v_mfma_f32_16x16x32_bf16 v[38:41], v[150:153], v[196:199], v[38:41]
	v_mfma_f32_16x16x32_bf16 v[34:37], v[158:161], v[196:199], v[34:37]
	v_mfma_f32_16x16x32_bf16 v[22:25], v[150:153], v[204:207], v[22:25]
	v_mfma_f32_16x16x32_bf16 v[18:21], v[158:161], v[204:207], v[18:21]
	s_barrier
	s_setprio 2
	v_mfma_f32_16x16x32_bf16 v[6:9], v[150:153], v[212:215], v[6:9]
	v_mfma_f32_16x16x32_bf16 v[2:5], v[158:161], v[212:215], v[2:5]
	s_setprio 0
	s_add_u32 s52, s52, 0x1000
	s_addc_u32 s53, s53, 0
	s_add_u32 s11, s11, 0x1000
	s_addc_u32 s39, s39, 0
	s_cmp_ge_i32 s43, s75
	s_mov_b32 s41, s43
	s_cbranch_scc0 .LBB0_1997
	s_and_b64 vcc, exec, s[34:35]
	s_cbranch_vccnz .LBB0_2002
	s_lshl_b32 s11, s2, 8
	s_cmp_gt_i32 s2, 63
	s_mov_b64 s[52:53], -1
	s_cbranch_scc1 .LBB0_2003

; #define PG8_STAGE(bufoff, gbase, voff) do { if constexpr (!pg8_noload<Epi>::value) { _Pragma("unroll") for (int _i = 0; _i < 2; ++_i) \
;         __builtin_amdgcn_global_load_lds((const unsigned*)((const char*)(gbase) + (size_t)_i * pstep + (voff)[0]), (PG8_LAS unsigned*)(lds + (bufoff) + ldsw + _i * 8192), 16, 0, 0); } } while (0)
; #define PG8_LDA(dst, b, h) do { _Pragma("unroll") for (int m = 0; m < 4; ++m) _Pragma("unroll") for (int k = 0; k < 2; ++k) dst[m][k] = *(const PG8_LAS bf16x8*)(lds + PG8_SA(b, h) + aoff + m * 2048 + k * 1024); } while (0)
; #define PG8_LDB(dst, b, h) do { _Pragma("unroll") for (int n = 0; n < 2; ++n) _Pragma("unroll") for (int k = 0; k < 2; ++k) dst[n][k] = *(const PG8_LAS bf16x8*)(lds + PG8_SB(b, h) + boff + n * 2048 + k * 1024); } while (0)
; #define PG8_MMA(ai, bj, At, Bt) do { __builtin_amdgcn_s_setprio(1); _Pragma("unroll") for (int m = 0; m < 4; ++m) _Pragma("unroll") for (int n = 0; n < 2; ++n) _Pragma("unroll") for (int k = 0; k < 2; ++k) \
;         acc[ai][bj][m][n] = __builtin_amdgcn_mfma_f32_16x16x32_bf16(Bt[n][k], At[m][k], acc[ai][bj][m][n], 0, 0, 0); __builtin_amdgcn_s_setprio(0); } while (0)
; #define PG8_WAIT_V(n) asm volatile("s_waitcnt vmcnt(" #n ")" ::: "memory")
; #define PG8_WAIT_L(n) asm volatile("s_waitcnt lgkmcnt(" #n ")" ::: "memory")
; #define PG8_BAR __builtin_amdgcn_s_barrier()
; #define PG8_SCHED __builtin_amdgcn_sched_barrier(0)
; template <class Epi, class Sched, bool ALIGN_EPI = false, bool SP2 = false, bool ABLK = false>
; __device__ __forceinline__ void gemm_phase(PG8_LAS unsigned char* lds, const Gemm g, const Sched& S, const Epi& E) {
;     ...
;             PG8_LDB(B0, 0, 0); PG8_LDB(B1, 0, 1); PG8_SCHED; PG8_LDA(At, 0, 0); PG8_STAGE(PG8_SA(1, 1), a1 + hstep, voffA);
;             PG8_WAIT_V(8); PG8_WAIT_L(0); PG8_BAR; PG8_MMA(0, 0, At, B0); PG8_MMA(0, 1, At, B1); PG8_BAR; PG8_SCHED;
;             PG8_LDA(At, 0, 1); PG8_STAGE(PG8_SB(0, 0), b2, voffB); PG8_STAGE(PG8_SB(0, 1), b2 + hstep, voffB); PG8_STAGE(PG8_SA(0, 0), a2, voffA);
;             PG8_WAIT_V(8); PG8_WAIT_L(0); PG8_BAR; PG8_MMA(1, 0, At, B0); PG8_MMA(1, 1, At, B1); PG8_BAR; PG8_SCHED;
.LBB0_2119:
	s_or_b32 s30, s59, 1
	s_lshl_b64 s[14:15], s[30:31], 11
	s_add_u32 s14, s82, s14
	v_add_u32_e32 v133, s71, v148
	s_addc_u32 s15, s83, s15
	s_add_i32 s30, s59, 2
	ds_read_b128 v[144:147], v133
	ds_read_b128 v[184:187], v133 offset:1024
	ds_read_b128 v[188:191], v133 offset:2048
	ds_read_b128 v[192:195], v133 offset:3072
	v_add_u32_e32 v133, s73, v148
	s_lshl_b64 s[34:35], s[30:31], 11
	ds_read_b128 v[196:199], v133
	ds_read_b128 v[200:203], v133 offset:1024
	ds_read_b128 v[204:207], v133 offset:2048
	ds_read_b128 v[208:211], v133 offset:3072
	s_add_u32 s96, s82, s34
	s_addc_u32 s97, s83, s35
	s_and_b64 s[94:95], s[92:93], exec
	s_cselect_b32 s95, s97, s77
	s_cselect_b32 s94, s96, s28
	s_add_u32 s96, s88, s34
	s_addc_u32 s97, s89, s35
	s_and_b64 s[34:35], s[92:93], exec
	s_cselect_b32 s35, s97, s29
	s_cselect_b32 s34, s96, s75
	v_lshl_add_u64 v[180:181], s[14:15], 0, v[130:131]
	v_lshl_add_u64 v[244:245], v[180:181], 0, s[24:25]
	s_add_i32 m0, s17, 0xc000
	ds_read_b128 v[212:215], v168
	ds_read_b128 v[216:219], v168 offset:1024
	ds_read_b128 v[220:223], v168 offset:2048
	ds_read_b128 v[224:227], v168 offset:3072
	ds_read_b128 v[228:231], v168 offset:4096
	ds_read_b128 v[232:235], v168 offset:5120
	ds_read_b128 v[236:239], v168 offset:6144
	ds_read_b128 v[240:243], v168 offset:7168
	global_load_lds_dwordx4 v[244:245], off
	v_lshl_add_u64 v[180:181], v[180:181], 0, s[26:27]
	s_add_i32 m0, s17, 0xe000
	s_nop 0
	global_load_lds_dwordx4 v[180:181], off
	s_waitcnt vmcnt(8)
	s_waitcnt lgkmcnt(0)
	s_barrier
	s_setprio 1
	s_waitcnt lgkmcnt(0)
	v_mfma_f32_16x16x32_bf16 v[126:129], v[144:147], v[212:215], v[126:129]
	v_mfma_f32_16x16x32_bf16 v[122:125], v[188:191], v[212:215], v[122:125]
	v_mfma_f32_16x16x32_bf16 v[110:113], v[144:147], v[220:223], v[110:113]
	v_mfma_f32_16x16x32_bf16 v[106:109], v[188:191], v[220:223], v[106:109]
	v_mfma_f32_16x16x32_bf16 v[94:97], v[144:147], v[228:231], v[94:97]
	v_mfma_f32_16x16x32_bf16 v[90:93], v[188:191], v[228:231], v[90:93]
	v_mfma_f32_16x16x32_bf16 v[78:81], v[144:147], v[236:239], v[78:81]
	v_mfma_f32_16x16x32_bf16 v[74:77], v[188:191], v[236:239], v[74:77]
	v_mfma_f32_16x16x32_bf16 v[126:129], v[184:187], v[216:219], v[126:129]
	v_mfma_f32_16x16x32_bf16 v[122:125], v[192:195], v[216:219], v[122:125]
	v_mfma_f32_16x16x32_bf16 v[110:113], v[184:187], v[224:227], v[110:113]
	v_mfma_f32_16x16x32_bf16 v[106:109], v[192:195], v[224:227], v[106:109]
	v_mfma_f32_16x16x32_bf16 v[94:97], v[184:187], v[232:235], v[94:97]
	v_mfma_f32_16x16x32_bf16 v[90:93], v[192:195], v[232:235], v[90:93]
	v_mfma_f32_16x16x32_bf16 v[78:81], v[184:187], v[240:243], v[78:81]
	v_mfma_f32_16x16x32_bf16 v[74:77], v[192:195], v[240:243], v[74:77]
	v_mfma_f32_16x16x32_bf16 v[118:121], v[196:199], v[212:215], v[118:121]
	v_mfma_f32_16x16x32_bf16 v[114:117], v[204:207], v[212:215], v[114:117]
	v_mfma_f32_16x16x32_bf16 v[102:105], v[196:199], v[220:223], v[102:105]
	v_mfma_f32_16x16x32_bf16 v[98:101], v[204:207], v[220:223], v[98:101]
	v_mfma_f32_16x16x32_bf16 v[86:89], v[196:199], v[228:231], v[86:89]
	v_mfma_f32_16x16x32_bf16 v[82:85], v[204:207], v[228:231], v[82:85]
	v_mfma_f32_16x16x32_bf16 v[70:73], v[196:199], v[236:239], v[70:73]
	v_mfma_f32_16x16x32_bf16 v[66:69], v[204:207], v[236:239], v[66:69]
	v_mfma_f32_16x16x32_bf16 v[118:121], v[200:203], v[216:219], v[118:121]
	v_mfma_f32_16x16x32_bf16 v[114:117], v[208:211], v[216:219], v[114:117]
	s_barrier
	s_setprio 2
	v_mfma_f32_16x16x32_bf16 v[102:105], v[200:203], v[224:227], v[102:105]
	v_mfma_f32_16x16x32_bf16 v[98:101], v[208:211], v[224:227], v[98:101]
	v_mfma_f32_16x16x32_bf16 v[86:89], v[200:203], v[232:235], v[86:89]
	v_mfma_f32_16x16x32_bf16 v[82:85], v[208:211], v[232:235], v[82:85]
	v_mfma_f32_16x16x32_bf16 v[70:73], v[200:203], v[240:243], v[70:73]
	v_mfma_f32_16x16x32_bf16 v[66:69], v[208:211], v[240:243], v[66:69]
	s_setprio 0
	s_add_i32 s14, s71, s3
	v_lshl_add_u64 v[180:181], s[34:35], 0, v[130:131]
	s_mov_b32 m0, s14
	ds_read_b128 v[212:215], v168 offset:16384
	ds_read_b128 v[216:219], v168 offset:17408
	ds_read_b128 v[220:223], v168 offset:18432
	ds_read_b128 v[224:227], v168 offset:19456
	ds_read_b128 v[228:231], v168 offset:20480
	ds_read_b128 v[232:235], v168 offset:21504
	ds_read_b128 v[236:239], v168 offset:22528
	ds_read_b128 v[240:243], v168 offset:23552
	global_load_lds_dwordx4 v[180:181], off
	v_lshl_add_u64 v[244:245], v[180:181], 0, s[22:23]
	s_add_i32 m0, s14, 0x2000
	s_add_i32 s14, s73, s3
	global_load_lds_dwordx4 v[244:245], off
	v_lshl_add_u64 v[244:245], v[180:181], 0, s[24:25]
	s_mov_b32 m0, s14
	s_nop 0
	global_load_lds_dwordx4 v[244:245], off
	v_lshl_add_u64 v[244:245], v[180:181], 0, s[26:27]
	s_add_i32 m0, s14, 0x2000
	s_nop 0
	global_load_lds_dwordx4 v[244:245], off
	v_lshl_add_u64 v[244:245], s[94:95], 0, v[130:131]
	s_mov_b32 m0, s17
	v_lshl_add_u64 v[246:247], v[244:245], 0, s[22:23]
	global_load_lds_dwordx4 v[244:245], off
	s_mov_b32 m0, s56
	s_nop 0
	global_load_lds_dwordx4 v[246:247], off
	s_waitcnt vmcnt(8)
	s_waitcnt lgkmcnt(0)
	s_barrier
; #define PG8_STAGE(bufoff, gbase, voff) do { if constexpr (!pg8_noload<Epi>::value) { _Pragma("unroll") for (int _i = 0; _i < 2; ++_i) \
;         __builtin_amdgcn_global_load_lds((const unsigned*)((const char*)(gbase) + (size_t)_i * pstep + (voff)[0]), (PG8_LAS unsigned*)(lds + (bufoff) + ldsw + _i * 8192), 16, 0, 0); } } while (0)
; #define PG8_LDA(dst, b, h) do { _Pragma("unroll") for (int m = 0; m < 4; ++m) _Pragma("unroll") for (int k = 0; k < 2; ++k) dst[m][k] = *(const PG8_LAS bf16x8*)(lds + PG8_SA(b, h) + aoff + m * 2048 + k * 1024); } while (0)
; #define PG8_LDB(dst, b, h) do { _Pragma("unroll") for (int n = 0; n < 2; ++n) _Pragma("unroll") for (int k = 0; k < 2; ++k) dst[n][k] = *(const PG8_LAS bf16x8*)(lds + PG8_SB(b, h) + boff + n * 2048 + k * 1024); } while (0)
; #define PG8_MMA(ai, bj, At, Bt) do { __builtin_amdgcn_s_setprio(1); _Pragma("unroll") for (int m = 0; m < 4; ++m) _Pragma("unroll") for (int n = 0; n < 2; ++n) _Pragma("unroll") for (int k = 0; k < 2; ++k) \
;         acc[ai][bj][m][n] = __builtin_amdgcn_mfma_f32_16x16x32_bf16(Bt[n][k], At[m][k], acc[ai][bj][m][n], 0, 0, 0); __builtin_amdgcn_s_setprio(0); } while (0)
; #define PG8_WAIT_V(n) asm volatile("s_waitcnt vmcnt(" #n ")" ::: "memory")
; #define PG8_WAIT_L(n) asm volatile("s_waitcnt lgkmcnt(" #n ")" ::: "memory")
; #define PG8_BAR __builtin_amdgcn_s_barrier()
; #define PG8_SCHED __builtin_amdgcn_sched_barrier(0)
; template <class Epi, class Sched, bool ALIGN_EPI = false, bool SP2 = false, bool ABLK = false>
; __device__ __forceinline__ void gemm_phase(PG8_LAS unsigned char* lds, const Gemm g, const Sched& S, const Epi& E) {
;     ...
;             PG8_WAIT_V(8); PG8_WAIT_L(0); PG8_BAR; PG8_MMA(1, 0, At, B0); PG8_MMA(1, 1, At, B1); PG8_BAR; PG8_SCHED;
;             PG8_LDB(B0, 1, 0); PG8_LDB(B1, 1, 1); PG8_SCHED; PG8_LDA(At, 1, 0); PG8_STAGE(PG8_SA(0, 1), a2 + hstep, voffA);
;             PG8_WAIT_V(8); PG8_WAIT_L(0); PG8_BAR; PG8_MMA(0, 0, At, B0); PG8_MMA(0, 1, At, B1); PG8_BAR; PG8_SCHED;
	s_setprio 1
	s_waitcnt lgkmcnt(0)
	v_mfma_f32_16x16x32_bf16 v[62:65], v[144:147], v[212:215], v[62:65]
	v_mfma_f32_16x16x32_bf16 v[58:61], v[188:191], v[212:215], v[58:61]
	v_mfma_f32_16x16x32_bf16 v[46:49], v[144:147], v[220:223], v[46:49]
	v_mfma_f32_16x16x32_bf16 v[42:45], v[188:191], v[220:223], v[42:45]
	v_mfma_f32_16x16x32_bf16 v[30:33], v[144:147], v[228:231], v[30:33]
	v_mfma_f32_16x16x32_bf16 v[26:29], v[188:191], v[228:231], v[26:29]
	v_mfma_f32_16x16x32_bf16 v[14:17], v[144:147], v[236:239], v[14:17]
	v_mfma_f32_16x16x32_bf16 v[10:13], v[188:191], v[236:239], v[10:13]
	v_mfma_f32_16x16x32_bf16 v[62:65], v[184:187], v[216:219], v[62:65]
	v_mfma_f32_16x16x32_bf16 v[58:61], v[192:195], v[216:219], v[58:61]
	v_mfma_f32_16x16x32_bf16 v[46:49], v[184:187], v[224:227], v[46:49]
	v_mfma_f32_16x16x32_bf16 v[42:45], v[192:195], v[224:227], v[42:45]
	v_mfma_f32_16x16x32_bf16 v[30:33], v[184:187], v[232:235], v[30:33]
	v_mfma_f32_16x16x32_bf16 v[26:29], v[192:195], v[232:235], v[26:29]
	v_mfma_f32_16x16x32_bf16 v[14:17], v[184:187], v[240:243], v[14:17]
	v_mfma_f32_16x16x32_bf16 v[10:13], v[192:195], v[240:243], v[10:13]
	v_mfma_f32_16x16x32_bf16 v[54:57], v[196:199], v[212:215], v[54:57]
	v_mfma_f32_16x16x32_bf16 v[50:53], v[204:207], v[212:215], v[50:53]
	v_mfma_f32_16x16x32_bf16 v[38:41], v[196:199], v[220:223], v[38:41]
	v_mfma_f32_16x16x32_bf16 v[34:37], v[204:207], v[220:223], v[34:37]
	v_mfma_f32_16x16x32_bf16 v[22:25], v[196:199], v[228:231], v[22:25]
	v_mfma_f32_16x16x32_bf16 v[18:21], v[204:207], v[228:231], v[18:21]
	v_mfma_f32_16x16x32_bf16 v[6:9], v[196:199], v[236:239], v[6:9]
	v_mfma_f32_16x16x32_bf16 v[2:5], v[204:207], v[236:239], v[2:5]
	v_mfma_f32_16x16x32_bf16 v[54:57], v[200:203], v[216:219], v[54:57]
	v_mfma_f32_16x16x32_bf16 v[50:53], v[208:211], v[216:219], v[50:53]
	v_mfma_f32_16x16x32_bf16 v[38:41], v[200:203], v[224:227], v[38:41]
	v_mfma_f32_16x16x32_bf16 v[34:37], v[208:211], v[224:227], v[34:37]
	v_mfma_f32_16x16x32_bf16 v[22:25], v[200:203], v[232:235], v[22:25]
	v_mfma_f32_16x16x32_bf16 v[18:21], v[208:211], v[232:235], v[18:21]
	s_barrier
	s_setprio 2
	v_mfma_f32_16x16x32_bf16 v[6:9], v[200:203], v[240:243], v[6:9]
	v_mfma_f32_16x16x32_bf16 v[2:5], v[208:211], v[240:243], v[2:5]
	s_setprio 0
	s_add_i32 s14, 0, 0x18000
	v_add_u32_e32 v133, s14, v148
	s_add_i32 s15, 0, 0x1c000
	ds_read_b128 v[144:147], v133
	ds_read_b128 v[184:187], v133 offset:1024
	ds_read_b128 v[188:191], v133 offset:2048
	ds_read_b128 v[192:195], v133 offset:3072
	v_add_u32_e32 v133, s15, v148
	ds_read_b128 v[196:199], v133
	ds_read_b128 v[200:203], v133 offset:1024
	ds_read_b128 v[204:207], v133 offset:2048
	ds_read_b128 v[208:211], v133 offset:3072
	s_mov_b32 m0, s57
	v_lshl_add_u64 v[246:247], v[244:245], 0, s[24:25]
	ds_read_b128 v[212:215], v168 offset:32768
	ds_read_b128 v[216:219], v168 offset:33792
	ds_read_b128 v[220:223], v168 offset:34816
	ds_read_b128 v[224:227], v168 offset:35840
	ds_read_b128 v[228:231], v168 offset:36864
	ds_read_b128 v[232:235], v168 offset:37888
	ds_read_b128 v[236:239], v168 offset:38912
	ds_read_b128 v[240:243], v168 offset:39936
	global_load_lds_dwordx4 v[246:247], off
	v_lshl_add_u64 v[246:247], v[244:245], 0, s[26:27]
	s_mov_b32 m0, s58
	s_nop 0
	global_load_lds_dwordx4 v[246:247], off
	s_waitcnt vmcnt(8)
	s_waitcnt lgkmcnt(0)
	s_barrier
	s_setprio 1
	s_waitcnt lgkmcnt(0)
	v_mfma_f32_16x16x32_bf16 v[126:129], v[144:147], v[212:215], v[126:129]
	v_mfma_f32_16x16x32_bf16 v[122:125], v[188:191], v[212:215], v[122:125]
	v_mfma_f32_16x16x32_bf16 v[110:113], v[144:147], v[220:223], v[110:113]
	v_mfma_f32_16x16x32_bf16 v[106:109], v[188:191], v[220:223], v[106:109]
	v_mfma_f32_16x16x32_bf16 v[94:97], v[144:147], v[228:231], v[94:97]
	v_mfma_f32_16x16x32_bf16 v[90:93], v[188:191], v[228:231], v[90:93]
	v_mfma_f32_16x16x32_bf16 v[78:81], v[144:147], v[236:239], v[78:81]
	v_mfma_f32_16x16x32_bf16 v[74:77], v[188:191], v[236:239], v[74:77]
	v_mfma_f32_16x16x32_bf16 v[126:129], v[184:187], v[216:219], v[126:129]
	v_mfma_f32_16x16x32_bf16 v[122:125], v[192:195], v[216:219], v[122:125]
	v_mfma_f32_16x16x32_bf16 v[110:113], v[184:187], v[224:227], v[110:113]
	v_mfma_f32_16x16x32_bf16 v[106:109], v[192:195], v[224:227], v[106:109]
	v_mfma_f32_16x16x32_bf16 v[94:97], v[184:187], v[232:235], v[94:97]
	v_mfma_f32_16x16x32_bf16 v[90:93], v[192:195], v[232:235], v[90:93]
	v_mfma_f32_16x16x32_bf16 v[78:81], v[184:187], v[240:243], v[78:81]
	v_mfma_f32_16x16x32_bf16 v[74:77], v[192:195], v[240:243], v[74:77]
	v_mfma_f32_16x16x32_bf16 v[118:121], v[196:199], v[212:215], v[118:121]
	v_mfma_f32_16x16x32_bf16 v[114:117], v[204:207], v[212:215], v[114:117]
	v_mfma_f32_16x16x32_bf16 v[102:105], v[196:199], v[220:223], v[102:105]
	v_mfma_f32_16x16x32_bf16 v[98:101], v[204:207], v[220:223], v[98:101]
	v_mfma_f32_16x16x32_bf16 v[86:89], v[196:199], v[228:231], v[86:89]
	v_mfma_f32_16x16x32_bf16 v[82:85], v[204:207], v[228:231], v[82:85]
	v_mfma_f32_16x16x32_bf16 v[70:73], v[196:199], v[236:239], v[70:73]
	v_mfma_f32_16x16x32_bf16 v[66:69], v[204:207], v[236:239], v[66:69]
	v_mfma_f32_16x16x32_bf16 v[118:121], v[200:203], v[216:219], v[118:121]
	v_mfma_f32_16x16x32_bf16 v[114:117], v[208:211], v[216:219], v[114:117]
	s_barrier
; #define PG8_STAGE(bufoff, gbase, voff) do { if constexpr (!pg8_noload<Epi>::value) { _Pragma("unroll") for (int _i = 0; _i < 2; ++_i) \
;         __builtin_amdgcn_global_load_lds((const unsigned*)((const char*)(gbase) + (size_t)_i * pstep + (voff)[0]), (PG8_LAS unsigned*)(lds + (bufoff) + ldsw + _i * 8192), 16, 0, 0); } } while (0)
; #define PG8_LDA(dst, b, h) do { _Pragma("unroll") for (int m = 0; m < 4; ++m) _Pragma("unroll") for (int k = 0; k < 2; ++k) dst[m][k] = *(const PG8_LAS bf16x8*)(lds + PG8_SA(b, h) + aoff + m * 2048 + k * 1024); } while (0)
; #define PG8_LDB(dst, b, h) do { _Pragma("unroll") for (int n = 0; n < 2; ++n) _Pragma("unroll") for (int k = 0; k < 2; ++k) dst[n][k] = *(const PG8_LAS bf16x8*)(lds + PG8_SB(b, h) + boff + n * 2048 + k * 1024); } while (0)
; #define PG8_MMA(ai, bj, At, Bt) do { __builtin_amdgcn_s_setprio(1); _Pragma("unroll") for (int m = 0; m < 4; ++m) _Pragma("unroll") for (int n = 0; n < 2; ++n) _Pragma("unroll") for (int k = 0; k < 2; ++k) \
;         acc[ai][bj][m][n] = __builtin_amdgcn_mfma_f32_16x16x32_bf16(Bt[n][k], At[m][k], acc[ai][bj][m][n], 0, 0, 0); __builtin_amdgcn_s_setprio(0); } while (0)
; template <class Epi, class Sched, bool ALIGN_EPI = false, bool SP2 = false, bool ABLK = false>
; __device__ __forceinline__ void gemm_phase(PG8_LAS unsigned char* lds, const Gemm g, const Sched& S, const Epi& E) {
;     ...
;             PG8_LDB(B0, 0, 0); PG8_LDB(B1, 0, 1); PG8_SCHED; PG8_LDA(At, 0, 0); PG8_STAGE(PG8_SA(1, 1), a1 + hstep, voffA);
;             PG8_WAIT_V(8); PG8_WAIT_L(0); PG8_BAR; PG8_MMA(0, 0, At, B0); PG8_MMA(0, 1, At, B1); PG8_BAR; PG8_SCHED;
;             PG8_LDA(At, 0, 1); PG8_STAGE(PG8_SB(0, 0), b2, voffB); PG8_STAGE(PG8_SB(0, 1), b2 + hstep, voffB); PG8_STAGE(PG8_SA(0, 0), a2, voffA);
;             PG8_WAIT_V(8); PG8_WAIT_L(0); PG8_BAR; PG8_MMA(1, 0, At, B0); PG8_MMA(1, 1, At, B1); PG8_BAR; PG8_SCHED;
;             PG8_LDB(B0, 1, 0); PG8_LDB(B1, 1, 1); PG8_SCHED; PG8_LDA(At, 1, 0); PG8_STAGE(PG8_SA(0, 1), a2 + hstep, voffA);
;             PG8_WAIT_V(8); PG8_WAIT_L(0); PG8_BAR; PG8_MMA(0, 0, At, B0); PG8_MMA(0, 1, At, B1); PG8_BAR; PG8_SCHED;
;             PG8_LDA(At, 1, 1); PG8_STAGE(PG8_SB(1, 0), b3, voffB); PG8_STAGE(PG8_SB(1, 1), b3 + hstep, voffB); PG8_STAGE(PG8_SA(1, 0), a3, voffA);
;             PG8_WAIT_V(8); PG8_WAIT_L(0); PG8_BAR; PG8_MMA(1, 0, At, B0); PG8_MMA(1, 1, At, B1); PG8_BAR; PG8_SCHED;
	s_setprio 2
	v_mfma_f32_16x16x32_bf16 v[102:105], v[200:203], v[224:227], v[102:105]
	v_mfma_f32_16x16x32_bf16 v[98:101], v[208:211], v[224:227], v[98:101]
	v_mfma_f32_16x16x32_bf16 v[86:89], v[200:203], v[232:235], v[86:89]
	v_mfma_f32_16x16x32_bf16 v[82:85], v[208:211], v[232:235], v[82:85]
	v_mfma_f32_16x16x32_bf16 v[70:73], v[200:203], v[240:243], v[70:73]
	v_mfma_f32_16x16x32_bf16 v[66:69], v[208:211], v[240:243], v[66:69]
	s_setprio 0
	s_add_i32 s14, s14, s3
	v_lshl_add_u64 v[246:247], v[180:181], 0, s[38:39]
	s_mov_b32 m0, s14
	ds_read_b128 v[212:215], v168 offset:49152
	ds_read_b128 v[216:219], v168 offset:50176
	ds_read_b128 v[220:223], v168 offset:51200
	ds_read_b128 v[224:227], v168 offset:52224
	ds_read_b128 v[228:231], v168 offset:53248
	ds_read_b128 v[232:235], v168 offset:54272
	ds_read_b128 v[236:239], v168 offset:55296
	ds_read_b128 v[240:243], v168 offset:56320
	global_load_lds_dwordx4 v[246:247], off
	v_lshl_add_u64 v[246:247], v[180:181], 0, s[40:41]
	s_add_i32 m0, s14, 0x2000
	s_add_i32 s14, s15, s3
	global_load_lds_dwordx4 v[246:247], off
	v_lshl_add_u64 v[246:247], v[180:181], 0, s[42:43]
	s_mov_b32 m0, s14
	v_lshl_add_u64 v[180:181], v[180:181], 0, s[44:45]
	global_load_lds_dwordx4 v[246:247], off
	s_add_i32 m0, s14, 0x2000
	s_nop 0
	global_load_lds_dwordx4 v[180:181], off
	v_lshl_add_u64 v[180:181], v[244:245], 0, s[38:39]
	s_mov_b32 m0, s61
	s_nop 0
	global_load_lds_dwordx4 v[180:181], off
	v_lshl_add_u64 v[180:181], v[244:245], 0, s[40:41]
	s_mov_b32 m0, s63
	s_nop 0
	global_load_lds_dwordx4 v[180:181], off
	s_waitcnt vmcnt(8)
	s_waitcnt lgkmcnt(0)
	s_barrier
	s_setprio 1
	s_waitcnt lgkmcnt(0)
	v_mfma_f32_16x16x32_bf16 v[62:65], v[144:147], v[212:215], v[62:65]
	v_mfma_f32_16x16x32_bf16 v[58:61], v[188:191], v[212:215], v[58:61]
	v_mfma_f32_16x16x32_bf16 v[46:49], v[144:147], v[220:223], v[46:49]
	v_mfma_f32_16x16x32_bf16 v[42:45], v[188:191], v[220:223], v[42:45]
	v_mfma_f32_16x16x32_bf16 v[30:33], v[144:147], v[228:231], v[30:33]
	v_mfma_f32_16x16x32_bf16 v[26:29], v[188:191], v[228:231], v[26:29]
	v_mfma_f32_16x16x32_bf16 v[14:17], v[144:147], v[236:239], v[14:17]
	v_mfma_f32_16x16x32_bf16 v[10:13], v[188:191], v[236:239], v[10:13]
	v_mfma_f32_16x16x32_bf16 v[62:65], v[184:187], v[216:219], v[62:65]
	v_mfma_f32_16x16x32_bf16 v[58:61], v[192:195], v[216:219], v[58:61]
	v_mfma_f32_16x16x32_bf16 v[46:49], v[184:187], v[224:227], v[46:49]
	v_mfma_f32_16x16x32_bf16 v[42:45], v[192:195], v[224:227], v[42:45]
	v_mfma_f32_16x16x32_bf16 v[30:33], v[184:187], v[232:235], v[30:33]
	v_mfma_f32_16x16x32_bf16 v[26:29], v[192:195], v[232:235], v[26:29]
	v_mfma_f32_16x16x32_bf16 v[14:17], v[184:187], v[240:243], v[14:17]
	v_mfma_f32_16x16x32_bf16 v[10:13], v[192:195], v[240:243], v[10:13]
	v_mfma_f32_16x16x32_bf16 v[54:57], v[196:199], v[212:215], v[54:57]
	v_mfma_f32_16x16x32_bf16 v[50:53], v[204:207], v[212:215], v[50:53]
	v_mfma_f32_16x16x32_bf16 v[38:41], v[196:199], v[220:223], v[38:41]
	v_mfma_f32_16x16x32_bf16 v[34:37], v[204:207], v[220:223], v[34:37]
	v_mfma_f32_16x16x32_bf16 v[22:25], v[196:199], v[228:231], v[22:25]
	v_mfma_f32_16x16x32_bf16 v[18:21], v[204:207], v[228:231], v[18:21]
	v_mfma_f32_16x16x32_bf16 v[6:9], v[196:199], v[236:239], v[6:9]
	v_mfma_f32_16x16x32_bf16 v[2:5], v[204:207], v[236:239], v[2:5]
	v_mfma_f32_16x16x32_bf16 v[54:57], v[200:203], v[216:219], v[54:57]
	v_mfma_f32_16x16x32_bf16 v[50:53], v[208:211], v[216:219], v[50:53]
	v_mfma_f32_16x16x32_bf16 v[38:41], v[200:203], v[224:227], v[38:41]
	v_mfma_f32_16x16x32_bf16 v[34:37], v[208:211], v[224:227], v[34:37]
	v_mfma_f32_16x16x32_bf16 v[22:25], v[200:203], v[232:235], v[22:25]
	v_mfma_f32_16x16x32_bf16 v[18:21], v[208:211], v[232:235], v[18:21]
	s_barrier
	s_setprio 2
	v_mfma_f32_16x16x32_bf16 v[6:9], v[200:203], v[240:243], v[6:9]
	v_mfma_f32_16x16x32_bf16 v[2:5], v[208:211], v[240:243], v[2:5]
	s_setprio 0
	s_cmp_gt_u32 s59, 29
	s_mov_b32 s59, s30
	s_cbranch_scc1 .LBB0_2131

; #define PG8_STAGE(bufoff, gbase, voff) do { if constexpr (!pg8_noload<Epi>::value) { _Pragma("unroll") for (int _i = 0; _i < 2; ++_i) \
;         __builtin_amdgcn_global_load_lds((const unsigned*)((const char*)(gbase) + (size_t)_i * pstep + (voff)[0]), (PG8_LAS unsigned*)(lds + (bufoff) + ldsw + _i * 8192), 16, 0, 0); } } while (0)
; #define PG8_LDA(dst, b, h) do { _Pragma("unroll") for (int m = 0; m < 4; ++m) _Pragma("unroll") for (int k = 0; k < 2; ++k) dst[m][k] = *(const PG8_LAS bf16x8*)(lds + PG8_SA(b, h) + aoff + m * 2048 + k * 1024); } while (0)
; #define PG8_LDB(dst, b, h) do { _Pragma("unroll") for (int n = 0; n < 2; ++n) _Pragma("unroll") for (int k = 0; k < 2; ++k) dst[n][k] = *(const PG8_LAS bf16x8*)(lds + PG8_SB(b, h) + boff + n * 2048 + k * 1024); } while (0)
; #define PG8_MMA(ai, bj, At, Bt) do { __builtin_amdgcn_s_setprio(1); _Pragma("unroll") for (int m = 0; m < 4; ++m) _Pragma("unroll") for (int n = 0; n < 2; ++n) _Pragma("unroll") for (int k = 0; k < 2; ++k) \
;         acc[ai][bj][m][n] = __builtin_amdgcn_mfma_f32_16x16x32_bf16(Bt[n][k], At[m][k], acc[ai][bj][m][n], 0, 0, 0); __builtin_amdgcn_s_setprio(0); } while (0)
; #define PG8_WAIT_V(n) asm volatile("s_waitcnt vmcnt(" #n ")" ::: "memory")
; #define PG8_WAIT_L(n) asm volatile("s_waitcnt lgkmcnt(" #n ")" ::: "memory")
; #define PG8_BAR __builtin_amdgcn_s_barrier()
; #define PG8_SCHED __builtin_amdgcn_sched_barrier(0)
; template <class Epi, class Sched, bool ALIGN_EPI = false, bool SP2 = false, bool ABLK = false>
; __device__ __forceinline__ void gemm_phase(PG8_LAS unsigned char* lds, const Gemm g, const Sched& S, const Epi& E) {
;     ...
;             PG8_LDB(B0, 0, 0); PG8_LDB(B1, 0, 1); PG8_SCHED; PG8_LDA(At, 0, 0); PG8_STAGE(PG8_SA(1, 1), a1 + hstep, voffA);
;             PG8_WAIT_V(8); PG8_WAIT_L(0); PG8_BAR; PG8_MMA(0, 0, At, B0); PG8_MMA(0, 1, At, B1); PG8_BAR; PG8_SCHED;
;             PG8_LDA(At, 0, 1); PG8_STAGE(PG8_SB(0, 0), b2, voffB); PG8_STAGE(PG8_SB(0, 1), b2 + hstep, voffB); PG8_STAGE(PG8_SA(0, 0), a2, voffA);
;             PG8_WAIT_V(8); PG8_WAIT_L(0); PG8_BAR; PG8_MMA(1, 0, At, B0); PG8_MMA(1, 1, At, B1); PG8_BAR; PG8_SCHED;
;             PG8_LDB(B0, 1, 0); PG8_LDB(B1, 1, 1); PG8_SCHED; PG8_LDA(At, 1, 0); PG8_STAGE(PG8_SA(0, 1), a2 + hstep, voffA);
;             PG8_WAIT_V(8); PG8_WAIT_L(0); PG8_BAR; PG8_MMA(0, 0, At, B0); PG8_MMA(0, 1, At, B1); PG8_BAR; PG8_SCHED;
.LBB0_2399:
	ds_read_b128 v[130:133], v175
	ds_read_b128 v[134:137], v175 offset:1024
	ds_read_b128 v[138:141], v175 offset:2048
	ds_read_b128 v[142:145], v175 offset:3072
	ds_read_b128 v[146:149], v176
	ds_read_b128 v[150:153], v176 offset:1024
	ds_read_b128 v[154:157], v176 offset:2048
	ds_read_b128 v[158:161], v176 offset:3072
	s_add_i32 s55, s53, 2
	s_add_u32 s64, s62, 0xfff00800
	s_addc_u32 s65, s63, -1
	s_cmp_eq_u32 s3, s53
	s_cselect_b32 s65, s57, s65
	s_cselect_b32 s64, s56, s64
	s_cselect_b32 s91, s59, s49
	s_cselect_b32 s90, s58, s11
	v_lshl_add_u64 v[170:171], s[62:63], 0, v[166:167]
	s_add_i32 m0, s61, 0xc000
	ds_read_b128 v[184:187], v177
	ds_read_b128 v[188:191], v177 offset:1024
	ds_read_b128 v[192:195], v177 offset:2048
	ds_read_b128 v[196:199], v177 offset:3072
	ds_read_b128 v[200:203], v177 offset:4096
	ds_read_b128 v[204:207], v177 offset:5120
	ds_read_b128 v[208:211], v177 offset:6144
	ds_read_b128 v[212:215], v177 offset:7168
	global_load_lds_dwordx4 v[170:171], off
	v_lshl_add_u64 v[170:171], v[170:171], 0, s[12:13]
	s_add_i32 m0, s61, 0xe000
	s_nop 0
	global_load_lds_dwordx4 v[170:171], off
	s_waitcnt vmcnt(8)
	s_waitcnt lgkmcnt(0)
	s_barrier
	s_setprio 1
	s_waitcnt lgkmcnt(0)
	v_mfma_f32_16x16x32_bf16 v[126:129], v[130:133], v[184:187], v[126:129]
	v_mfma_f32_16x16x32_bf16 v[122:125], v[138:141], v[184:187], v[122:125]
	v_mfma_f32_16x16x32_bf16 v[110:113], v[130:133], v[192:195], v[110:113]
	v_mfma_f32_16x16x32_bf16 v[106:109], v[138:141], v[192:195], v[106:109]
	v_mfma_f32_16x16x32_bf16 v[94:97], v[130:133], v[200:203], v[94:97]
	v_mfma_f32_16x16x32_bf16 v[90:93], v[138:141], v[200:203], v[90:93]
	v_mfma_f32_16x16x32_bf16 v[78:81], v[130:133], v[208:211], v[78:81]
	v_mfma_f32_16x16x32_bf16 v[74:77], v[138:141], v[208:211], v[74:77]
	v_mfma_f32_16x16x32_bf16 v[126:129], v[134:137], v[188:191], v[126:129]
	v_mfma_f32_16x16x32_bf16 v[122:125], v[142:145], v[188:191], v[122:125]
	v_mfma_f32_16x16x32_bf16 v[110:113], v[134:137], v[196:199], v[110:113]
	v_mfma_f32_16x16x32_bf16 v[106:109], v[142:145], v[196:199], v[106:109]
	v_mfma_f32_16x16x32_bf16 v[94:97], v[134:137], v[204:207], v[94:97]
	v_mfma_f32_16x16x32_bf16 v[90:93], v[142:145], v[204:207], v[90:93]
	v_mfma_f32_16x16x32_bf16 v[78:81], v[134:137], v[212:215], v[78:81]
	v_mfma_f32_16x16x32_bf16 v[74:77], v[142:145], v[212:215], v[74:77]
	v_mfma_f32_16x16x32_bf16 v[118:121], v[146:149], v[184:187], v[118:121]
	v_mfma_f32_16x16x32_bf16 v[114:117], v[154:157], v[184:187], v[114:117]
	v_mfma_f32_16x16x32_bf16 v[102:105], v[146:149], v[192:195], v[102:105]
	v_mfma_f32_16x16x32_bf16 v[98:101], v[154:157], v[192:195], v[98:101]
	v_mfma_f32_16x16x32_bf16 v[86:89], v[146:149], v[200:203], v[86:89]
	v_mfma_f32_16x16x32_bf16 v[82:85], v[154:157], v[200:203], v[82:85]
	v_mfma_f32_16x16x32_bf16 v[70:73], v[146:149], v[208:211], v[70:73]
	v_mfma_f32_16x16x32_bf16 v[66:69], v[154:157], v[208:211], v[66:69]
	v_mfma_f32_16x16x32_bf16 v[118:121], v[150:153], v[188:191], v[118:121]
	v_mfma_f32_16x16x32_bf16 v[114:117], v[158:161], v[188:191], v[114:117]
	s_barrier
	s_setprio 2
	v_mfma_f32_16x16x32_bf16 v[102:105], v[150:153], v[196:199], v[102:105]
	v_mfma_f32_16x16x32_bf16 v[98:101], v[158:161], v[196:199], v[98:101]
	v_mfma_f32_16x16x32_bf16 v[86:89], v[150:153], v[204:207], v[86:89]
	v_mfma_f32_16x16x32_bf16 v[82:85], v[158:161], v[204:207], v[82:85]
	v_mfma_f32_16x16x32_bf16 v[70:73], v[150:153], v[212:215], v[70:73]
	v_mfma_f32_16x16x32_bf16 v[66:69], v[158:161], v[212:215], v[66:69]
	s_setprio 0
	s_add_i32 s53, s80, s69
	v_lshl_add_u64 v[170:171], s[90:91], 0, v[162:163]
	s_mov_b32 m0, s53
	ds_read_b128 v[184:187], v177 offset:16384
	ds_read_b128 v[188:191], v177 offset:17408
	ds_read_b128 v[192:195], v177 offset:18432
	ds_read_b128 v[196:199], v177 offset:19456
	ds_read_b128 v[200:203], v177 offset:20480
	ds_read_b128 v[204:207], v177 offset:21504
	ds_read_b128 v[208:211], v177 offset:22528
	ds_read_b128 v[212:215], v177 offset:23552
	global_load_lds_dwordx4 v[170:171], off
	v_lshl_add_u64 v[216:217], v[170:171], 0, s[12:13]
	s_add_i32 m0, s53, 0x2000
	s_add_i32 s53, s81, s69
	global_load_lds_dwordx4 v[216:217], off
	v_lshl_add_u64 v[216:217], v[170:171], 0, s[14:15]
	s_mov_b32 m0, s53
	s_nop 0
	global_load_lds_dwordx4 v[216:217], off
	v_lshl_add_u64 v[216:217], v[170:171], 0, s[16:17]
	s_add_i32 m0, s53, 0x2000
	s_nop 0
	global_load_lds_dwordx4 v[216:217], off
	v_lshl_add_u64 v[216:217], s[64:65], 0, v[162:163]
	s_mov_b32 m0, s61
	v_lshl_add_u64 v[218:219], v[216:217], 0, s[12:13]
	global_load_lds_dwordx4 v[216:217], off
	s_mov_b32 m0, s70
	s_nop 0
	global_load_lds_dwordx4 v[218:219], off
	s_waitcnt vmcnt(8)
	s_waitcnt lgkmcnt(0)
	s_barrier
; #define PG8_STAGE(bufoff, gbase, voff) do { if constexpr (!pg8_noload<Epi>::value) { _Pragma("unroll") for (int _i = 0; _i < 2; ++_i) \
;         __builtin_amdgcn_global_load_lds((const unsigned*)((const char*)(gbase) + (size_t)_i * pstep + (voff)[0]), (PG8_LAS unsigned*)(lds + (bufoff) + ldsw + _i * 8192), 16, 0, 0); } } while (0)
; #define PG8_LDA(dst, b, h) do { _Pragma("unroll") for (int m = 0; m < 4; ++m) _Pragma("unroll") for (int k = 0; k < 2; ++k) dst[m][k] = *(const PG8_LAS bf16x8*)(lds + PG8_SA(b, h) + aoff + m * 2048 + k * 1024); } while (0)
; #define PG8_LDB(dst, b, h) do { _Pragma("unroll") for (int n = 0; n < 2; ++n) _Pragma("unroll") for (int k = 0; k < 2; ++k) dst[n][k] = *(const PG8_LAS bf16x8*)(lds + PG8_SB(b, h) + boff + n * 2048 + k * 1024); } while (0)
; #define PG8_MMA(ai, bj, At, Bt) do { __builtin_amdgcn_s_setprio(1); _Pragma("unroll") for (int m = 0; m < 4; ++m) _Pragma("unroll") for (int n = 0; n < 2; ++n) _Pragma("unroll") for (int k = 0; k < 2; ++k) \
;         acc[ai][bj][m][n] = __builtin_amdgcn_mfma_f32_16x16x32_bf16(Bt[n][k], At[m][k], acc[ai][bj][m][n], 0, 0, 0); __builtin_amdgcn_s_setprio(0); } while (0)
; #define PG8_WAIT_V(n) asm volatile("s_waitcnt vmcnt(" #n ")" ::: "memory")
; #define PG8_WAIT_L(n) asm volatile("s_waitcnt lgkmcnt(" #n ")" ::: "memory")
; #define PG8_BAR __builtin_amdgcn_s_barrier()
; #define PG8_SCHED __builtin_amdgcn_sched_barrier(0)
; template <class Epi, class Sched, bool ALIGN_EPI = false, bool SP2 = false, bool ABLK = false>
; __device__ __forceinline__ void gemm_phase(PG8_LAS unsigned char* lds, const Gemm g, const Sched& S, const Epi& E) {
;     ...
;             PG8_WAIT_V(8); PG8_WAIT_L(0); PG8_BAR; PG8_MMA(1, 0, At, B0); PG8_MMA(1, 1, At, B1); PG8_BAR; PG8_SCHED;
;             PG8_LDB(B0, 1, 0); PG8_LDB(B1, 1, 1); PG8_SCHED; PG8_LDA(At, 1, 0); PG8_STAGE(PG8_SA(0, 1), a2 + hstep, voffA);
;             PG8_WAIT_V(8); PG8_WAIT_L(0); PG8_BAR; PG8_MMA(0, 0, At, B0); PG8_MMA(0, 1, At, B1); PG8_BAR; PG8_SCHED;
	s_setprio 1
	s_waitcnt lgkmcnt(0)
	v_mfma_f32_16x16x32_bf16 v[62:65], v[130:133], v[184:187], v[62:65]
	v_mfma_f32_16x16x32_bf16 v[58:61], v[138:141], v[184:187], v[58:61]
	v_mfma_f32_16x16x32_bf16 v[46:49], v[130:133], v[192:195], v[46:49]
	v_mfma_f32_16x16x32_bf16 v[42:45], v[138:141], v[192:195], v[42:45]
	v_mfma_f32_16x16x32_bf16 v[30:33], v[130:133], v[200:203], v[30:33]
	v_mfma_f32_16x16x32_bf16 v[26:29], v[138:141], v[200:203], v[26:29]
	v_mfma_f32_16x16x32_bf16 v[14:17], v[130:133], v[208:211], v[14:17]
	v_mfma_f32_16x16x32_bf16 v[10:13], v[138:141], v[208:211], v[10:13]
	v_mfma_f32_16x16x32_bf16 v[62:65], v[134:137], v[188:191], v[62:65]
	v_mfma_f32_16x16x32_bf16 v[58:61], v[142:145], v[188:191], v[58:61]
	v_mfma_f32_16x16x32_bf16 v[46:49], v[134:137], v[196:199], v[46:49]
	v_mfma_f32_16x16x32_bf16 v[42:45], v[142:145], v[196:199], v[42:45]
	v_mfma_f32_16x16x32_bf16 v[30:33], v[134:137], v[204:207], v[30:33]
	v_mfma_f32_16x16x32_bf16 v[26:29], v[142:145], v[204:207], v[26:29]
	v_mfma_f32_16x16x32_bf16 v[14:17], v[134:137], v[212:215], v[14:17]
	v_mfma_f32_16x16x32_bf16 v[10:13], v[142:145], v[212:215], v[10:13]
	v_mfma_f32_16x16x32_bf16 v[54:57], v[146:149], v[184:187], v[54:57]
	v_mfma_f32_16x16x32_bf16 v[50:53], v[154:157], v[184:187], v[50:53]
	v_mfma_f32_16x16x32_bf16 v[38:41], v[146:149], v[192:195], v[38:41]
	v_mfma_f32_16x16x32_bf16 v[34:37], v[154:157], v[192:195], v[34:37]
	v_mfma_f32_16x16x32_bf16 v[22:25], v[146:149], v[200:203], v[22:25]
	v_mfma_f32_16x16x32_bf16 v[18:21], v[154:157], v[200:203], v[18:21]
	v_mfma_f32_16x16x32_bf16 v[6:9], v[146:149], v[208:211], v[6:9]
	v_mfma_f32_16x16x32_bf16 v[2:5], v[154:157], v[208:211], v[2:5]
	v_mfma_f32_16x16x32_bf16 v[54:57], v[150:153], v[188:191], v[54:57]
	v_mfma_f32_16x16x32_bf16 v[50:53], v[158:161], v[188:191], v[50:53]
	v_mfma_f32_16x16x32_bf16 v[38:41], v[150:153], v[196:199], v[38:41]
	v_mfma_f32_16x16x32_bf16 v[34:37], v[158:161], v[196:199], v[34:37]
	v_mfma_f32_16x16x32_bf16 v[22:25], v[150:153], v[204:207], v[22:25]
	v_mfma_f32_16x16x32_bf16 v[18:21], v[158:161], v[204:207], v[18:21]
	s_barrier
	s_setprio 2
	v_mfma_f32_16x16x32_bf16 v[6:9], v[150:153], v[212:215], v[6:9]
	v_mfma_f32_16x16x32_bf16 v[2:5], v[158:161], v[212:215], v[2:5]
	s_setprio 0
	s_add_i32 s53, 0, 0x18000
	s_add_i32 s64, 0, 0x1c000
	v_add_u32_e32 v142, s53, v1
	v_add_u32_e32 v158, s64, v1
	ds_read_b128 v[130:133], v142
	ds_read_b128 v[134:137], v142 offset:1024
	ds_read_b128 v[138:141], v142 offset:2048
	ds_read_b128 v[142:145], v142 offset:3072
	ds_read_b128 v[146:149], v158
	ds_read_b128 v[150:153], v158 offset:1024
	ds_read_b128 v[154:157], v158 offset:2048
	ds_read_b128 v[158:161], v158 offset:3072
	s_mov_b32 m0, s71
	v_lshl_add_u64 v[218:219], v[216:217], 0, s[14:15]
	ds_read_b128 v[184:187], v177 offset:32768
	ds_read_b128 v[188:191], v177 offset:33792
	ds_read_b128 v[192:195], v177 offset:34816
	ds_read_b128 v[196:199], v177 offset:35840
	ds_read_b128 v[200:203], v177 offset:36864
	ds_read_b128 v[204:207], v177 offset:37888
	ds_read_b128 v[208:211], v177 offset:38912
	ds_read_b128 v[212:215], v177 offset:39936
	global_load_lds_dwordx4 v[218:219], off
	v_lshl_add_u64 v[218:219], v[216:217], 0, s[16:17]
	s_mov_b32 m0, s72
	s_nop 0
	global_load_lds_dwordx4 v[218:219], off
	s_waitcnt vmcnt(8)
	s_waitcnt lgkmcnt(0)
	s_barrier
	s_setprio 1
	s_waitcnt lgkmcnt(0)
	v_mfma_f32_16x16x32_bf16 v[126:129], v[130:133], v[184:187], v[126:129]
	v_mfma_f32_16x16x32_bf16 v[122:125], v[138:141], v[184:187], v[122:125]
	v_mfma_f32_16x16x32_bf16 v[110:113], v[130:133], v[192:195], v[110:113]
	v_mfma_f32_16x16x32_bf16 v[106:109], v[138:141], v[192:195], v[106:109]
	v_mfma_f32_16x16x32_bf16 v[94:97], v[130:133], v[200:203], v[94:97]
	v_mfma_f32_16x16x32_bf16 v[90:93], v[138:141], v[200:203], v[90:93]
	v_mfma_f32_16x16x32_bf16 v[78:81], v[130:133], v[208:211], v[78:81]
	v_mfma_f32_16x16x32_bf16 v[74:77], v[138:141], v[208:211], v[74:77]
	v_mfma_f32_16x16x32_bf16 v[126:129], v[134:137], v[188:191], v[126:129]
	v_mfma_f32_16x16x32_bf16 v[122:125], v[142:145], v[188:191], v[122:125]
	v_mfma_f32_16x16x32_bf16 v[110:113], v[134:137], v[196:199], v[110:113]
	v_mfma_f32_16x16x32_bf16 v[106:109], v[142:145], v[196:199], v[106:109]
	v_mfma_f32_16x16x32_bf16 v[94:97], v[134:137], v[204:207], v[94:97]
	v_mfma_f32_16x16x32_bf16 v[90:93], v[142:145], v[204:207], v[90:93]
	v_mfma_f32_16x16x32_bf16 v[78:81], v[134:137], v[212:215], v[78:81]
	v_mfma_f32_16x16x32_bf16 v[74:77], v[142:145], v[212:215], v[74:77]
	v_mfma_f32_16x16x32_bf16 v[118:121], v[146:149], v[184:187], v[118:121]
	v_mfma_f32_16x16x32_bf16 v[114:117], v[154:157], v[184:187], v[114:117]
	v_mfma_f32_16x16x32_bf16 v[102:105], v[146:149], v[192:195], v[102:105]
	v_mfma_f32_16x16x32_bf16 v[98:101], v[154:157], v[192:195], v[98:101]
	v_mfma_f32_16x16x32_bf16 v[86:89], v[146:149], v[200:203], v[86:89]
	v_mfma_f32_16x16x32_bf16 v[82:85], v[154:157], v[200:203], v[82:85]
	v_mfma_f32_16x16x32_bf16 v[70:73], v[146:149], v[208:211], v[70:73]
	v_mfma_f32_16x16x32_bf16 v[66:69], v[154:157], v[208:211], v[66:69]
	v_mfma_f32_16x16x32_bf16 v[118:121], v[150:153], v[188:191], v[118:121]
	v_mfma_f32_16x16x32_bf16 v[114:117], v[158:161], v[188:191], v[114:117]
	s_barrier
; #define PG8_STAGE(bufoff, gbase, voff) do { if constexpr (!pg8_noload<Epi>::value) { _Pragma("unroll") for (int _i = 0; _i < 2; ++_i) \
;         __builtin_amdgcn_global_load_lds((const unsigned*)((const char*)(gbase) + (size_t)_i * pstep + (voff)[0]), (PG8_LAS unsigned*)(lds + (bufoff) + ldsw + _i * 8192), 16, 0, 0); } } while (0)
; #define PG8_LDA(dst, b, h) do { _Pragma("unroll") for (int m = 0; m < 4; ++m) _Pragma("unroll") for (int k = 0; k < 2; ++k) dst[m][k] = *(const PG8_LAS bf16x8*)(lds + PG8_SA(b, h) + aoff + m * 2048 + k * 1024); } while (0)
; #define PG8_MMA(ai, bj, At, Bt) do { __builtin_amdgcn_s_setprio(1); _Pragma("unroll") for (int m = 0; m < 4; ++m) _Pragma("unroll") for (int n = 0; n < 2; ++n) _Pragma("unroll") for (int k = 0; k < 2; ++k) \
;         acc[ai][bj][m][n] = __builtin_amdgcn_mfma_f32_16x16x32_bf16(Bt[n][k], At[m][k], acc[ai][bj][m][n], 0, 0, 0); __builtin_amdgcn_s_setprio(0); } while (0)
; #define PG8_WAIT_V(n) asm volatile("s_waitcnt vmcnt(" #n ")" ::: "memory")
; #define PG8_WAIT_L(n) asm volatile("s_waitcnt lgkmcnt(" #n ")" ::: "memory")
; #define PG8_BAR __builtin_amdgcn_s_barrier()
; #define PG8_SCHED __builtin_amdgcn_sched_barrier(0)
; template <class Epi, class Sched, bool ALIGN_EPI = false, bool SP2 = false, bool ABLK = false>
; __device__ __forceinline__ void gemm_phase(PG8_LAS unsigned char* lds, const Gemm g, const Sched& S, const Epi& E) {
;     ...
;             PG8_WAIT_V(8); PG8_WAIT_L(0); PG8_BAR; PG8_MMA(0, 0, At, B0); PG8_MMA(0, 1, At, B1); PG8_BAR; PG8_SCHED;
;             PG8_LDA(At, 1, 1); PG8_STAGE(PG8_SB(1, 0), b3, voffB); PG8_STAGE(PG8_SB(1, 1), b3 + hstep, voffB); PG8_STAGE(PG8_SA(1, 0), a3, voffA);
;             PG8_WAIT_V(8); PG8_WAIT_L(0); PG8_BAR; PG8_MMA(1, 0, At, B0); PG8_MMA(1, 1, At, B1); PG8_BAR; PG8_SCHED;
;     ...
;         }
;         if constexpr (ALIGN_EPI) { if (wr == 0) PG8_BAR; }
;         if constexpr (!Epi::AFTER_DRAIN) { E(acc, cur, wr, wc, fr, fq); S.done(cur); }
;         if (!has_next) break;
	s_setprio 2
	v_mfma_f32_16x16x32_bf16 v[102:105], v[150:153], v[196:199], v[102:105]
	v_mfma_f32_16x16x32_bf16 v[98:101], v[158:161], v[196:199], v[98:101]
	v_mfma_f32_16x16x32_bf16 v[86:89], v[150:153], v[204:207], v[86:89]
	v_mfma_f32_16x16x32_bf16 v[82:85], v[158:161], v[204:207], v[82:85]
	v_mfma_f32_16x16x32_bf16 v[70:73], v[150:153], v[212:215], v[70:73]
	v_mfma_f32_16x16x32_bf16 v[66:69], v[158:161], v[212:215], v[66:69]
	s_setprio 0
	s_add_i32 s53, s53, s69
	v_lshl_add_u64 v[218:219], v[170:171], 0, s[24:25]
	s_mov_b32 m0, s53
	ds_read_b128 v[184:187], v177 offset:49152
	ds_read_b128 v[188:191], v177 offset:50176
	ds_read_b128 v[192:195], v177 offset:51200
	ds_read_b128 v[196:199], v177 offset:52224
	ds_read_b128 v[200:203], v177 offset:53248
	ds_read_b128 v[204:207], v177 offset:54272
	ds_read_b128 v[208:211], v177 offset:55296
	ds_read_b128 v[212:215], v177 offset:56320
	global_load_lds_dwordx4 v[218:219], off
	v_lshl_add_u64 v[218:219], v[170:171], 0, s[26:27]
	s_add_i32 m0, s53, 0x2000
	s_add_i32 s53, s64, s69
	global_load_lds_dwordx4 v[218:219], off
	v_lshl_add_u64 v[218:219], v[170:171], 0, s[28:29]
	s_mov_b32 m0, s53
	v_lshl_add_u64 v[170:171], v[170:171], 0, s[30:31]
	global_load_lds_dwordx4 v[218:219], off
	s_add_i32 m0, s53, 0x2000
	s_nop 0
	global_load_lds_dwordx4 v[170:171], off
	v_lshl_add_u64 v[170:171], v[216:217], 0, s[24:25]
	s_mov_b32 m0, s75
	s_nop 0
	global_load_lds_dwordx4 v[170:171], off
	v_lshl_add_u64 v[170:171], v[216:217], 0, s[26:27]
	s_mov_b32 m0, s76
	s_nop 0
	global_load_lds_dwordx4 v[170:171], off
	s_waitcnt vmcnt(8)
	s_waitcnt lgkmcnt(0)
	s_barrier
	s_setprio 1
	s_waitcnt lgkmcnt(0)
	v_mfma_f32_16x16x32_bf16 v[62:65], v[130:133], v[184:187], v[62:65]
	v_mfma_f32_16x16x32_bf16 v[58:61], v[138:141], v[184:187], v[58:61]
	v_mfma_f32_16x16x32_bf16 v[46:49], v[130:133], v[192:195], v[46:49]
	v_mfma_f32_16x16x32_bf16 v[42:45], v[138:141], v[192:195], v[42:45]
	v_mfma_f32_16x16x32_bf16 v[30:33], v[130:133], v[200:203], v[30:33]
	v_mfma_f32_16x16x32_bf16 v[26:29], v[138:141], v[200:203], v[26:29]
	v_mfma_f32_16x16x32_bf16 v[14:17], v[130:133], v[208:211], v[14:17]
	v_mfma_f32_16x16x32_bf16 v[10:13], v[138:141], v[208:211], v[10:13]
	v_mfma_f32_16x16x32_bf16 v[62:65], v[134:137], v[188:191], v[62:65]
	v_mfma_f32_16x16x32_bf16 v[58:61], v[142:145], v[188:191], v[58:61]
	v_mfma_f32_16x16x32_bf16 v[46:49], v[134:137], v[196:199], v[46:49]
	v_mfma_f32_16x16x32_bf16 v[42:45], v[142:145], v[196:199], v[42:45]
	v_mfma_f32_16x16x32_bf16 v[30:33], v[134:137], v[204:207], v[30:33]
	v_mfma_f32_16x16x32_bf16 v[26:29], v[142:145], v[204:207], v[26:29]
	v_mfma_f32_16x16x32_bf16 v[14:17], v[134:137], v[212:215], v[14:17]
	v_mfma_f32_16x16x32_bf16 v[10:13], v[142:145], v[212:215], v[10:13]
	v_mfma_f32_16x16x32_bf16 v[54:57], v[146:149], v[184:187], v[54:57]
	v_mfma_f32_16x16x32_bf16 v[50:53], v[154:157], v[184:187], v[50:53]
	v_mfma_f32_16x16x32_bf16 v[38:41], v[146:149], v[192:195], v[38:41]
	v_mfma_f32_16x16x32_bf16 v[34:37], v[154:157], v[192:195], v[34:37]
	v_mfma_f32_16x16x32_bf16 v[22:25], v[146:149], v[200:203], v[22:25]
	v_mfma_f32_16x16x32_bf16 v[18:21], v[154:157], v[200:203], v[18:21]
	v_mfma_f32_16x16x32_bf16 v[6:9], v[146:149], v[208:211], v[6:9]
	v_mfma_f32_16x16x32_bf16 v[2:5], v[154:157], v[208:211], v[2:5]
	v_mfma_f32_16x16x32_bf16 v[54:57], v[150:153], v[188:191], v[54:57]
	v_mfma_f32_16x16x32_bf16 v[50:53], v[158:161], v[188:191], v[50:53]
	v_mfma_f32_16x16x32_bf16 v[38:41], v[150:153], v[196:199], v[38:41]
	v_mfma_f32_16x16x32_bf16 v[34:37], v[158:161], v[196:199], v[34:37]
	v_mfma_f32_16x16x32_bf16 v[22:25], v[150:153], v[204:207], v[22:25]
	v_mfma_f32_16x16x32_bf16 v[18:21], v[158:161], v[204:207], v[18:21]
	s_barrier
	s_setprio 2
	v_mfma_f32_16x16x32_bf16 v[6:9], v[150:153], v[212:215], v[6:9]
	v_mfma_f32_16x16x32_bf16 v[2:5], v[158:161], v[212:215], v[2:5]
	s_setprio 0
	s_add_u32 s62, s62, 0x1000
	s_addc_u32 s63, s63, 0
	s_add_u32 s11, s11, 0x1000
	s_addc_u32 s49, s49, 0
	s_cmp_ge_i32 s55, s89
	s_mov_b32 s53, s55
	s_cbranch_scc0 .LBB0_2399
	s_and_b64 vcc, exec, s[34:35]
	s_cbranch_vccnz .LBB0_2404
	s_lshl_b32 s11, s2, 8
	s_cmp_gt_i32 s2, 63
	s_mov_b64 s[62:63], -1
	s_cbranch_scc1 .LBB0_2405
